# v022_wt
# baseline (speedup 1.0000x reference)
; #define SCHED __builtin_amdgcn_sched_barrier(0)
; __device__ __forceinline__ void phase_gemm2(const Params& p, int layer, const float* xold, float* xnew) {
;     ...
; #pragma unroll
;     for (int ai = 0; ai < 2; ++ai)
; #pragma unroll
;       for (int bj = 0; bj < 2; ++bj) {
;         f32x4 xo[4][2];
; #pragma unroll
;         for (int m = 0; m < 4; ++m)
; #pragma unroll
;           for (int n = 0; n < 2; ++n) {
;             int feat = feat0 + ai * 128 + wr * 64 + m * 16 + fq * 4;
;             int tok = tok0 + bj * 128 + wc * 32 + n * 16 + fr;
;             xo[m][n] = *reinterpret_cast<const f32x4*>(xold + (size_t)tok * DM + feat);
;           }
;         SCHED;
; #pragma unroll
;         for (int m = 0; m < 4; ++m)
; #pragma unroll
;           for (int n = 0; n < 2; ++n) {
;             int feat = feat0 + ai * 128 + wr * 64 + m * 16 + fq * 4;
;             int tok = tok0 + bj * 128 + wc * 32 + n * 16 + fr;
;             *reinterpret_cast<f32x4*>(xnew + (size_t)tok * DM + feat) = xo[m][n] + acc[ai][bj][m][n];
.LBB0_34:
	s_or_b64 exec, exec, s[18:19]
	v_lshrrev_b32_e32 v130, 4, v97
	v_lshlrev_b32_e32 v130, 2, v130
	v_lshrrev_b32_e32 v97, 1, v97
	v_and_or_b32 v130, v130, 12, v147
	v_and_b32_e32 v97, 0x60, v97
	v_add_u32_e32 v134, s16, v130
	v_or3_b32 v160, v97, v146, s14
	v_and_b32_e32 v140, 15, v210
	v_bfe_u32 v141, v210, 4, 2
	v_lshrrev_b32_e32 v142, 6, v210
	v_sub_u32_e32 v143, v160, v140
	v_lshlrev_b32_e32 v144, 2, v141
	v_sub_u32_e32 v144, v134, v144
	v_add_u32_e32 v143, v143, v141
	v_lshl_add_u32 v144, v140, 2, v144
	v_lshlrev_b32_e32 v143, 14, v143
	v_lshl_add_u32 v130, v144, 2, v143
	v_add_u32_e32 v131, 0x10000, v130
	v_add_u32_e32 v132, 0x20000, v130
	v_add_u32_e32 v133, 0x30000, v130
	v_add_u32_e32 v134, 0x40000, v130
	v_add_u32_e32 v135, 0x50000, v130
	v_add_u32_e32 v136, 0x60000, v130
	v_add_u32_e32 v137, 0x70000, v130
	v_mul_u32_u24_e32 v142, 0x2200, v142
	v_mul_u32_u24_e32 v145, 0x110, v140
	v_lshl_add_u32 v145, v141, 4, v145
	v_add3_u32 v138, v142, v145, 32
	v_mul_u32_u24_e32 v145, 0x110, v141
	v_lshl_add_u32 v145, v140, 4, v145
	v_add3_u32 v139, v142, v145, 32
	s_add_u32 s16, s10, 0x200000
	s_addc_u32 s17, s11, 0
	s_mov_b64 s[14:15], s[8:9]
	global_load_dwordx4 v[164:167], v130, s[14:15] offset:0
	global_load_dwordx4 v[168:171], v131, s[14:15] offset:0
	global_load_dwordx4 v[172:175], v132, s[14:15] offset:0
	global_load_dwordx4 v[176:179], v133, s[14:15] offset:0
	global_load_dwordx4 v[180:183], v134, s[14:15] offset:0
	global_load_dwordx4 v[184:187], v135, s[14:15] offset:0
	global_load_dwordx4 v[188:191], v136, s[14:15] offset:0
	global_load_dwordx4 v[192:195], v137, s[14:15] offset:0
	s_mov_b64 s[14:15], s[8:9]
	global_load_dwordx4 v[140:143], v130, s[14:15] offset:512
	global_load_dwordx4 v[144:147], v131, s[14:15] offset:512
	global_load_dwordx4 v[148:151], v132, s[14:15] offset:512
	global_load_dwordx4 v[152:155], v133, s[14:15] offset:512
	global_load_dwordx4 v[156:159], v134, s[14:15] offset:512
	global_load_dwordx4 v[196:199], v135, s[14:15] offset:512
	global_load_dwordx4 v[200:203], v136, s[14:15] offset:512
	global_load_dwordx4 v[204:207], v137, s[14:15] offset:512
	ds_write_b128 v138, v[126:129] offset:0
	ds_write_b128 v138, v[122:125] offset:4352
	ds_write_b128 v138, v[118:121] offset:64
	ds_write_b128 v138, v[114:117] offset:4416
	ds_write_b128 v138, v[110:113] offset:128
	ds_write_b128 v138, v[106:109] offset:4480
	ds_write_b128 v138, v[102:105] offset:192
	ds_write_b128 v138, v[98:101] offset:4544
	ds_read_b128 v[222:225], v139 offset:0
	ds_read_b128 v[226:229], v139 offset:1088
	ds_read_b128 v[230:233], v139 offset:2176
	ds_read_b128 v[234:237], v139 offset:3264
	ds_read_b128 v[238:241], v139 offset:4352
	ds_read_b128 v[242:245], v139 offset:5440
	ds_read_b128 v[246:249], v139 offset:6528
	ds_read_b128 v[250:253], v139 offset:7616
	s_waitcnt lgkmcnt(0)
	s_waitcnt vmcnt(15)
	v_pk_add_f32 v[222:223], v[222:223], v[164:165]
	v_pk_add_f32 v[224:225], v[224:225], v[166:167]
	global_store_dwordx4 v130, v[222:225], s[10:11] offset:0 sc1
	s_waitcnt vmcnt(15)
	v_pk_add_f32 v[226:227], v[226:227], v[168:169]
	v_pk_add_f32 v[228:229], v[228:229], v[170:171]
	global_store_dwordx4 v131, v[226:229], s[10:11] offset:0 sc1
	s_waitcnt vmcnt(15)
	v_pk_add_f32 v[230:231], v[230:231], v[172:173]
	v_pk_add_f32 v[232:233], v[232:233], v[174:175]
	global_store_dwordx4 v132, v[230:233], s[10:11] offset:0 sc1
	s_waitcnt vmcnt(15)
	v_pk_add_f32 v[234:235], v[234:235], v[176:177]
	v_pk_add_f32 v[236:237], v[236:237], v[178:179]
	global_store_dwordx4 v133, v[234:237], s[10:11] offset:0 sc1
	s_waitcnt vmcnt(15)
	v_pk_add_f32 v[238:239], v[238:239], v[180:181]
	v_pk_add_f32 v[240:241], v[240:241], v[182:183]
	global_store_dwordx4 v134, v[238:241], s[10:11] offset:0 sc1
	s_waitcnt vmcnt(15)
	v_pk_add_f32 v[242:243], v[242:243], v[184:185]
	v_pk_add_f32 v[244:245], v[244:245], v[186:187]
	global_store_dwordx4 v135, v[242:245], s[10:11] offset:0 sc1
	s_waitcnt vmcnt(15)
	v_pk_add_f32 v[246:247], v[246:247], v[188:189]
	v_pk_add_f32 v[248:249], v[248:249], v[190:191]
	global_store_dwordx4 v136, v[246:249], s[10:11] offset:0 sc1
	s_waitcnt vmcnt(15)
	v_pk_add_f32 v[250:251], v[250:251], v[192:193]
	v_pk_add_f32 v[252:253], v[252:253], v[194:195]
	global_store_dwordx4 v137, v[250:253], s[10:11] offset:0 sc1
	s_add_u32 s14, s8, 0x200000
	s_addc_u32 s15, s9, 0
	global_load_dwordx4 v[164:167], v130, s[14:15] offset:0
	global_load_dwordx4 v[168:171], v131, s[14:15] offset:0
	global_load_dwordx4 v[172:175], v132, s[14:15] offset:0
	global_load_dwordx4 v[176:179], v133, s[14:15] offset:0
	global_load_dwordx4 v[180:183], v134, s[14:15] offset:0
	global_load_dwordx4 v[184:187], v135, s[14:15] offset:0
	global_load_dwordx4 v[188:191], v136, s[14:15] offset:0
	global_load_dwordx4 v[192:195], v137, s[14:15] offset:0
	ds_write_b128 v138, v[60:63] offset:0
	ds_write_b128 v138, v[56:59] offset:4352
	ds_write_b128 v138, v[52:55] offset:64
	ds_write_b128 v138, v[48:51] offset:4416
	ds_write_b128 v138, v[44:47] offset:128
	ds_write_b128 v138, v[40:43] offset:4480
	ds_write_b128 v138, v[36:39] offset:192
	ds_write_b128 v138, v[32:35] offset:4544
	ds_read_b128 v[222:225], v139 offset:0
	ds_read_b128 v[226:229], v139 offset:1088
	ds_read_b128 v[230:233], v139 offset:2176
	ds_read_b128 v[234:237], v139 offset:3264
	ds_read_b128 v[238:241], v139 offset:4352
	ds_read_b128 v[242:245], v139 offset:5440
	ds_read_b128 v[246:249], v139 offset:6528
	ds_read_b128 v[250:253], v139 offset:7616
	s_waitcnt lgkmcnt(0)
	s_waitcnt vmcnt(23)
	v_pk_add_f32 v[222:223], v[222:223], v[140:141]
	v_pk_add_f32 v[224:225], v[224:225], v[142:143]
	global_store_dwordx4 v130, v[222:225], s[10:11] offset:512 sc1
	s_waitcnt vmcnt(23)
; #define SCHED __builtin_amdgcn_sched_barrier(0)
; __device__ __forceinline__ void phase_gemm2(const Params& p, int layer, const float* xold, float* xnew) {
;     ...
;   for (int tile = blockIdx.x; tile < nA * nB; tile += gridDim.x) {
;     ...
; #pragma unroll
;     for (int ai = 0; ai < 2; ++ai)
; #pragma unroll
;       for (int bj = 0; bj < 2; ++bj) {
;         f32x4 xo[4][2];
; #pragma unroll
;         for (int m = 0; m < 4; ++m)
; #pragma unroll
;           for (int n = 0; n < 2; ++n) {
;             int feat = feat0 + ai * 128 + wr * 64 + m * 16 + fq * 4;
;             int tok = tok0 + bj * 128 + wc * 32 + n * 16 + fr;
;             xo[m][n] = *reinterpret_cast<const f32x4*>(xold + (size_t)tok * DM + feat);
;           }
;         SCHED;
; #pragma unroll
;         for (int m = 0; m < 4; ++m)
; #pragma unroll
;           for (int n = 0; n < 2; ++n) {
;             int feat = feat0 + ai * 128 + wr * 64 + m * 16 + fq * 4;
;             int tok = tok0 + bj * 128 + wc * 32 + n * 16 + fr;
;             *reinterpret_cast<f32x4*>(xnew + (size_t)tok * DM + feat) = xo[m][n] + acc[ai][bj][m][n];
;           }
;         SCHED;
;       }
	v_pk_add_f32 v[226:227], v[226:227], v[144:145]
	v_pk_add_f32 v[228:229], v[228:229], v[146:147]
	global_store_dwordx4 v131, v[226:229], s[10:11] offset:512 sc1
	s_waitcnt vmcnt(23)
	v_pk_add_f32 v[230:231], v[230:231], v[148:149]
	v_pk_add_f32 v[232:233], v[232:233], v[150:151]
	global_store_dwordx4 v132, v[230:233], s[10:11] offset:512 sc1
	s_waitcnt vmcnt(23)
	v_pk_add_f32 v[234:235], v[234:235], v[152:153]
	v_pk_add_f32 v[236:237], v[236:237], v[154:155]
	global_store_dwordx4 v133, v[234:237], s[10:11] offset:512 sc1
	s_waitcnt vmcnt(23)
	v_pk_add_f32 v[238:239], v[238:239], v[156:157]
	v_pk_add_f32 v[240:241], v[240:241], v[158:159]
	global_store_dwordx4 v134, v[238:241], s[10:11] offset:512 sc1
	s_waitcnt vmcnt(23)
	v_pk_add_f32 v[242:243], v[242:243], v[196:197]
	v_pk_add_f32 v[244:245], v[244:245], v[198:199]
	global_store_dwordx4 v135, v[242:245], s[10:11] offset:512 sc1
	s_waitcnt vmcnt(23)
	v_pk_add_f32 v[246:247], v[246:247], v[200:201]
	v_pk_add_f32 v[248:249], v[248:249], v[202:203]
	global_store_dwordx4 v136, v[246:249], s[10:11] offset:512 sc1
	s_waitcnt vmcnt(23)
	v_pk_add_f32 v[250:251], v[250:251], v[204:205]
	v_pk_add_f32 v[252:253], v[252:253], v[206:207]
	global_store_dwordx4 v137, v[250:253], s[10:11] offset:512 sc1
	s_add_u32 s14, s8, 0x200000
	s_addc_u32 s15, s9, 0
	global_load_dwordx4 v[140:143], v130, s[14:15] offset:512
	global_load_dwordx4 v[144:147], v131, s[14:15] offset:512
	global_load_dwordx4 v[148:151], v132, s[14:15] offset:512
	global_load_dwordx4 v[152:155], v133, s[14:15] offset:512
	global_load_dwordx4 v[156:159], v134, s[14:15] offset:512
	global_load_dwordx4 v[196:199], v135, s[14:15] offset:512
	global_load_dwordx4 v[200:203], v136, s[14:15] offset:512
	global_load_dwordx4 v[204:207], v137, s[14:15] offset:512
	ds_write_b128 v138, v[92:95] offset:0
	ds_write_b128 v138, v[88:91] offset:4352
	ds_write_b128 v138, v[84:87] offset:64
	ds_write_b128 v138, v[80:83] offset:4416
	ds_write_b128 v138, v[76:79] offset:128
	ds_write_b128 v138, v[72:75] offset:4480
	ds_write_b128 v138, v[68:71] offset:192
	ds_write_b128 v138, v[64:67] offset:4544
	ds_read_b128 v[222:225], v139 offset:0
	ds_read_b128 v[226:229], v139 offset:1088
	ds_read_b128 v[230:233], v139 offset:2176
	ds_read_b128 v[234:237], v139 offset:3264
	ds_read_b128 v[238:241], v139 offset:4352
	ds_read_b128 v[242:245], v139 offset:5440
	ds_read_b128 v[246:249], v139 offset:6528
	ds_read_b128 v[250:253], v139 offset:7616
	s_waitcnt lgkmcnt(0)
	s_waitcnt vmcnt(23)
	v_pk_add_f32 v[222:223], v[222:223], v[164:165]
	v_pk_add_f32 v[224:225], v[224:225], v[166:167]
	global_store_dwordx4 v130, v[222:225], s[16:17] offset:0 sc1
	s_waitcnt vmcnt(23)
	v_pk_add_f32 v[226:227], v[226:227], v[168:169]
	v_pk_add_f32 v[228:229], v[228:229], v[170:171]
	global_store_dwordx4 v131, v[226:229], s[16:17] offset:0 sc1
	s_waitcnt vmcnt(23)
	v_pk_add_f32 v[230:231], v[230:231], v[172:173]
	v_pk_add_f32 v[232:233], v[232:233], v[174:175]
	global_store_dwordx4 v132, v[230:233], s[16:17] offset:0 sc1
	s_waitcnt vmcnt(23)
	v_pk_add_f32 v[234:235], v[234:235], v[176:177]
	v_pk_add_f32 v[236:237], v[236:237], v[178:179]
	global_store_dwordx4 v133, v[234:237], s[16:17] offset:0 sc1
	s_waitcnt vmcnt(23)
	v_pk_add_f32 v[238:239], v[238:239], v[180:181]
	v_pk_add_f32 v[240:241], v[240:241], v[182:183]
	global_store_dwordx4 v134, v[238:241], s[16:17] offset:0 sc1
	s_waitcnt vmcnt(23)
	v_pk_add_f32 v[242:243], v[242:243], v[184:185]
	v_pk_add_f32 v[244:245], v[244:245], v[186:187]
	global_store_dwordx4 v135, v[242:245], s[16:17] offset:0 sc1
	s_waitcnt vmcnt(23)
	v_pk_add_f32 v[246:247], v[246:247], v[188:189]
	v_pk_add_f32 v[248:249], v[248:249], v[190:191]
	global_store_dwordx4 v136, v[246:249], s[16:17] offset:0 sc1
	s_waitcnt vmcnt(23)
	v_pk_add_f32 v[250:251], v[250:251], v[192:193]
	v_pk_add_f32 v[252:253], v[252:253], v[194:195]
	global_store_dwordx4 v137, v[250:253], s[16:17] offset:0 sc1
	ds_write_b128 v138, v[28:31] offset:0
	ds_write_b128 v138, v[24:27] offset:4352
	ds_write_b128 v138, v[20:23] offset:64
	ds_write_b128 v138, v[16:19] offset:4416
	ds_write_b128 v138, v[12:15] offset:128
	ds_write_b128 v138, v[8:11] offset:4480
	ds_write_b128 v138, v[4:7] offset:192
	ds_write_b128 v138, v[0:3] offset:4544
	ds_read_b128 v[222:225], v139 offset:0
	ds_read_b128 v[226:229], v139 offset:1088
	ds_read_b128 v[230:233], v139 offset:2176
	ds_read_b128 v[234:237], v139 offset:3264
	ds_read_b128 v[238:241], v139 offset:4352
	ds_read_b128 v[242:245], v139 offset:5440
	ds_read_b128 v[246:249], v139 offset:6528
	ds_read_b128 v[250:253], v139 offset:7616
	s_waitcnt lgkmcnt(0)
	s_waitcnt vmcnt(15)
	v_pk_add_f32 v[222:223], v[222:223], v[140:141]
	v_pk_add_f32 v[224:225], v[224:225], v[142:143]
	global_store_dwordx4 v130, v[222:225], s[16:17] offset:512 sc1
	s_waitcnt vmcnt(15)
	v_pk_add_f32 v[226:227], v[226:227], v[144:145]
	v_pk_add_f32 v[228:229], v[228:229], v[146:147]
	global_store_dwordx4 v131, v[226:229], s[16:17] offset:512 sc1
	s_waitcnt vmcnt(15)
	v_pk_add_f32 v[230:231], v[230:231], v[148:149]
	v_pk_add_f32 v[232:233], v[232:233], v[150:151]
	global_store_dwordx4 v132, v[230:233], s[16:17] offset:512 sc1
	s_waitcnt vmcnt(15)
	v_pk_add_f32 v[234:235], v[234:235], v[152:153]
	v_pk_add_f32 v[236:237], v[236:237], v[154:155]
	global_store_dwordx4 v133, v[234:237], s[16:17] offset:512 sc1
	s_waitcnt vmcnt(15)
	v_pk_add_f32 v[238:239], v[238:239], v[156:157]
	v_pk_add_f32 v[240:241], v[240:241], v[158:159]
	global_store_dwordx4 v134, v[238:241], s[16:17] offset:512 sc1
	s_waitcnt vmcnt(15)
	v_pk_add_f32 v[242:243], v[242:243], v[196:197]
	v_pk_add_f32 v[244:245], v[244:245], v[198:199]
	global_store_dwordx4 v135, v[242:245], s[16:17] offset:512 sc1
	s_waitcnt vmcnt(15)
	v_pk_add_f32 v[246:247], v[246:247], v[200:201]
	v_pk_add_f32 v[248:249], v[248:249], v[202:203]
	global_store_dwordx4 v136, v[246:249], s[16:17] offset:512 sc1
	s_waitcnt vmcnt(15)
	v_pk_add_f32 v[250:251], v[250:251], v[204:205]
	v_pk_add_f32 v[252:253], v[252:253], v[206:207]
	global_store_dwordx4 v137, v[250:253], s[16:17] offset:512 sc1
	s_load_dword s14, s[48:49], 0x0
	s_waitcnt lgkmcnt(0)
	s_add_i32 s30, s14, s30
	s_cmpk_gt_i32 s30, 0x1ff
	s_cbranch_scc1 .LBB0_47

; __device__ __forceinline__ float bflo(unsigned u) { return __uint_as_float(u << 16); }
; __device__ __forceinline__ float bfhi(unsigned u) { return __uint_as_float(u & 0xffff0000u); }
; #define SCHED __builtin_amdgcn_sched_barrier(0)
; __device__ __forceinline__ void phase_finalize(const Params& p, int layer) {
;     ...
;   for (int row = blockIdx.x * 8 + wid; row < T; row += gridDim.x * 8) {
;     const u16* yr = yraw + (size_t)row * DM;
;     const u16* pr = proj + (size_t)row * DIN;
;     u32x4 v[8], gts[8];
; #pragma unroll
;     for (int i = 0; i < 8; ++i) {
;       int col = i * 512 + lane * 8;
;       int gcol = (i < 2) ? (OFF_PG + col) : ((i < 6) ? (OFF_AG + col - 1024) : (OFF_SG + col - 3072));
;       v[i] = *reinterpret_cast<const u32x4*>(yr + col);
;       gts[i] = *reinterpret_cast<const u32x4*>(pr + gcol);
;     }
;     SCHED;
;     float f[8][8];
;     float s0 = 0.f, s1 = 0.f, s2 = 0.f;
; #pragma unroll
;     for (int i = 0; i < 8; ++i) {
;       f[i][0] = bflo(v[i].x); f[i][1] = bfhi(v[i].x); f[i][2] = bflo(v[i].y); f[i][3] = bfhi(v[i].y);
;       f[i][4] = bflo(v[i].z); f[i][5] = bfhi(v[i].z); f[i][6] = bflo(v[i].w); f[i][7] = bfhi(v[i].w);
;       float q = 0.f;
; #pragma unroll
;       for (int j = 0; j < 8; ++j) q += f[i][j] * f[i][j];
;       if (i < 2) s0 += q;
;       else if (i < 6) s1 += q;
;       else s2 += q;
;     }
;     s0 = wave_sum(s0);
;     s1 = wave_sum(s1);
;     s2 = wave_sum(s2);
;     float r0 = rsqrtf(s0 * (1.f / 1024.f) + 1e-6f), r1 = rsqrtf(s1 * (1.f / 2048.f) + 1e-6f), r2 = rsqrtf(s2 * (1.f / 1024.f) + 1e-6f);
.LBB0_51:
	v_ashrrev_i32_e32 v115, 31, v114
	v_lshlrev_b64 v[126:127], 13, v[114:115]
	v_lshl_add_u64 v[64:65], s[10:11], 0, v[126:127]
	v_mad_i64_i32 v[68:69], s[16:17], v114, s63, v[116:117]
	v_lshl_add_u64 v[66:67], v[64:65], 0, v[162:163]
	v_add_co_u32_e32 v70, vcc, s18, v68
	v_mov_b32_e32 v119, v163
	global_load_dwordx4 v[128:131], v[66:67], off
	global_load_dwordx4 v[132:135], v[66:67], off offset:1024
	global_load_dwordx4 v[136:139], v[68:69], off offset:2048
	global_load_dwordx4 v[140:143], v[68:69], off offset:3072
	v_addc_co_u32_e32 v71, vcc, 0, v69, vcc
	global_load_dwordx4 v[106:109], v[66:67], off offset:2048
	global_load_dwordx4 v[98:101], v[66:67], off offset:3072
	global_load_dwordx4 v[110:113], v[70:71], off
	global_load_dwordx4 v[102:105], v[70:71], off offset:1024
	v_lshl_add_u64 v[66:67], v[64:65], 0, v[118:119]
	v_mov_b32_e32 v121, v163
	v_mov_b32_e32 v123, v163
	v_lshl_add_u64 v[72:73], v[64:65], 0, v[120:121]
	global_load_dwordx4 v[88:91], v[66:67], off
	global_load_dwordx4 v[84:87], v[72:73], off
	global_load_dwordx4 v[92:95], v[70:71], off offset:2048
	global_load_dwordx4 v[80:83], v[70:71], off offset:3072
	v_lshl_add_u64 v[66:67], v[64:65], 0, v[122:123]
	global_load_dwordx4 v[72:75], v[66:67], off
	v_add_co_u32_e32 v66, vcc, s19, v68
	v_mov_b32_e32 v125, v163
	s_nop 0
	v_addc_co_u32_e32 v67, vcc, 0, v69, vcc
	v_lshl_add_u64 v[64:65], v[64:65], 0, v[124:125]
	global_load_dwordx4 v[68:71], v[64:65], off
	global_load_dwordx4 v[76:79], v[66:67], off offset:2048
	s_nop 0
	global_load_dwordx4 v[64:67], v[66:67], off offset:3072
	s_waitcnt vmcnt(13)
	v_lshlrev_b32_e32 v144, 16, v139
	v_mul_f32_e32 v115, 0xbfb8aa3b, v144
	v_exp_f32_e32 v115, v115
	v_lshlrev_b32_e32 v146, 16, v138
	v_lshlrev_b32_e32 v145, 16, v131
	v_and_b32_e32 v151, 0xffff0000, v131
	v_add_f32_e32 v115, 1.0, v115
	v_rcp_f32_e32 v148, v115
	v_mul_f32_e32 v115, 0xbfb8aa3b, v146
	v_exp_f32_e32 v115, v115
	v_lshlrev_b32_e32 v147, 16, v130
	v_and_b32_e32 v131, 0xffff0000, v130
	v_and_b32_e32 v130, 0xffff0000, v138
	v_lshlrev_b32_e32 v138, 16, v137
	v_and_b32_e32 v158, 0xffff0000, v137
	v_and_b32_e32 v137, 0xffff0000, v128
	v_and_b32_e32 v185, 0xffff0000, v132
	v_and_b32_e32 v150, 0xffff0000, v139
	v_mul_f32_e32 v139, 0xbfb8aa3b, v138
	v_lshlrev_b32_e32 v161, 16, v128
	v_lshlrev_b32_e32 v183, 16, v132
	v_mov_b32_e32 v198, v137
	v_mov_b32_e32 v199, v185
	v_exp_f32_e32 v149, v139
	v_lshlrev_b32_e32 v139, 16, v129
	s_waitcnt vmcnt(12)
	v_lshlrev_b32_e32 v170, 16, v143
	v_and_b32_e32 v176, 0xffff0000, v143
	v_lshlrev_b32_e32 v143, 16, v133
	v_mov_b32_e32 v196, v161
	v_mov_b32_e32 v197, v183
	v_pk_mul_f32 v[198:199], v[198:199], v[198:199]
	v_add_f32_e32 v115, 1.0, v115
	v_and_b32_e32 v159, 0xffff0000, v129
	v_and_b32_e32 v181, 0xffff0000, v133
	v_mov_b32_e32 v192, v139
	v_mov_b32_e32 v193, v143
	v_pk_fma_f32 v[196:197], v[196:197], v[196:197], v[198:199]
	v_rcp_f32_e32 v152, v115
	v_mul_f32_e32 v115, 0xbfb8aa3b, v130
	v_lshlrev_b32_e32 v179, 16, v134
	v_mov_b32_e32 v194, v159
	v_mov_b32_e32 v195, v181
	v_pk_fma_f32 v[192:193], v[192:193], v[192:193], v[196:197]
	v_exp_f32_e32 v115, v115
	v_lshlrev_b32_e32 v171, 16, v135
	v_and_b32_e32 v177, 0xffff0000, v135
	v_and_b32_e32 v135, 0xffff0000, v134
	v_mov_b32_e32 v188, v147
	v_mov_b32_e32 v189, v179
	v_pk_fma_f32 v[192:193], v[194:195], v[194:195], v[192:193]
	v_mov_b32_e32 v190, v131
	v_mov_b32_e32 v191, v135
	v_pk_fma_f32 v[188:189], v[188:189], v[188:189], v[192:193]
	v_mov_b32_e32 v132, v145
	v_mov_b32_e32 v133, v171
	v_pk_fma_f32 v[188:189], v[190:191], v[190:191], v[188:189]
	v_mov_b32_e32 v186, v151
	v_mov_b32_e32 v187, v177
	v_pk_fma_f32 v[132:133], v[132:133], v[132:133], v[188:189]
	v_add_f32_e32 v115, 1.0, v115
	v_pk_fma_f32 v[132:133], v[186:187], v[186:187], v[132:133]
	v_rcp_f32_e32 v154, v115
	v_add_f32_e32 v115, 1.0, v149
	v_add_f32_e32 v132, v132, v133
	v_rcp_f32_e32 v156, v115
	v_mul_f32_e32 v115, 0xbfb8aa3b, v158
	v_lshlrev_b32_e32 v160, 16, v136
	ds_bpermute_b32 v133, v97, v132
	v_exp_f32_e32 v115, v115
	v_mul_f32_e32 v129, 0xbfb8aa3b, v160
	v_exp_f32_e32 v129, v129
	v_and_b32_e32 v136, 0xffff0000, v136
	v_add_f32_e32 v115, 1.0, v115
	s_waitcnt lgkmcnt(0)
	v_add_f32_e32 v132, v132, v133
	v_rcp_f32_e32 v164, v115
	v_add_f32_e32 v115, 1.0, v129
	ds_bpermute_b32 v133, v222, v132
	v_rcp_f32_e32 v166, v115
	v_mul_f32_e32 v115, 0xbfb8aa3b, v136
	v_exp_f32_e32 v115, v115
	v_mul_f32_e32 v129, 0xbfb8aa3b, v150
	v_exp_f32_e32 v129, v129
	v_mul_f32_e32 v128, 0xbfb8aa3b, v170
	v_exp_f32_e32 v149, v128
	s_waitcnt lgkmcnt(0)
	v_add_f32_e32 v132, v132, v133
	v_add_f32_e32 v115, 1.0, v115
	ds_bpermute_b32 v133, v223, v132
	v_rcp_f32_e32 v168, v115
	v_add_f32_e32 v115, 1.0, v129
	v_rcp_f32_e32 v172, v115
	v_add_f32_e32 v115, 1.0, v149
	v_lshlrev_b32_e32 v178, 16, v142
	v_rcp_f32_e32 v174, v115
	v_mul_f32_e32 v115, 0xbfb8aa3b, v178
	v_and_b32_e32 v134, 0xffff0000, v142
	v_exp_f32_e32 v115, v115
	v_mul_f32_e32 v142, 0xbfb8aa3b, v134
	v_exp_f32_e32 v142, v142
	s_waitcnt lgkmcnt(0)
	v_add_f32_e32 v132, v132, v133
	ds_bpermute_b32 v133, v224, v132
	v_add_f32_e32 v115, 1.0, v115
	v_rcp_f32_e32 v186, v115
	v_add_f32_e32 v115, 1.0, v142
	v_lshlrev_b32_e32 v142, 16, v141
	v_mul_f32_e32 v149, 0xbfb8aa3b, v142
	v_and_b32_e32 v180, 0xffff0000, v141
	v_exp_f32_e32 v149, v149
	v_mul_f32_e32 v141, 0xbfb8aa3b, v180
	s_waitcnt lgkmcnt(0)
	v_add_f32_e32 v132, v132, v133
	v_exp_f32_e32 v141, v141
	ds_bpermute_b32 v133, v225, v132
	v_rcp_f32_e32 v188, v115
	v_add_f32_e32 v115, 1.0, v149
	v_rcp_f32_e32 v190, v115
	v_add_f32_e32 v115, 1.0, v141
	v_rcp_f32_e32 v192, v115
	s_waitcnt lgkmcnt(0)
; __device__ __forceinline__ float bflo(unsigned u) { return __uint_as_float(u << 16); }
; __device__ __forceinline__ float bfhi(unsigned u) { return __uint_as_float(u & 0xffff0000u); }
; __device__ __forceinline__ float siluf_(float x) { return x * __builtin_amdgcn_rcpf(1.f + __expf(-x)); }
; __device__ __forceinline__ void phase_finalize(const Params& p, int layer) {
;     ...
;     float r0 = rsqrtf(s0 * (1.f / 1024.f) + 1e-6f), r1 = rsqrtf(s1 * (1.f / 2048.f) + 1e-6f), r2 = rsqrtf(s2 * (1.f / 1024.f) + 1e-6f);
; #pragma unroll
;     for (int i = 0; i < 8; ++i) {
;       int col = i * 512 + lane * 8;
;       float rs = (i < 2) ? r0 : ((i < 6) ? r1 : r2);
;       u32x4 gt = gts[i];
;       float gv[8] = {bflo(gt.x), bfhi(gt.x), bflo(gt.y), bfhi(gt.y), bflo(gt.z), bfhi(gt.z), bflo(gt.w), bfhi(gt.w)};
;       float o[8];
; #pragma unroll
;       for (int j = 0; j < 8; ++j) o[j] = f[i][j] * rs * ggv[i][j >> 2][j & 3] * siluf_(gv[j]);
;       u32x4 pk = {pack2(o[0], o[1]), pack2(o[2], o[3]), pack2(o[4], o[5]), pack2(o[6], o[7])};
;       *reinterpret_cast<u32x4*>(Y + (size_t)row * DM + col) = pk;
;     }
	v_add_f32_e32 v115, v132, v133
	ds_bpermute_b32 v132, v226, v115
	v_lshlrev_b32_e32 v182, 16, v140
	v_mul_f32_e32 v141, 0xbfb8aa3b, v182
	v_exp_f32_e32 v141, v141
	v_and_b32_e32 v184, 0xffff0000, v140
	s_waitcnt lgkmcnt(0)
	v_add_f32_e32 v115, v115, v132
	v_fmamk_f32 v115, v115, 0x3a800000, v211
	v_mul_f32_e32 v140, 0xbfb8aa3b, v184
	v_mul_f32_e32 v132, 0x4b800000, v115
	v_cmp_gt_f32_e32 vcc, s1, v115
	v_add_f32_e32 v133, 1.0, v141
	v_exp_f32_e32 v141, v140
	v_cndmask_b32_e32 v115, v115, v132, vcc
	v_rsq_f32_e32 v115, v115
	v_rcp_f32_e32 v140, v133
	v_add_f32_e32 v132, 1.0, v141
	v_rcp_f32_e32 v194, v132
	v_mul_f32_e32 v132, 0x45800000, v115
	v_cndmask_b32_e32 v167, v115, v132, vcc
	v_pk_mul_f32 v[132:133], v[166:167], v[160:161]
	v_mov_b32_e32 v169, v167
	v_mul_f32_e32 v115, v56, v133
	v_mul_f32_e32 v115, v132, v115
	v_pk_mul_f32 v[132:133], v[168:169], v[136:137]
	v_mov_b32_e32 v157, v167
	v_mul_f32_e32 v133, v57, v133
	v_mul_f32_e32 v136, v132, v133
	v_pk_mul_f32 v[132:133], v[156:157], v[138:139]
	v_mov_b32_e32 v165, v167
	v_mul_f32_e32 v133, v58, v133
	v_mul_f32_e32 v137, v132, v133
	v_pk_mul_f32 v[132:133], v[164:165], v[158:159]
	v_mov_b32_e32 v153, v167
	v_mul_f32_e32 v133, v59, v133
	v_mov_b32_e32 v155, v167
	v_mul_f32_e32 v138, v132, v133
	v_pk_mul_f32 v[132:133], v[152:153], v[146:147]
	v_pk_mul_f32 v[130:131], v[154:155], v[130:131]
	v_mul_f32_e32 v133, v60, v133
	v_mul_f32_e32 v131, v61, v131
	v_mov_b32_e32 v149, v167
	v_mul_f32_e32 v132, v132, v133
	v_mul_f32_e32 v133, v130, v131
	v_pk_mul_f32 v[130:131], v[148:149], v[144:145]
	v_mov_b32_e32 v173, v167
	v_mul_f32_e32 v131, v62, v131
	v_mul_f32_e32 v139, v130, v131
	v_pk_mul_f32 v[130:131], v[172:173], v[150:151]
	v_lshl_add_u64 v[126:127], s[12:13], 0, v[126:127]
	v_mul_f32_e32 v131, v63, v131
	v_mul_f32_e32 v141, v130, v131
	v_lshl_add_u64 v[128:129], v[126:127], 0, v[162:163]
	v_cvt_pk_bf16_f32 v130, v115, v136
	v_cvt_pk_bf16_f32 v131, v137, v138
	v_cvt_pk_bf16_f32 v132, v132, v133
	v_cvt_pk_bf16_f32 v133, v139, v141
	v_mov_b32_e32 v141, v167
	global_store_dwordx4 v[128:129], v[130:133], off sc1
	v_mov_b32_e32 v195, v167
	v_mov_b32_e32 v191, v167
	v_pk_mul_f32 v[130:131], v[140:141], v[182:183]
	v_mov_b32_e32 v193, v167
	v_mul_f32_e32 v115, v48, v131
	v_mul_f32_e32 v115, v130, v115
	v_pk_mul_f32 v[130:131], v[194:195], v[184:185]
	v_mov_b32_e32 v187, v167
	v_mul_f32_e32 v131, v49, v131
	v_mul_f32_e32 v132, v130, v131
	v_pk_mul_f32 v[130:131], v[190:191], v[142:143]
	v_mov_b32_e32 v189, v167
	v_mul_f32_e32 v131, v50, v131
	v_mul_f32_e32 v133, v130, v131
	v_pk_mul_f32 v[130:131], v[192:193], v[180:181]
	v_mov_b32_e32 v175, v167
	v_mul_f32_e32 v131, v51, v131
	v_mul_f32_e32 v136, v130, v131
	v_pk_mul_f32 v[130:131], v[186:187], v[178:179]
	v_cvt_pk_bf16_f32 v132, v115, v132
	v_cvt_pk_bf16_f32 v133, v133, v136
	s_waitcnt vmcnt(10)
	v_lshlrev_b32_e32 v136, 16, v112
	v_mul_f32_e32 v131, v52, v131
	v_mul_f32_e32 v137, v130, v131
	v_pk_mul_f32 v[130:131], v[188:189], v[134:135]
	v_mul_f32_e32 v134, 0xbfb8aa3b, v176
	v_exp_f32_e32 v134, v134
	v_mul_f32_e32 v131, v53, v131
	v_mul_f32_e32 v135, v130, v131
	v_and_b32_e32 v112, 0xffff0000, v112
	v_add_f32_e32 v130, 1.0, v134
	v_rcp_f32_e32 v166, v130
	v_pk_mul_f32 v[130:131], v[174:175], v[170:171]
	v_cvt_pk_bf16_f32 v134, v137, v135
	v_lshlrev_b32_e32 v137, 16, v108
	v_mul_f32_e32 v131, v54, v131
	v_mul_f32_e32 v138, v130, v131
	v_pk_mul_f32 v[130:131], v[166:167], v[176:177]
	v_lshlrev_b32_e32 v146, 16, v111
	v_mul_f32_e32 v131, v55, v131
	v_mul_f32_e32 v131, v130, v131
	v_lshlrev_b32_e32 v130, 16, v113
	v_mul_f32_e32 v115, 0xbfb8aa3b, v130
	v_exp_f32_e32 v115, v115
	v_cvt_pk_bf16_f32 v135, v138, v131
	global_store_dwordx4 v[128:129], v[132:135], off offset:1024 sc1
	v_lshlrev_b32_e32 v131, 16, v109
	v_add_f32_e32 v115, 1.0, v115
	v_and_b32_e32 v132, 0xffff0000, v113
	v_mul_f32_e32 v113, 0xbfb8aa3b, v112
	v_rcp_f32_e32 v134, v115
	v_and_b32_e32 v133, 0xffff0000, v109
	v_mul_f32_e32 v109, 0xbfb8aa3b, v136
	v_exp_f32_e32 v115, v113
	v_exp_f32_e32 v109, v109
	v_and_b32_e32 v113, 0xffff0000, v108
	v_and_b32_e32 v148, 0xffff0000, v111
	v_add_f32_e32 v108, 1.0, v115
	v_add_f32_e32 v109, 1.0, v109
	v_rcp_f32_e32 v140, v108
	v_mul_f32_e32 v108, 0xbfb8aa3b, v146
	v_rcp_f32_e32 v142, v109
	v_exp_f32_e32 v108, v108
	v_mul_f32_e32 v109, 0xbfb8aa3b, v148
	v_exp_f32_e32 v109, v109
	v_and_b32_e32 v166, 0xffff0000, v110
	v_add_f32_e32 v108, 1.0, v108
	v_lshlrev_b32_e32 v147, 16, v107
	v_rcp_f32_e32 v154, v108
	v_and_b32_e32 v149, 0xffff0000, v107
	v_add_f32_e32 v107, 1.0, v109
	v_lshlrev_b32_e32 v160, 16, v110
	v_mul_f32_e32 v108, 0xbfb8aa3b, v166
	v_rcp_f32_e32 v152, v107
	v_mul_f32_e32 v107, 0xbfb8aa3b, v160
	v_exp_f32_e32 v109, v108
	v_exp_f32_e32 v107, v107
	v_lshlrev_b32_e32 v161, 16, v106
	v_and_b32_e32 v167, 0xffff0000, v106
	v_add_f32_e32 v106, 1.0, v109
	v_add_f32_e32 v107, 1.0, v107
	v_rcp_f32_e32 v174, v106
	v_mul_f32_e32 v106, 0xbfb8aa3b, v132
	v_rcp_f32_e32 v108, v107
	v_exp_f32_e32 v107, v106
	s_waitcnt vmcnt(10)
; __device__ __forceinline__ float bflo(unsigned u) { return __uint_as_float(u << 16); }
; __device__ __forceinline__ float bfhi(unsigned u) { return __uint_as_float(u & 0xffff0000u); }
; __device__ __forceinline__ float siluf_(float x) { return x * __builtin_amdgcn_rcpf(1.f + __expf(-x)); }
; __device__ __forceinline__ void phase_finalize(const Params& p, int layer) {
;     ...
;     float f[8][8];
;     float s0 = 0.f, s1 = 0.f, s2 = 0.f;
; #pragma unroll
;     for (int i = 0; i < 8; ++i) {
;       f[i][0] = bflo(v[i].x); f[i][1] = bfhi(v[i].x); f[i][2] = bflo(v[i].y); f[i][3] = bfhi(v[i].y);
;       f[i][4] = bflo(v[i].z); f[i][5] = bfhi(v[i].z); f[i][6] = bflo(v[i].w); f[i][7] = bfhi(v[i].w);
;       float q = 0.f;
; #pragma unroll
;       for (int j = 0; j < 8; ++j) q += f[i][j] * f[i][j];
;       if (i < 2) s0 += q;
;       else if (i < 6) s1 += q;
;       else s2 += q;
;     }
;     s0 = wave_sum(s0);
;     s1 = wave_sum(s1);
;     s2 = wave_sum(s2);
;     float r0 = rsqrtf(s0 * (1.f / 1024.f) + 1e-6f), r1 = rsqrtf(s1 * (1.f / 2048.f) + 1e-6f), r2 = rsqrtf(s2 * (1.f / 1024.f) + 1e-6f);
; #pragma unroll
;     for (int i = 0; i < 8; ++i) {
;       int col = i * 512 + lane * 8;
;       float rs = (i < 2) ? r0 : ((i < 6) ? r1 : r2);
;       u32x4 gt = gts[i];
;       float gv[8] = {bflo(gt.x), bfhi(gt.x), bflo(gt.y), bfhi(gt.y), bflo(gt.z), bfhi(gt.z), bflo(gt.w), bfhi(gt.w)};
;       float o[8];
; #pragma unroll
;       for (int j = 0; j < 8; ++j) o[j] = f[i][j] * rs * ggv[i][j >> 2][j & 3] * siluf_(gv[j]);
	v_lshlrev_b32_e32 v144, 16, v104
	v_and_b32_e32 v111, 0xffff0000, v101
	v_lshlrev_b32_e32 v158, 16, v103
	v_add_f32_e32 v107, 1.0, v107
	v_rcp_f32_e32 v156, v107
	v_lshlrev_b32_e32 v107, 16, v101
	v_mul_f32_e32 v101, 0xbfb8aa3b, v144
	v_exp_f32_e32 v101, v101
	v_and_b32_e32 v164, 0xffff0000, v103
	v_mul_f32_e32 v103, 0xbfb8aa3b, v164
	v_exp_f32_e32 v103, v103
	v_add_f32_e32 v101, 1.0, v101
	v_rcp_f32_e32 v150, v101
	v_mul_f32_e32 v101, 0xbfb8aa3b, v158
	v_exp_f32_e32 v101, v101
	v_lshlrev_b32_e32 v106, 16, v105
	v_mul_f32_e32 v109, 0xbfb8aa3b, v106
	v_exp_f32_e32 v109, v109
	v_lshlrev_b32_e32 v159, 16, v99
	v_add_f32_e32 v101, 1.0, v101
	v_and_b32_e32 v165, 0xffff0000, v99
	v_add_f32_e32 v99, 1.0, v103
	v_lshlrev_b32_e32 v178, 16, v102
	v_and_b32_e32 v182, 0xffff0000, v102
	v_and_b32_e32 v183, 0xffff0000, v98
	v_rcp_f32_e32 v172, v101
	v_rcp_f32_e32 v170, v99
	v_lshlrev_b32_e32 v179, 16, v98
	v_mul_f32_e32 v99, 0xbfb8aa3b, v178
	v_mul_f32_e32 v101, 0xbfb8aa3b, v182
	v_mov_b32_e32 v192, v167
	v_mov_b32_e32 v193, v183
	v_exp_f32_e32 v99, v99
	v_exp_f32_e32 v101, v101
	v_mov_b32_e32 v190, v161
	v_mov_b32_e32 v191, v179
	v_pk_mul_f32 v[192:193], v[192:193], v[192:193]
	v_and_b32_e32 v104, 0xffff0000, v104
	v_mov_b32_e32 v180, v147
	v_mov_b32_e32 v181, v159
	v_pk_fma_f32 v[190:191], v[190:191], v[190:191], v[192:193]
	v_add_f32_e32 v109, 1.0, v109
	v_and_b32_e32 v110, 0xffff0000, v105
	v_lshlrev_b32_e32 v145, 16, v100
	v_mul_f32_e32 v105, 0xbfb8aa3b, v104
	v_mov_b32_e32 v186, v149
	v_mov_b32_e32 v187, v165
	v_pk_fma_f32 v[180:181], v[180:181], v[180:181], v[190:191]
	v_rcp_f32_e32 v138, v109
	v_exp_f32_e32 v109, v105
	v_and_b32_e32 v105, 0xffff0000, v100
	v_mov_b32_e32 v168, v137
	v_mov_b32_e32 v169, v145
	v_pk_fma_f32 v[180:181], v[186:187], v[186:187], v[180:181]
	v_add_f32_e32 v99, 1.0, v99
	v_add_f32_e32 v98, 1.0, v101
	v_mov_b32_e32 v176, v113
	v_mov_b32_e32 v177, v105
	v_pk_fma_f32 v[168:169], v[168:169], v[168:169], v[180:181]
	v_rcp_f32_e32 v188, v99
	v_rcp_f32_e32 v184, v98
	v_mov_b32_e32 v98, v131
	v_mov_b32_e32 v99, v107
	v_pk_fma_f32 v[168:169], v[176:177], v[176:177], v[168:169]
	v_mov_b32_e32 v102, v133
	v_mov_b32_e32 v103, v111
	v_pk_fma_f32 v[98:99], v[98:99], v[98:99], v[168:169]
	s_waitcnt vmcnt(7)
	v_lshlrev_b32_e32 v176, 16, v94
	v_pk_fma_f32 v[212:213], v[102:103], v[102:103], v[98:99]
	v_mul_f32_e32 v98, 0xbfb8aa3b, v110
	v_exp_f32_e32 v99, v98
	v_lshlrev_b32_e32 v98, 16, v95
	v_mul_f32_e32 v101, 0xbfb8aa3b, v98
	v_exp_f32_e32 v101, v101
	v_add_f32_e32 v99, 1.0, v99
	v_and_b32_e32 v94, 0xffff0000, v94
	v_rcp_f32_e32 v190, v99
	v_add_f32_e32 v101, 1.0, v101
	v_rcp_f32_e32 v102, v101
	v_mul_f32_e32 v101, 0xbfb8aa3b, v176
	v_exp_f32_e32 v101, v101
	v_lshlrev_b32_e32 v99, 16, v91
	v_and_b32_e32 v169, 0xffff0000, v91
	v_and_b32_e32 v168, 0xffff0000, v95
	v_lshlrev_b32_e32 v177, 16, v90
	v_add_f32_e32 v91, 1.0, v101
	v_and_b32_e32 v95, 0xffff0000, v90
	v_mul_f32_e32 v90, 0xbfb8aa3b, v94
	v_lshlrev_b32_e32 v192, 16, v93
	v_rcp_f32_e32 v180, v91
	v_exp_f32_e32 v90, v90
	v_mul_f32_e32 v91, 0xbfb8aa3b, v192
	v_exp_f32_e32 v91, v91
	v_and_b32_e32 v196, 0xffff0000, v93
	v_add_f32_e32 v90, 1.0, v90
	v_rcp_f32_e32 v186, v90
	v_lshlrev_b32_e32 v193, 16, v89
	v_add_f32_e32 v90, 1.0, v91
	v_and_b32_e32 v197, 0xffff0000, v89
	v_mul_f32_e32 v89, 0xbfb8aa3b, v196
	v_lshlrev_b32_e32 v206, 16, v92
	v_rcp_f32_e32 v198, v90
	v_exp_f32_e32 v89, v89
	v_mul_f32_e32 v90, 0xbfb8aa3b, v206
	v_exp_f32_e32 v90, v90
	v_and_b32_e32 v208, 0xffff0000, v92
	v_add_f32_e32 v89, 1.0, v89
	v_rcp_f32_e32 v202, v89
	v_add_f32_e32 v89, 1.0, v90
	v_rcp_f32_e32 v216, v89
	v_mul_f32_e32 v89, 0xbfb8aa3b, v208
	v_exp_f32_e32 v89, v89
	v_mul_f32_e32 v90, 0xbfb8aa3b, v168
	v_exp_f32_e32 v90, v90
	v_lshlrev_b32_e32 v207, 16, v88
	v_and_b32_e32 v209, 0xffff0000, v88
	v_add_f32_e32 v88, 1.0, v89
	v_rcp_f32_e32 v218, v88
	s_waitcnt vmcnt(6)
	v_lshlrev_b32_e32 v88, 16, v83
	v_add_f32_e32 v89, 1.0, v90
	v_mul_f32_e32 v90, 0xbfb8aa3b, v88
	v_exp_f32_e32 v90, v90
	v_and_b32_e32 v231, 0xffff0000, v84
	v_lshlrev_b32_e32 v229, 16, v84
	v_mov_b32_e32 v246, v209
	v_mov_b32_e32 v247, v231
	v_rcp_f32_e32 v204, v89
	v_lshlrev_b32_e32 v89, 16, v87
	v_and_b32_e32 v91, 0xffff0000, v87
	v_lshlrev_b32_e32 v87, 16, v85
	v_mov_b32_e32 v244, v207
	v_mov_b32_e32 v245, v229
	v_pk_mul_f32 v[246:247], v[246:247], v[246:247]
	v_add_f32_e32 v90, 1.0, v90
	v_lshlrev_b32_e32 v194, 16, v82
	v_and_b32_e32 v85, 0xffff0000, v85
	v_mov_b32_e32 v240, v193
	v_mov_b32_e32 v241, v87
	v_pk_fma_f32 v[244:245], v[244:245], v[244:245], v[246:247]
	v_rcp_f32_e32 v92, v90
	v_and_b32_e32 v90, 0xffff0000, v83
	v_lshlrev_b32_e32 v195, 16, v86
	v_mul_f32_e32 v83, 0xbfb8aa3b, v194
	v_mov_b32_e32 v242, v197
	v_mov_b32_e32 v243, v85
	v_pk_fma_f32 v[240:241], v[240:241], v[240:241], v[244:245]
	v_exp_f32_e32 v93, v83
	v_and_b32_e32 v83, 0xffff0000, v86
	v_mov_b32_e32 v236, v177
	v_mov_b32_e32 v237, v195
	v_pk_fma_f32 v[240:241], v[242:243], v[242:243], v[240:241]
	v_mov_b32_e32 v238, v95
	v_mov_b32_e32 v239, v83
	v_pk_fma_f32 v[236:237], v[236:237], v[236:237], v[240:241]
	v_mov_b32_e32 v232, v99
	v_mov_b32_e32 v233, v89
	v_pk_fma_f32 v[236:237], v[238:239], v[238:239], v[236:237]
	v_mov_b32_e32 v234, v169
	v_mov_b32_e32 v235, v91
	v_pk_fma_f32 v[232:233], v[232:233], v[232:233], v[236:237]
	v_add_f32_e32 v84, v212, v213
	v_pk_fma_f32 v[232:233], v[234:235], v[234:235], v[232:233]
	v_and_b32_e32 v82, 0xffff0000, v82
	v_add_f32_e32 v84, v84, v232
	v_add_f32_e32 v84, v84, v233
	ds_bpermute_b32 v86, v97, v84
	v_add_f32_e32 v100, 1.0, v109
	v_mul_f32_e32 v101, 0xbfb8aa3b, v82
	v_exp_f32_e32 v101, v101
	v_add_f32_e32 v93, 1.0, v93
	s_waitcnt lgkmcnt(0)
; __device__ __forceinline__ float bflo(unsigned u) { return __uint_as_float(u << 16); }
; __device__ __forceinline__ float bfhi(unsigned u) { return __uint_as_float(u & 0xffff0000u); }
; __device__ __forceinline__ float siluf_(float x) { return x * __builtin_amdgcn_rcpf(1.f + __expf(-x)); }
; __device__ __forceinline__ void phase_finalize(const Params& p, int layer) {
;     ...
;     s0 = wave_sum(s0);
;     s1 = wave_sum(s1);
;     s2 = wave_sum(s2);
;     float r0 = rsqrtf(s0 * (1.f / 1024.f) + 1e-6f), r1 = rsqrtf(s1 * (1.f / 2048.f) + 1e-6f), r2 = rsqrtf(s2 * (1.f / 1024.f) + 1e-6f);
; #pragma unroll
;     for (int i = 0; i < 8; ++i) {
;       int col = i * 512 + lane * 8;
;       float rs = (i < 2) ? r0 : ((i < 6) ? r1 : r2);
;       u32x4 gt = gts[i];
;       float gv[8] = {bflo(gt.x), bfhi(gt.x), bflo(gt.y), bfhi(gt.y), bflo(gt.z), bfhi(gt.z), bflo(gt.w), bfhi(gt.w)};
;       float o[8];
; #pragma unroll
;       for (int j = 0; j < 8; ++j) o[j] = f[i][j] * rs * ggv[i][j >> 2][j & 3] * siluf_(gv[j]);
;       u32x4 pk = {pack2(o[0], o[1]), pack2(o[2], o[3]), pack2(o[4], o[5]), pack2(o[6], o[7])};
;       *reinterpret_cast<u32x4*>(Y + (size_t)row * DM + col) = pk;
	v_add_f32_e32 v84, v84, v86
	ds_bpermute_b32 v103, v222, v84
	v_lshlrev_b32_e32 v86, 16, v81
	v_rcp_f32_e32 v212, v93
	v_add_f32_e32 v93, 1.0, v101
	v_mul_f32_e32 v101, 0xbfb8aa3b, v86
	s_waitcnt lgkmcnt(0)
	v_add_f32_e32 v103, v84, v103
	ds_bpermute_b32 v109, v223, v103
	v_exp_f32_e32 v101, v101
	v_and_b32_e32 v84, 0xffff0000, v81
	v_rcp_f32_e32 v232, v93
	v_mul_f32_e32 v81, 0xbfb8aa3b, v84
	s_waitcnt lgkmcnt(0)
	v_add_f32_e32 v103, v103, v109
	ds_bpermute_b32 v109, v224, v103
	v_add_f32_e32 v93, 1.0, v101
	v_rcp_f32_e32 v234, v93
	v_exp_f32_e32 v81, v81
	v_lshlrev_b32_e32 v228, 16, v80
	s_waitcnt lgkmcnt(0)
	v_add_f32_e32 v93, v103, v109
	ds_bpermute_b32 v101, v225, v93
	v_add_f32_e32 v81, 1.0, v81
	v_rcp_f32_e32 v236, v81
	v_mul_f32_e32 v103, 0xbfb8aa3b, v228
	v_exp_f32_e32 v103, v103
	s_waitcnt lgkmcnt(0)
	v_add_f32_e32 v81, v93, v101
	ds_bpermute_b32 v93, v226, v81
	v_and_b32_e32 v230, 0xffff0000, v80
	v_mul_f32_e32 v80, 0xbfb8aa3b, v230
	v_add_f32_e32 v101, 1.0, v103
	v_exp_f32_e32 v103, v80
	s_waitcnt lgkmcnt(0)
	v_add_f32_e32 v80, v81, v93
	v_fmamk_f32 v80, v80, 0x3a000000, v211
	v_mul_f32_e32 v81, 0x4b800000, v80
	v_cmp_gt_f32_e32 vcc, s1, v80
	v_add_f32_e32 v93, 1.0, v103
	v_rcp_f32_e32 v238, v93
	v_cndmask_b32_e32 v80, v80, v81, vcc
	v_rsq_f32_e32 v81, v80
	v_lshl_add_u64 v[200:201], v[126:127], 0, v[118:119]
	v_rcp_f32_e32 v80, v101
	v_rcp_f32_e32 v100, v100
	v_mul_f32_e32 v93, 0x45800000, v81
	v_cndmask_b32_e32 v109, v81, v93, vcc
	v_mov_b32_e32 v141, v109
	v_pk_mul_f32 v[112:113], v[140:141], v[112:113]
	v_mov_b32_e32 v135, v109
	v_mul_f32_e32 v113, v45, v113
	v_mul_f32_e32 v115, v112, v113
	v_pk_mul_f32 v[112:113], v[134:135], v[130:131]
	v_mov_b32_e32 v157, v109
	v_mul_f32_e32 v113, v46, v113
	v_pk_mul_f32 v[160:161], v[108:109], v[160:161]
	v_mul_f32_e32 v119, v112, v113
	v_pk_mul_f32 v[112:113], v[156:157], v[132:133]
	v_mul_f32_e32 v81, v36, v161
	v_mov_b32_e32 v175, v109
	v_mul_f32_e32 v113, v47, v113
	v_mul_f32_e32 v81, v160, v81
	v_pk_mul_f32 v[160:161], v[174:175], v[166:167]
	v_mul_f32_e32 v112, v112, v113
	v_mov_b32_e32 v189, v109
	v_mul_f32_e32 v93, v37, v161
	v_mov_b32_e32 v155, v109
	v_cvt_pk_bf16_f32 v133, v119, v112
	v_pk_mul_f32 v[112:113], v[188:189], v[178:179]
	v_mul_f32_e32 v93, v160, v93
	v_pk_mul_f32 v[146:147], v[154:155], v[146:147]
	v_cvt_pk_bf16_f32 v130, v81, v93
	v_mul_f32_e32 v81, v40, v113
	v_mov_b32_e32 v185, v109
	v_mul_f32_e32 v101, v38, v147
	v_mov_b32_e32 v153, v109
	v_mul_f32_e32 v81, v112, v81
	v_pk_mul_f32 v[112:113], v[184:185], v[182:183]
	v_mul_f32_e32 v101, v146, v101
	v_pk_mul_f32 v[146:147], v[152:153], v[148:149]
	v_mul_f32_e32 v93, v41, v113
	v_mov_b32_e32 v173, v109
	v_mul_f32_e32 v103, v39, v147
	v_mov_b32_e32 v143, v109
	v_mul_f32_e32 v93, v112, v93
	v_pk_mul_f32 v[112:113], v[172:173], v[158:159]
	v_mul_f32_e32 v103, v146, v103
	v_pk_mul_f32 v[136:137], v[142:143], v[136:137]
	v_cvt_pk_bf16_f32 v131, v101, v103
	v_mul_f32_e32 v101, v42, v113
	v_mov_b32_e32 v171, v109
	v_mul_f32_e32 v108, v44, v137
	v_mul_f32_e32 v103, v112, v101
	v_pk_mul_f32 v[112:113], v[170:171], v[164:165]
	v_mul_f32_e32 v108, v136, v108
	v_mul_f32_e32 v101, v43, v113
	v_mov_b32_e32 v151, v109
	v_cvt_pk_bf16_f32 v132, v108, v115
	v_mul_f32_e32 v108, v112, v101
	v_pk_mul_f32 v[112:113], v[150:151], v[144:145]
	v_mov_b32_e32 v139, v109
	v_mul_f32_e32 v101, v32, v113
	v_mul_f32_e32 v112, v112, v101
	v_mov_b32_e32 v101, v109
	v_pk_mul_f32 v[100:101], v[100:101], v[104:105]
	v_mov_b32_e32 v191, v109
	v_mul_f32_e32 v101, v33, v101
	v_mul_f32_e32 v113, v100, v101
	v_pk_mul_f32 v[100:101], v[138:139], v[106:107]
	v_mov_b32_e32 v217, v109
	v_mul_f32_e32 v101, v34, v101
	v_mul_f32_e32 v107, v100, v101
	v_pk_mul_f32 v[100:101], v[190:191], v[110:111]
	v_cvt_pk_bf16_f32 v104, v81, v93
	v_mov_b32_e32 v219, v109
	v_mul_f32_e32 v101, v35, v101
	v_mul_f32_e32 v100, v100, v101
	v_cvt_pk_bf16_f32 v107, v107, v100
	v_pk_mul_f32 v[100:101], v[216:217], v[206:207]
	v_mov_b32_e32 v199, v109
	v_mul_f32_e32 v81, v20, v101
	v_mul_f32_e32 v81, v100, v81
	v_pk_mul_f32 v[100:101], v[218:219], v[208:209]
	v_mov_b32_e32 v203, v109
	v_mul_f32_e32 v93, v21, v101
	v_mul_f32_e32 v93, v100, v93
	v_pk_mul_f32 v[100:101], v[198:199], v[192:193]
	v_cvt_pk_bf16_f32 v105, v103, v108
	v_cvt_pk_bf16_f32 v106, v112, v113
	global_store_dwordx4 v[128:129], v[104:107], off offset:3072 sc1
	v_mul_f32_e32 v101, v22, v101
	v_mov_b32_e32 v181, v109
	v_mul_f32_e32 v104, v100, v101
	v_pk_mul_f32 v[100:101], v[202:203], v[196:197]
	v_mov_b32_e32 v187, v109
	v_mul_f32_e32 v101, v23, v101
	v_mul_f32_e32 v105, v100, v101
	v_pk_mul_f32 v[100:101], v[180:181], v[176:177]
	v_pk_mul_f32 v[94:95], v[186:187], v[94:95]
	v_mul_f32_e32 v101, v28, v101
	v_mul_f32_e32 v95, v29, v95
	v_mov_b32_e32 v103, v109
	v_mul_f32_e32 v100, v100, v101
	v_mul_f32_e32 v101, v94, v95
	v_pk_mul_f32 v[94:95], v[102:103], v[98:99]
	v_mov_b32_e32 v205, v109
	v_mul_f32_e32 v95, v30, v95
	v_mul_f32_e32 v102, v94, v95
	v_pk_mul_f32 v[94:95], v[204:205], v[168:169]
	v_cvt_pk_bf16_f32 v98, v81, v93
	v_mov_b32_e32 v81, v109
	v_mul_f32_e32 v95, v31, v95
	v_pk_mul_f32 v[80:81], v[80:81], v[228:229]
	v_mul_f32_e32 v94, v94, v95
	v_mul_f32_e32 v81, v24, v81
	v_mov_b32_e32 v239, v109
	v_cvt_pk_bf16_f32 v100, v100, v101
	v_cvt_pk_bf16_f32 v101, v102, v94
	v_mul_f32_e32 v94, v80, v81
	v_pk_mul_f32 v[80:81], v[238:239], v[230:231]
	v_mov_b32_e32 v235, v109
	v_mul_f32_e32 v81, v25, v81
	v_mul_f32_e32 v95, v80, v81
	v_pk_mul_f32 v[80:81], v[234:235], v[86:87]
	v_mov_b32_e32 v237, v109
	v_mul_f32_e32 v81, v26, v81
	v_mul_f32_e32 v86, v80, v81
	v_pk_mul_f32 v[80:81], v[236:237], v[84:85]
	v_mov_b32_e32 v213, v109
	v_mul_f32_e32 v81, v27, v81
	v_mul_f32_e32 v84, v80, v81
	v_pk_mul_f32 v[80:81], v[212:213], v[194:195]
	v_mov_b32_e32 v233, v109
	v_mul_f32_e32 v81, v16, v81
	v_mul_f32_e32 v85, v80, v81
	v_pk_mul_f32 v[80:81], v[232:233], v[82:83]
	v_mul_f32_e32 v82, 0xbfb8aa3b, v90
	v_exp_f32_e32 v82, v82
	v_mul_f32_e32 v81, v17, v81
	v_mul_f32_e32 v83, v80, v81
	v_mov_b32_e32 v93, v109
	v_add_f32_e32 v80, 1.0, v82
	v_rcp_f32_e32 v108, v80
	v_pk_mul_f32 v[80:81], v[92:93], v[88:89]
	v_cvt_pk_bf16_f32 v82, v85, v83
	v_cvt_pk_bf16_f32 v99, v104, v105
	global_store_dwordx4 v[200:201], v[98:101], off sc1
	v_mul_f32_e32 v81, v18, v81
	v_mul_f32_e32 v87, v80, v81
	v_pk_mul_f32 v[80:81], v[108:109], v[90:91]
	s_waitcnt vmcnt(5)
; __device__ __forceinline__ float bflo(unsigned u) { return __uint_as_float(u << 16); }
; __device__ __forceinline__ float bfhi(unsigned u) { return __uint_as_float(u & 0xffff0000u); }
; __device__ __forceinline__ float siluf_(float x) { return x * __builtin_amdgcn_rcpf(1.f + __expf(-x)); }
; __device__ __forceinline__ void phase_finalize(const Params& p, int layer) {
;     ...
; #pragma unroll
;     for (int i = 0; i < 8; ++i) {
;       f[i][0] = bflo(v[i].x); f[i][1] = bfhi(v[i].x); f[i][2] = bflo(v[i].y); f[i][3] = bfhi(v[i].y);
;       f[i][4] = bflo(v[i].z); f[i][5] = bfhi(v[i].z); f[i][6] = bflo(v[i].w); f[i][7] = bfhi(v[i].w);
;       float q = 0.f;
; #pragma unroll
;       for (int j = 0; j < 8; ++j) q += f[i][j] * f[i][j];
;       if (i < 2) s0 += q;
;       else if (i < 6) s1 += q;
;       else s2 += q;
;     }
;     s0 = wave_sum(s0);
;     s1 = wave_sum(s1);
;     s2 = wave_sum(s2);
;     float r0 = rsqrtf(s0 * (1.f / 1024.f) + 1e-6f), r1 = rsqrtf(s1 * (1.f / 2048.f) + 1e-6f), r2 = rsqrtf(s2 * (1.f / 1024.f) + 1e-6f);
; #pragma unroll
;     for (int i = 0; i < 8; ++i) {
;       int col = i * 512 + lane * 8;
;       float rs = (i < 2) ? r0 : ((i < 6) ? r1 : r2);
;       u32x4 gt = gts[i];
;       float gv[8] = {bflo(gt.x), bfhi(gt.x), bflo(gt.y), bfhi(gt.y), bflo(gt.z), bfhi(gt.z), bflo(gt.w), bfhi(gt.w)};
;       float o[8];
; #pragma unroll
;       for (int j = 0; j < 8; ++j) o[j] = f[i][j] * rs * ggv[i][j >> 2][j & 3] * siluf_(gv[j]);
;       u32x4 pk = {pack2(o[0], o[1]), pack2(o[2], o[3]), pack2(o[4], o[5]), pack2(o[6], o[7])};
;       *reinterpret_cast<u32x4*>(Y + (size_t)row * DM + col) = pk;
	v_lshlrev_b32_e32 v98, 16, v76
	v_mul_f32_e32 v81, v19, v81
	v_mul_f32_e32 v88, v80, v81
	v_cvt_pk_bf16_f32 v81, v86, v84
	v_cvt_pk_bf16_f32 v83, v87, v88
	v_lshl_add_u64 v[86:87], v[126:127], 0, v[120:121]
	v_cvt_pk_bf16_f32 v80, v94, v95
	global_store_dwordx4 v[86:87], v[80:83], off sc1
	v_lshlrev_b32_e32 v84, 16, v79
	v_mul_f32_e32 v85, 0xbfb8aa3b, v84
	v_lshlrev_b32_e32 v82, 16, v78
	v_mul_f32_e32 v81, 0xbfb8aa3b, v82
	v_exp_f32_e32 v81, v81
	v_exp_f32_e32 v88, v85
	v_lshlrev_b32_e32 v85, 16, v75
	v_and_b32_e32 v87, 0xffff0000, v75
	v_add_f32_e32 v75, 1.0, v81
	v_add_f32_e32 v80, 1.0, v88
	v_lshlrev_b32_e32 v83, 16, v74
	v_rcp_f32_e32 v88, v75
	v_and_b32_e32 v75, 0xffff0000, v74
	v_and_b32_e32 v74, 0xffff0000, v78
	v_mul_f32_e32 v78, 0xbfb8aa3b, v74
	v_and_b32_e32 v86, 0xffff0000, v79
	v_exp_f32_e32 v79, v78
	v_and_b32_e32 v94, 0xffff0000, v77
	v_lshlrev_b32_e32 v78, 16, v77
	v_and_b32_e32 v95, 0xffff0000, v73
	v_add_f32_e32 v79, 1.0, v79
	v_rcp_f32_e32 v90, v79
	v_lshlrev_b32_e32 v79, 16, v73
	v_mul_f32_e32 v73, 0xbfb8aa3b, v94
	v_mul_f32_e32 v81, 0xbfb8aa3b, v78
	v_exp_f32_e32 v73, v73
	v_mul_f32_e32 v77, 0xbfb8aa3b, v98
	v_exp_f32_e32 v81, v81
	v_exp_f32_e32 v77, v77
	v_add_f32_e32 v73, 1.0, v73
	v_rcp_f32_e32 v100, v73
	v_add_f32_e32 v81, 1.0, v81
	v_add_f32_e32 v73, 1.0, v77
	v_and_b32_e32 v76, 0xffff0000, v76
	v_mul_f32_e32 v77, 0xbfb8aa3b, v86
	v_rcp_f32_e32 v92, v81
	v_rcp_f32_e32 v102, v73
	v_mul_f32_e32 v73, 0xbfb8aa3b, v76
	v_exp_f32_e32 v81, v77
	v_and_b32_e32 v77, 0xffff0000, v72
	v_and_b32_e32 v135, 0xffff0000, v68
	global_store_dwordx4 v[128:129], v[130:133], off offset:2048 sc1
	v_lshlrev_b32_e32 v99, 16, v72
	v_exp_f32_e32 v73, v73
	v_lshlrev_b32_e32 v133, 16, v68
	v_mov_b32_e32 v150, v77
	v_mov_b32_e32 v151, v135
	v_lshlrev_b32_e32 v131, 16, v69
	v_mov_b32_e32 v148, v99
	v_mov_b32_e32 v149, v133
	v_pk_mul_f32 v[150:151], v[150:151], v[150:151]
	v_and_b32_e32 v69, 0xffff0000, v69
	v_mov_b32_e32 v144, v79
	v_mov_b32_e32 v145, v131
	v_pk_fma_f32 v[148:149], v[148:149], v[148:149], v[150:151]
	s_waitcnt vmcnt(6)
	v_lshlrev_b32_e32 v104, 16, v67
	v_lshlrev_b32_e32 v129, 16, v70
	v_mov_b32_e32 v146, v95
	v_mov_b32_e32 v147, v69
	v_pk_fma_f32 v[144:145], v[144:145], v[144:145], v[148:149]
	v_add_f32_e32 v72, 1.0, v73
	v_add_f32_e32 v73, 1.0, v81
	v_mul_f32_e32 v81, 0xbfb8aa3b, v104
	v_lshlrev_b32_e32 v105, 16, v71
	v_and_b32_e32 v113, 0xffff0000, v71
	v_and_b32_e32 v71, 0xffff0000, v70
	v_mov_b32_e32 v140, v83
	v_mov_b32_e32 v141, v129
	v_pk_fma_f32 v[144:145], v[146:147], v[146:147], v[144:145]
	v_exp_f32_e32 v81, v81
	v_mov_b32_e32 v142, v75
	v_mov_b32_e32 v143, v71
	v_pk_fma_f32 v[140:141], v[140:141], v[140:141], v[144:145]
	v_mov_b32_e32 v136, v85
	v_mov_b32_e32 v137, v105
	v_pk_fma_f32 v[140:141], v[142:143], v[142:143], v[140:141]
	v_mov_b32_e32 v138, v87
	v_mov_b32_e32 v139, v113
	v_pk_fma_f32 v[136:137], v[136:137], v[136:137], v[140:141]
	v_rcp_f32_e32 v106, v73
	v_pk_fma_f32 v[136:137], v[138:139], v[138:139], v[136:137]
	v_add_f32_e32 v73, 1.0, v81
	v_add_f32_e32 v68, v136, v137
	v_rcp_f32_e32 v110, v73
	ds_bpermute_b32 v73, v97, v68
	v_lshlrev_b32_e32 v128, 16, v66
	v_and_b32_e32 v112, 0xffff0000, v67
	v_mul_f32_e32 v67, 0xbfb8aa3b, v128
	v_exp_f32_e32 v67, v67
	s_waitcnt lgkmcnt(0)
	v_add_f32_e32 v68, v68, v73
	ds_bpermute_b32 v73, v222, v68
	v_and_b32_e32 v70, 0xffff0000, v66
	v_add_f32_e32 v67, 1.0, v67
	v_mul_f32_e32 v66, 0xbfb8aa3b, v70
	v_lshlrev_b32_e32 v130, 16, v65
	s_waitcnt lgkmcnt(0)
	v_add_f32_e32 v73, v68, v73
	ds_bpermute_b32 v81, v223, v73
	v_exp_f32_e32 v66, v66
	v_rcp_f32_e32 v136, v67
	v_mul_f32_e32 v67, 0xbfb8aa3b, v130
	v_exp_f32_e32 v67, v67
	s_waitcnt lgkmcnt(0)
	v_add_f32_e32 v73, v73, v81
	ds_bpermute_b32 v81, v224, v73
	v_add_f32_e32 v66, 1.0, v66
	v_and_b32_e32 v68, 0xffff0000, v65
	v_rcp_f32_e32 v138, v66
	v_add_f32_e32 v66, 1.0, v67
	v_mul_f32_e32 v65, 0xbfb8aa3b, v68
	v_rcp_f32_e32 v140, v66
	s_waitcnt lgkmcnt(0)
; __device__ __forceinline__ float bflo(unsigned u) { return __uint_as_float(u << 16); }
; __device__ __forceinline__ float bfhi(unsigned u) { return __uint_as_float(u & 0xffff0000u); }
; __device__ __forceinline__ float siluf_(float x) { return x * __builtin_amdgcn_rcpf(1.f + __expf(-x)); }
; __device__ __forceinline__ void phase_finalize(const Params& p, int layer) {
;     ...
;     float r0 = rsqrtf(s0 * (1.f / 1024.f) + 1e-6f), r1 = rsqrtf(s1 * (1.f / 2048.f) + 1e-6f), r2 = rsqrtf(s2 * (1.f / 1024.f) + 1e-6f);
; #pragma unroll
;     for (int i = 0; i < 8; ++i) {
;       int col = i * 512 + lane * 8;
;       float rs = (i < 2) ? r0 : ((i < 6) ? r1 : r2);
;       u32x4 gt = gts[i];
;       float gv[8] = {bflo(gt.x), bfhi(gt.x), bflo(gt.y), bfhi(gt.y), bflo(gt.z), bfhi(gt.z), bflo(gt.w), bfhi(gt.w)};
;       float o[8];
; #pragma unroll
;       for (int j = 0; j < 8; ++j) o[j] = f[i][j] * rs * ggv[i][j >> 2][j & 3] * siluf_(gv[j]);
;       u32x4 pk = {pack2(o[0], o[1]), pack2(o[2], o[3]), pack2(o[4], o[5]), pack2(o[6], o[7])};
;       *reinterpret_cast<u32x4*>(Y + (size_t)row * DM + col) = pk;
;     }
;   }
	v_add_f32_e32 v66, v73, v81
	v_exp_f32_e32 v65, v65
	ds_bpermute_b32 v67, v225, v66
	v_and_b32_e32 v134, 0xffff0000, v64
	v_lshlrev_b32_e32 v132, 16, v64
	v_add_f32_e32 v65, 1.0, v65
	v_rcp_f32_e32 v142, v65
	s_waitcnt lgkmcnt(0)
	v_add_f32_e32 v65, v66, v67
	ds_bpermute_b32 v66, v226, v65
	v_mul_f32_e32 v64, 0xbfb8aa3b, v134
	v_exp_f32_e32 v64, v64
	v_mul_f32_e32 v73, 0xbfb8aa3b, v132
	v_exp_f32_e32 v73, v73
	s_waitcnt lgkmcnt(0)
	v_add_f32_e32 v65, v65, v66
	v_fmamk_f32 v65, v65, 0x3a800000, v211
	v_mul_f32_e32 v66, 0x4b800000, v65
	v_cmp_gt_f32_e32 vcc, s1, v65
	v_add_f32_e32 v64, 1.0, v64
	v_rcp_f32_e32 v72, v72
	v_cndmask_b32_e32 v65, v65, v66, vcc
	v_rsq_f32_e32 v65, v65
	v_rcp_f32_e32 v146, v64
	v_add_f32_e32 v67, 1.0, v73
	v_rcp_f32_e32 v144, v67
	v_mul_f32_e32 v64, 0x45800000, v65
	v_cndmask_b32_e32 v103, v65, v64, vcc
	v_pk_mul_f32 v[64:65], v[102:103], v[98:99]
	v_mov_b32_e32 v73, v103
	v_mul_f32_e32 v65, v4, v65
	v_mul_f32_e32 v66, v64, v65
	v_pk_mul_f32 v[64:65], v[72:73], v[76:77]
	v_mov_b32_e32 v93, v103
	v_mul_f32_e32 v65, v5, v65
	v_mul_f32_e32 v67, v64, v65
	v_pk_mul_f32 v[64:65], v[92:93], v[78:79]
	v_mov_b32_e32 v101, v103
	v_mul_f32_e32 v65, v6, v65
	v_mul_f32_e32 v72, v64, v65
	v_pk_mul_f32 v[64:65], v[100:101], v[94:95]
	v_mov_b32_e32 v89, v103
	v_mul_f32_e32 v65, v7, v65
	v_rcp_f32_e32 v80, v80
	v_mul_f32_e32 v73, v64, v65
	v_pk_mul_f32 v[64:65], v[88:89], v[82:83]
	v_mov_b32_e32 v91, v103
	v_mul_f32_e32 v65, v12, v65
	v_mul_f32_e32 v76, v64, v65
	v_pk_mul_f32 v[64:65], v[90:91], v[74:75]
	v_mov_b32_e32 v81, v103
	v_mul_f32_e32 v65, v13, v65
	v_mul_f32_e32 v74, v64, v65
	v_pk_mul_f32 v[64:65], v[80:81], v[84:85]
	v_mov_b32_e32 v107, v103
	v_mul_f32_e32 v65, v14, v65
	v_mul_f32_e32 v75, v64, v65
	v_pk_mul_f32 v[64:65], v[106:107], v[86:87]
	v_lshl_add_u64 v[108:109], v[126:127], 0, v[122:123]
	v_mul_f32_e32 v65, v15, v65
	v_mul_f32_e32 v77, v64, v65
	v_cvt_pk_bf16_f32 v64, v66, v67
	v_cvt_pk_bf16_f32 v65, v72, v73
	v_mov_b32_e32 v145, v103
	v_cvt_pk_bf16_f32 v66, v76, v74
	v_cvt_pk_bf16_f32 v67, v75, v77
	global_store_dwordx4 v[108:109], v[64:67], off sc1
	v_mov_b32_e32 v147, v103
	v_mov_b32_e32 v141, v103
	v_pk_mul_f32 v[64:65], v[144:145], v[132:133]
	v_mov_b32_e32 v143, v103
	v_mul_f32_e32 v65, v8, v65
	v_mul_f32_e32 v66, v64, v65
	v_pk_mul_f32 v[64:65], v[146:147], v[134:135]
	v_mov_b32_e32 v137, v103
	v_mul_f32_e32 v65, v9, v65
	v_mul_f32_e32 v67, v64, v65
	v_pk_mul_f32 v[64:65], v[140:141], v[130:131]
	v_mov_b32_e32 v139, v103
	v_mul_f32_e32 v65, v10, v65
	v_mul_f32_e32 v72, v64, v65
	v_pk_mul_f32 v[64:65], v[142:143], v[68:69]
	v_mov_b32_e32 v111, v103
	v_mul_f32_e32 v65, v11, v65
	v_mul_f32_e32 v68, v64, v65
	v_pk_mul_f32 v[64:65], v[136:137], v[128:129]
	s_nop 0
	v_mul_f32_e32 v65, v0, v65
	v_mul_f32_e32 v69, v64, v65
	v_pk_mul_f32 v[64:65], v[138:139], v[70:71]
	v_mul_f32_e32 v70, 0xbfb8aa3b, v112
	v_exp_f32_e32 v70, v70
	v_mul_f32_e32 v65, v1, v65
	v_mul_f32_e32 v71, v64, v65
	v_add_f32_e32 v64, 1.0, v70
	v_rcp_f32_e32 v102, v64
	v_pk_mul_f32 v[64:65], v[110:111], v[104:105]
	s_nop 0
	v_mul_f32_e32 v65, v2, v65
	v_mul_f32_e32 v70, v64, v65
	v_pk_mul_f32 v[64:65], v[102:103], v[112:113]
	s_nop 0
	v_mul_f32_e32 v65, v3, v65
	v_mul_f32_e32 v73, v64, v65
	v_cvt_pk_bf16_f32 v64, v66, v67
	v_cvt_pk_bf16_f32 v65, v72, v68
	v_cvt_pk_bf16_f32 v66, v69, v71
	v_lshl_add_u64 v[68:69], v[126:127], 0, v[124:125]
	v_cvt_pk_bf16_f32 v67, v70, v73
	global_store_dwordx4 v[68:69], v[64:67], off sc1
	s_load_dword s16, s[48:49], 0x0
	s_waitcnt lgkmcnt(0)
	v_lshl_add_u32 v114, s16, 3, v114
	v_cmp_lt_i32_e32 vcc, s20, v114
	s_or_b64 s[14:15], vcc, s[14:15]
	s_andn2_b64 exec, exec, s[14:15]
	s_cbranch_execnz .LBB0_51

; __device__ __forceinline__ void convert_item(const float* __restrict__ src, int Ksz, int Nsz, u16* __restrict__ dst, int kb, int nb,
;                                              int mode, const int tid) {
;   const int n = nb * NTHR + tid;
;   if (n < Nsz) {
;     const float* sp = src + (size_t)(kb * 64) * Nsz + n;
;     float v[64];
; #pragma unroll
;     for (int j = 0; j < 64; ++j) v[j] = sp[(size_t)j * Nsz];
;     int nd = n;
;     if (mode == 1) {
;       int isg = n >= 1024, c = n & 1023;
;       nd = (c >> 7) * 256 + isg * 128 + (c & 127);
;     }
;     u32x4* d = reinterpret_cast<u32x4*>(dst + (size_t)nd * Ksz + kb * 64);
.Lcvm_nd:
	s_lshl_b32 s30, s25, 1
	s_lshl_b32 s31, s29, 1
	s_add_u32 s22, s22, s31
	s_addc_u32 s23, s23, 0
	s_lshl_b32 s6, s30, 3
	s_mov_b32 s7, 0
	v_mov_b32_e32 v86, s22
	v_mov_b32_e32 v87, s23
	v_mov_b32_e32 v88, s30
	v_mad_u64_u32 v[90:91], vcc, v84, v88, v[86:87]
	v_and_b32_e32 v0, 7, v164
	v_lshlrev_b32_e32 v0, 4, v0
	v_add_co_u32_e32 v84, vcc, v90, v0
	s_nop 1
	v_addc_co_u32_e32 v85, vcc, 0, v91, vcc
	v_lshlrev_b32_e32 v1, 2, v164
	v_lshrrev_b32_e32 v2, 6, v164
	v_mul_u32_u24_e32 v2, 0x2400, v2
	v_and_b32_e32 v3, 63, v164
	v_lshrrev_b32_e32 v89, 3, v3
	v_mul_u32_u24_e32 v89, 0x90, v89
	v_add3_u32 v89, v89, v0, v2
	v_mul_u32_u24_e32 v3, 0x90, v3
	v_add3_u32 v2, v2, v3, 32
	v_add_u32_e32 v3, 32, v89
	global_load_dword v4, v1, s[8:9]
	s_add_u32 s8, s8, s10
	s_addc_u32 s9, s9, 0
	global_load_dword v5, v1, s[8:9]
	s_add_u32 s8, s8, s10
	s_addc_u32 s9, s9, 0
	global_load_dword v6, v1, s[8:9]
	s_add_u32 s8, s8, s10
	s_addc_u32 s9, s9, 0
	global_load_dword v7, v1, s[8:9]
	s_add_u32 s8, s8, s10
	s_addc_u32 s9, s9, 0
	global_load_dword v8, v1, s[8:9]
	s_add_u32 s8, s8, s10
	s_addc_u32 s9, s9, 0
	global_load_dword v9, v1, s[8:9]
	s_add_u32 s8, s8, s10
	s_addc_u32 s9, s9, 0
	global_load_dword v10, v1, s[8:9]
	s_add_u32 s8, s8, s10
	s_addc_u32 s9, s9, 0
	global_load_dword v11, v1, s[8:9]
	s_add_u32 s8, s8, s10
	s_addc_u32 s9, s9, 0
	global_load_dword v12, v1, s[8:9]
	s_add_u32 s8, s8, s10
	s_addc_u32 s9, s9, 0
	global_load_dword v13, v1, s[8:9]
	s_add_u32 s8, s8, s10
	s_addc_u32 s9, s9, 0
	global_load_dword v14, v1, s[8:9]
	s_add_u32 s8, s8, s10
	s_addc_u32 s9, s9, 0
	global_load_dword v15, v1, s[8:9]
	s_add_u32 s8, s8, s10
	s_addc_u32 s9, s9, 0
	global_load_dword v16, v1, s[8:9]
	s_add_u32 s8, s8, s10
	s_addc_u32 s9, s9, 0
	global_load_dword v17, v1, s[8:9]
	s_add_u32 s8, s8, s10
	s_addc_u32 s9, s9, 0
	global_load_dword v18, v1, s[8:9]
	s_add_u32 s8, s8, s10
	s_addc_u32 s9, s9, 0
	global_load_dword v19, v1, s[8:9]
	s_add_u32 s8, s8, s10
	s_addc_u32 s9, s9, 0
	global_load_dword v20, v1, s[8:9]
	s_add_u32 s8, s8, s10
	s_addc_u32 s9, s9, 0
	global_load_dword v21, v1, s[8:9]
	s_add_u32 s8, s8, s10
	s_addc_u32 s9, s9, 0
	global_load_dword v22, v1, s[8:9]
	s_add_u32 s8, s8, s10
	s_addc_u32 s9, s9, 0
	global_load_dword v23, v1, s[8:9]
	s_add_u32 s8, s8, s10
	s_addc_u32 s9, s9, 0
	global_load_dword v24, v1, s[8:9]
	s_add_u32 s8, s8, s10
	s_addc_u32 s9, s9, 0
	global_load_dword v25, v1, s[8:9]
	s_add_u32 s8, s8, s10
	s_addc_u32 s9, s9, 0
	global_load_dword v26, v1, s[8:9]
	s_add_u32 s8, s8, s10
	s_addc_u32 s9, s9, 0
	global_load_dword v27, v1, s[8:9]
	s_add_u32 s8, s8, s10
	s_addc_u32 s9, s9, 0
	global_load_dword v28, v1, s[8:9]
	s_add_u32 s8, s8, s10
	s_addc_u32 s9, s9, 0
	global_load_dword v29, v1, s[8:9]
	s_add_u32 s8, s8, s10
	s_addc_u32 s9, s9, 0
	global_load_dword v30, v1, s[8:9]
	s_add_u32 s8, s8, s10
	s_addc_u32 s9, s9, 0
	global_load_dword v31, v1, s[8:9]
	s_add_u32 s8, s8, s10
	s_addc_u32 s9, s9, 0
	global_load_dword v32, v1, s[8:9]
	s_add_u32 s8, s8, s10
	s_addc_u32 s9, s9, 0
	global_load_dword v33, v1, s[8:9]
	s_add_u32 s8, s8, s10
	s_addc_u32 s9, s9, 0
	global_load_dword v34, v1, s[8:9]
	s_add_u32 s8, s8, s10
	s_addc_u32 s9, s9, 0
	global_load_dword v35, v1, s[8:9]
	s_add_u32 s8, s8, s10
	s_addc_u32 s9, s9, 0
	global_load_dword v36, v1, s[8:9]
	s_add_u32 s8, s8, s10
	s_addc_u32 s9, s9, 0
	global_load_dword v37, v1, s[8:9]
	s_add_u32 s8, s8, s10
	s_addc_u32 s9, s9, 0
	global_load_dword v38, v1, s[8:9]
	s_add_u32 s8, s8, s10
	s_addc_u32 s9, s9, 0
	global_load_dword v39, v1, s[8:9]
	s_add_u32 s8, s8, s10
	s_addc_u32 s9, s9, 0
	global_load_dword v40, v1, s[8:9]
	s_add_u32 s8, s8, s10
	s_addc_u32 s9, s9, 0
	global_load_dword v41, v1, s[8:9]
	s_add_u32 s8, s8, s10
	s_addc_u32 s9, s9, 0
	global_load_dword v42, v1, s[8:9]
	s_add_u32 s8, s8, s10
	s_addc_u32 s9, s9, 0
	global_load_dword v43, v1, s[8:9]
	s_add_u32 s8, s8, s10
	s_addc_u32 s9, s9, 0
	global_load_dword v44, v1, s[8:9]
	s_add_u32 s8, s8, s10
	s_addc_u32 s9, s9, 0
	global_load_dword v45, v1, s[8:9]
	s_add_u32 s8, s8, s10
	s_addc_u32 s9, s9, 0
	global_load_dword v46, v1, s[8:9]
	s_add_u32 s8, s8, s10
	s_addc_u32 s9, s9, 0
	global_load_dword v47, v1, s[8:9]
	s_add_u32 s8, s8, s10
	s_addc_u32 s9, s9, 0
	global_load_dword v48, v1, s[8:9]
	s_add_u32 s8, s8, s10
	s_addc_u32 s9, s9, 0
	global_load_dword v49, v1, s[8:9]
	s_add_u32 s8, s8, s10
	s_addc_u32 s9, s9, 0
	global_load_dword v50, v1, s[8:9]
	s_add_u32 s8, s8, s10
	s_addc_u32 s9, s9, 0
	global_load_dword v51, v1, s[8:9]
	s_add_u32 s8, s8, s10
	s_addc_u32 s9, s9, 0
	global_load_dword v52, v1, s[8:9]
	s_add_u32 s8, s8, s10
	s_addc_u32 s9, s9, 0
	global_load_dword v53, v1, s[8:9]
	s_add_u32 s8, s8, s10
	s_addc_u32 s9, s9, 0
	global_load_dword v54, v1, s[8:9]
	s_add_u32 s8, s8, s10
	s_addc_u32 s9, s9, 0
	global_load_dword v55, v1, s[8:9]
	s_add_u32 s8, s8, s10
	s_addc_u32 s9, s9, 0
	global_load_dword v56, v1, s[8:9]
	s_add_u32 s8, s8, s10
	s_addc_u32 s9, s9, 0
	global_load_dword v57, v1, s[8:9]
	s_add_u32 s8, s8, s10
	s_addc_u32 s9, s9, 0
	global_load_dword v58, v1, s[8:9]
	s_add_u32 s8, s8, s10
	s_addc_u32 s9, s9, 0
	global_load_dword v59, v1, s[8:9]
	s_add_u32 s8, s8, s10
	s_addc_u32 s9, s9, 0
	global_load_dword v60, v1, s[8:9]
	s_add_u32 s8, s8, s10
	s_addc_u32 s9, s9, 0
	global_load_dword v61, v1, s[8:9]
	s_add_u32 s8, s8, s10
	s_addc_u32 s9, s9, 0
	global_load_dword v62, v1, s[8:9]
	s_add_u32 s8, s8, s10
	s_addc_u32 s9, s9, 0
	global_load_dword v63, v1, s[8:9]
	s_add_u32 s8, s8, s10
	s_addc_u32 s9, s9, 0
	global_load_dword v64, v1, s[8:9]
	s_add_u32 s8, s8, s10
	s_addc_u32 s9, s9, 0
	global_load_dword v65, v1, s[8:9]
	s_add_u32 s8, s8, s10
	s_addc_u32 s9, s9, 0
	global_load_dword v66, v1, s[8:9]
	s_add_u32 s8, s8, s10
	s_addc_u32 s9, s9, 0
	global_load_dword v67, v1, s[8:9]
	s_add_u32 s8, s8, s10
	s_addc_u32 s9, s9, 0
	s_waitcnt vmcnt(32)
; __device__ __forceinline__ void convert_item(const float* __restrict__ src, int Ksz, int Nsz, u16* __restrict__ dst, int kb, int nb,
;                                              int mode, const int tid) {
;     ...
;     const float* sp = src + (size_t)(kb * 64) * Nsz + n;
;     float v[64];
; #pragma unroll
;     for (int j = 0; j < 64; ++j) v[j] = sp[(size_t)j * Nsz];
;     int nd = n;
;     if (mode == 1) {
;       int isg = n >= 1024, c = n & 1023;
;       nd = (c >> 7) * 256 + isg * 128 + (c & 127);
;     }
;     u32x4* d = reinterpret_cast<u32x4*>(dst + (size_t)nd * Ksz + kb * 64);
; #pragma unroll
;     for (int q = 0; q < 8; ++q) {
;       u32x4 o;
;       o.x = pack2(v[q * 8 + 0], v[q * 8 + 1]);
;       o.y = pack2(v[q * 8 + 2], v[q * 8 + 3]);
;       o.z = pack2(v[q * 8 + 4], v[q * 8 + 5]);
;       o.w = pack2(v[q * 8 + 6], v[q * 8 + 7]);
;       d[q] = o;
;     }
	v_cvt_pk_bf16_f32 v68, v4, v5
	v_cvt_pk_bf16_f32 v69, v6, v7
	v_cvt_pk_bf16_f32 v70, v8, v9
	v_cvt_pk_bf16_f32 v71, v10, v11
	v_cvt_pk_bf16_f32 v72, v12, v13
	v_cvt_pk_bf16_f32 v73, v14, v15
	v_cvt_pk_bf16_f32 v74, v16, v17
	v_cvt_pk_bf16_f32 v75, v18, v19
	v_cvt_pk_bf16_f32 v76, v20, v21
	v_cvt_pk_bf16_f32 v77, v22, v23
	v_cvt_pk_bf16_f32 v78, v24, v25
	v_cvt_pk_bf16_f32 v79, v26, v27
	v_cvt_pk_bf16_f32 v80, v28, v29
	v_cvt_pk_bf16_f32 v81, v30, v31
	v_cvt_pk_bf16_f32 v82, v32, v33
	v_cvt_pk_bf16_f32 v83, v34, v35
	ds_write_b128 v2, v[68:71] offset:0
	ds_write_b128 v2, v[72:75] offset:16
	ds_write_b128 v2, v[76:79] offset:32
	ds_write_b128 v2, v[80:83] offset:48
	global_load_dword v4, v1, s[8:9]
	s_add_u32 s8, s8, s10
	s_addc_u32 s9, s9, 0
	global_load_dword v5, v1, s[8:9]
	s_add_u32 s8, s8, s10
	s_addc_u32 s9, s9, 0
	global_load_dword v6, v1, s[8:9]
	s_add_u32 s8, s8, s10
	s_addc_u32 s9, s9, 0
	global_load_dword v7, v1, s[8:9]
	s_add_u32 s8, s8, s10
	s_addc_u32 s9, s9, 0
	global_load_dword v8, v1, s[8:9]
	s_add_u32 s8, s8, s10
	s_addc_u32 s9, s9, 0
	global_load_dword v9, v1, s[8:9]
	s_add_u32 s8, s8, s10
	s_addc_u32 s9, s9, 0
	global_load_dword v10, v1, s[8:9]
	s_add_u32 s8, s8, s10
	s_addc_u32 s9, s9, 0
	global_load_dword v11, v1, s[8:9]
	s_add_u32 s8, s8, s10
	s_addc_u32 s9, s9, 0
	global_load_dword v12, v1, s[8:9]
	s_add_u32 s8, s8, s10
	s_addc_u32 s9, s9, 0
	global_load_dword v13, v1, s[8:9]
	s_add_u32 s8, s8, s10
	s_addc_u32 s9, s9, 0
	global_load_dword v14, v1, s[8:9]
	s_add_u32 s8, s8, s10
	s_addc_u32 s9, s9, 0
	global_load_dword v15, v1, s[8:9]
	s_add_u32 s8, s8, s10
	s_addc_u32 s9, s9, 0
	global_load_dword v16, v1, s[8:9]
	s_add_u32 s8, s8, s10
	s_addc_u32 s9, s9, 0
	global_load_dword v17, v1, s[8:9]
	s_add_u32 s8, s8, s10
	s_addc_u32 s9, s9, 0
	global_load_dword v18, v1, s[8:9]
	s_add_u32 s8, s8, s10
	s_addc_u32 s9, s9, 0
	global_load_dword v19, v1, s[8:9]
	s_add_u32 s8, s8, s10
	s_addc_u32 s9, s9, 0
	global_load_dword v20, v1, s[8:9]
	s_add_u32 s8, s8, s10
	s_addc_u32 s9, s9, 0
	global_load_dword v21, v1, s[8:9]
	s_add_u32 s8, s8, s10
	s_addc_u32 s9, s9, 0
	global_load_dword v22, v1, s[8:9]
	s_add_u32 s8, s8, s10
	s_addc_u32 s9, s9, 0
	global_load_dword v23, v1, s[8:9]
	s_add_u32 s8, s8, s10
	s_addc_u32 s9, s9, 0
	global_load_dword v24, v1, s[8:9]
	s_add_u32 s8, s8, s10
	s_addc_u32 s9, s9, 0
	global_load_dword v25, v1, s[8:9]
	s_add_u32 s8, s8, s10
	s_addc_u32 s9, s9, 0
	global_load_dword v26, v1, s[8:9]
	s_add_u32 s8, s8, s10
	s_addc_u32 s9, s9, 0
	global_load_dword v27, v1, s[8:9]
	s_add_u32 s8, s8, s10
	s_addc_u32 s9, s9, 0
	global_load_dword v28, v1, s[8:9]
	s_add_u32 s8, s8, s10
	s_addc_u32 s9, s9, 0
	global_load_dword v29, v1, s[8:9]
	s_add_u32 s8, s8, s10
	s_addc_u32 s9, s9, 0
	global_load_dword v30, v1, s[8:9]
	s_add_u32 s8, s8, s10
	s_addc_u32 s9, s9, 0
	global_load_dword v31, v1, s[8:9]
	s_add_u32 s8, s8, s10
	s_addc_u32 s9, s9, 0
	global_load_dword v32, v1, s[8:9]
	s_add_u32 s8, s8, s10
	s_addc_u32 s9, s9, 0
	global_load_dword v33, v1, s[8:9]
	s_add_u32 s8, s8, s10
	s_addc_u32 s9, s9, 0
	global_load_dword v34, v1, s[8:9]
	s_add_u32 s8, s8, s10
	s_addc_u32 s9, s9, 0
	global_load_dword v35, v1, s[8:9]
	s_add_u32 s8, s8, s10
	s_addc_u32 s9, s9, 0
	s_waitcnt vmcnt(32)
	v_cvt_pk_bf16_f32 v100, v36, v37
	v_cvt_pk_bf16_f32 v101, v38, v39
	v_cvt_pk_bf16_f32 v102, v40, v41
	v_cvt_pk_bf16_f32 v103, v42, v43
	v_cvt_pk_bf16_f32 v104, v44, v45
	v_cvt_pk_bf16_f32 v105, v46, v47
	v_cvt_pk_bf16_f32 v106, v48, v49
	v_cvt_pk_bf16_f32 v107, v50, v51
	v_cvt_pk_bf16_f32 v108, v52, v53
	v_cvt_pk_bf16_f32 v109, v54, v55
	v_cvt_pk_bf16_f32 v110, v56, v57
	v_cvt_pk_bf16_f32 v111, v58, v59
	v_cvt_pk_bf16_f32 v112, v60, v61
	v_cvt_pk_bf16_f32 v113, v62, v63
	v_cvt_pk_bf16_f32 v114, v64, v65
	v_cvt_pk_bf16_f32 v115, v66, v67
	ds_write_b128 v2, v[100:103] offset:64
	ds_write_b128 v2, v[104:107] offset:80
	ds_write_b128 v2, v[108:111] offset:96
	ds_write_b128 v2, v[112:115] offset:112
	global_load_dword v36, v1, s[8:9]
	s_add_u32 s8, s8, s10
	s_addc_u32 s9, s9, 0
	global_load_dword v37, v1, s[8:9]
	s_add_u32 s8, s8, s10
	s_addc_u32 s9, s9, 0
	global_load_dword v38, v1, s[8:9]
	s_add_u32 s8, s8, s10
	s_addc_u32 s9, s9, 0
	global_load_dword v39, v1, s[8:9]
	s_add_u32 s8, s8, s10
	s_addc_u32 s9, s9, 0
	global_load_dword v40, v1, s[8:9]
	s_add_u32 s8, s8, s10
	s_addc_u32 s9, s9, 0
	global_load_dword v41, v1, s[8:9]
	s_add_u32 s8, s8, s10
	s_addc_u32 s9, s9, 0
	global_load_dword v42, v1, s[8:9]
	s_add_u32 s8, s8, s10
	s_addc_u32 s9, s9, 0
	global_load_dword v43, v1, s[8:9]
	s_add_u32 s8, s8, s10
	s_addc_u32 s9, s9, 0
	global_load_dword v44, v1, s[8:9]
	s_add_u32 s8, s8, s10
	s_addc_u32 s9, s9, 0
	global_load_dword v45, v1, s[8:9]
	s_add_u32 s8, s8, s10
	s_addc_u32 s9, s9, 0
	global_load_dword v46, v1, s[8:9]
	s_add_u32 s8, s8, s10
	s_addc_u32 s9, s9, 0
	global_load_dword v47, v1, s[8:9]
	s_add_u32 s8, s8, s10
	s_addc_u32 s9, s9, 0
	global_load_dword v48, v1, s[8:9]
	s_add_u32 s8, s8, s10
	s_addc_u32 s9, s9, 0
	global_load_dword v49, v1, s[8:9]
	s_add_u32 s8, s8, s10
	s_addc_u32 s9, s9, 0
	global_load_dword v50, v1, s[8:9]
	s_add_u32 s8, s8, s10
	s_addc_u32 s9, s9, 0
	global_load_dword v51, v1, s[8:9]
	s_add_u32 s8, s8, s10
	s_addc_u32 s9, s9, 0
	global_load_dword v52, v1, s[8:9]
	s_add_u32 s8, s8, s10
	s_addc_u32 s9, s9, 0
	global_load_dword v53, v1, s[8:9]
	s_add_u32 s8, s8, s10
	s_addc_u32 s9, s9, 0
	global_load_dword v54, v1, s[8:9]
	s_add_u32 s8, s8, s10
	s_addc_u32 s9, s9, 0
	global_load_dword v55, v1, s[8:9]
	s_add_u32 s8, s8, s10
	s_addc_u32 s9, s9, 0
	global_load_dword v56, v1, s[8:9]
	s_add_u32 s8, s8, s10
	s_addc_u32 s9, s9, 0
	global_load_dword v57, v1, s[8:9]
	s_add_u32 s8, s8, s10
	s_addc_u32 s9, s9, 0
	global_load_dword v58, v1, s[8:9]
	s_add_u32 s8, s8, s10
	s_addc_u32 s9, s9, 0
	global_load_dword v59, v1, s[8:9]
	s_add_u32 s8, s8, s10
	s_addc_u32 s9, s9, 0
	global_load_dword v60, v1, s[8:9]
	s_add_u32 s8, s8, s10
	s_addc_u32 s9, s9, 0
	global_load_dword v61, v1, s[8:9]
	s_add_u32 s8, s8, s10
	s_addc_u32 s9, s9, 0
	global_load_dword v62, v1, s[8:9]
	s_add_u32 s8, s8, s10
	s_addc_u32 s9, s9, 0
	global_load_dword v63, v1, s[8:9]
	s_add_u32 s8, s8, s10
	s_addc_u32 s9, s9, 0
	global_load_dword v64, v1, s[8:9]
	s_add_u32 s8, s8, s10
	s_addc_u32 s9, s9, 0
	global_load_dword v65, v1, s[8:9]
	s_add_u32 s8, s8, s10
	s_addc_u32 s9, s9, 0
	global_load_dword v66, v1, s[8:9]
	s_add_u32 s8, s8, s10
	s_addc_u32 s9, s9, 0
	global_load_dword v67, v1, s[8:9]
	s_add_u32 s8, s8, s10
	s_addc_u32 s9, s9, 0
	v_mov_b32_e32 v86, v84
	v_mov_b32_e32 v87, v85
	ds_read_b128 v[116:119], v3 offset:0
	ds_read_b128 v[120:123], v3 offset:1152
	ds_read_b128 v[124:127], v3 offset:2304
	ds_read_b128 v[128:131], v3 offset:3456
	s_waitcnt lgkmcnt(0)
; __device__ __forceinline__ void convert_item(const float* __restrict__ src, int Ksz, int Nsz, u16* __restrict__ dst, int kb, int nb,
;                                              int mode, const int tid) {
;     ...
;     u32x4* d = reinterpret_cast<u32x4*>(dst + (size_t)nd * Ksz + kb * 64);
; #pragma unroll
;     for (int q = 0; q < 8; ++q) {
;       u32x4 o;
;       o.x = pack2(v[q * 8 + 0], v[q * 8 + 1]);
;       o.y = pack2(v[q * 8 + 2], v[q * 8 + 3]);
;       o.z = pack2(v[q * 8 + 4], v[q * 8 + 5]);
;       o.w = pack2(v[q * 8 + 6], v[q * 8 + 7]);
;       d[q] = o;
;     }
	global_store_dwordx4 v[86:87], v[116:119], off offset:0 sc1
	v_lshl_add_u64 v[86:87], v[86:87], 0, s[6:7]
	global_store_dwordx4 v[86:87], v[120:123], off offset:0 sc1
	v_lshl_add_u64 v[86:87], v[86:87], 0, s[6:7]
	global_store_dwordx4 v[86:87], v[124:127], off offset:0 sc1
	v_lshl_add_u64 v[86:87], v[86:87], 0, s[6:7]
	global_store_dwordx4 v[86:87], v[128:131], off offset:0 sc1
	v_lshl_add_u64 v[86:87], v[86:87], 0, s[6:7]
	ds_read_b128 v[116:119], v3 offset:4608
	ds_read_b128 v[120:123], v3 offset:5760
	ds_read_b128 v[124:127], v3 offset:6912
	ds_read_b128 v[128:131], v3 offset:8064
	s_waitcnt lgkmcnt(0)
	global_store_dwordx4 v[86:87], v[116:119], off offset:0 sc1
	v_lshl_add_u64 v[86:87], v[86:87], 0, s[6:7]
	global_store_dwordx4 v[86:87], v[120:123], off offset:0 sc1
	v_lshl_add_u64 v[86:87], v[86:87], 0, s[6:7]
	global_store_dwordx4 v[86:87], v[124:127], off offset:0 sc1
	v_lshl_add_u64 v[86:87], v[86:87], 0, s[6:7]
	global_store_dwordx4 v[86:87], v[128:131], off offset:0 sc1
	v_lshl_add_u64 v[86:87], v[86:87], 0, s[6:7]
	s_waitcnt vmcnt(40)
	v_cvt_pk_bf16_f32 v68, v4, v5
	v_cvt_pk_bf16_f32 v69, v6, v7
	v_cvt_pk_bf16_f32 v70, v8, v9
	v_cvt_pk_bf16_f32 v71, v10, v11
	v_cvt_pk_bf16_f32 v72, v12, v13
	v_cvt_pk_bf16_f32 v73, v14, v15
	v_cvt_pk_bf16_f32 v74, v16, v17
	v_cvt_pk_bf16_f32 v75, v18, v19
	v_cvt_pk_bf16_f32 v76, v20, v21
	v_cvt_pk_bf16_f32 v77, v22, v23
	v_cvt_pk_bf16_f32 v78, v24, v25
	v_cvt_pk_bf16_f32 v79, v26, v27
	v_cvt_pk_bf16_f32 v80, v28, v29
	v_cvt_pk_bf16_f32 v81, v30, v31
	v_cvt_pk_bf16_f32 v82, v32, v33
	v_cvt_pk_bf16_f32 v83, v34, v35
	ds_write_b128 v2, v[68:71] offset:0
	ds_write_b128 v2, v[72:75] offset:16
	ds_write_b128 v2, v[76:79] offset:32
	ds_write_b128 v2, v[80:83] offset:48
	global_load_dword v4, v1, s[8:9]
	s_add_u32 s8, s8, s10
	s_addc_u32 s9, s9, 0
	global_load_dword v5, v1, s[8:9]
	s_add_u32 s8, s8, s10
	s_addc_u32 s9, s9, 0
	global_load_dword v6, v1, s[8:9]
	s_add_u32 s8, s8, s10
	s_addc_u32 s9, s9, 0
	global_load_dword v7, v1, s[8:9]
	s_add_u32 s8, s8, s10
	s_addc_u32 s9, s9, 0
	global_load_dword v8, v1, s[8:9]
	s_add_u32 s8, s8, s10
	s_addc_u32 s9, s9, 0
	global_load_dword v9, v1, s[8:9]
	s_add_u32 s8, s8, s10
	s_addc_u32 s9, s9, 0
	global_load_dword v10, v1, s[8:9]
	s_add_u32 s8, s8, s10
	s_addc_u32 s9, s9, 0
	global_load_dword v11, v1, s[8:9]
	s_add_u32 s8, s8, s10
	s_addc_u32 s9, s9, 0
	global_load_dword v12, v1, s[8:9]
	s_add_u32 s8, s8, s10
	s_addc_u32 s9, s9, 0
	global_load_dword v13, v1, s[8:9]
	s_add_u32 s8, s8, s10
	s_addc_u32 s9, s9, 0
	global_load_dword v14, v1, s[8:9]
	s_add_u32 s8, s8, s10
	s_addc_u32 s9, s9, 0
	global_load_dword v15, v1, s[8:9]
	s_add_u32 s8, s8, s10
	s_addc_u32 s9, s9, 0
	global_load_dword v16, v1, s[8:9]
	s_add_u32 s8, s8, s10
	s_addc_u32 s9, s9, 0
	global_load_dword v17, v1, s[8:9]
	s_add_u32 s8, s8, s10
	s_addc_u32 s9, s9, 0
	global_load_dword v18, v1, s[8:9]
	s_add_u32 s8, s8, s10
	s_addc_u32 s9, s9, 0
	global_load_dword v19, v1, s[8:9]
	s_add_u32 s8, s8, s10
	s_addc_u32 s9, s9, 0
	global_load_dword v20, v1, s[8:9]
	s_add_u32 s8, s8, s10
	s_addc_u32 s9, s9, 0
	global_load_dword v21, v1, s[8:9]
	s_add_u32 s8, s8, s10
	s_addc_u32 s9, s9, 0
	global_load_dword v22, v1, s[8:9]
	s_add_u32 s8, s8, s10
	s_addc_u32 s9, s9, 0
	global_load_dword v23, v1, s[8:9]
	s_add_u32 s8, s8, s10
	s_addc_u32 s9, s9, 0
	global_load_dword v24, v1, s[8:9]
	s_add_u32 s8, s8, s10
	s_addc_u32 s9, s9, 0
	global_load_dword v25, v1, s[8:9]
	s_add_u32 s8, s8, s10
	s_addc_u32 s9, s9, 0
	global_load_dword v26, v1, s[8:9]
	s_add_u32 s8, s8, s10
	s_addc_u32 s9, s9, 0
	global_load_dword v27, v1, s[8:9]
	s_add_u32 s8, s8, s10
	s_addc_u32 s9, s9, 0
	global_load_dword v28, v1, s[8:9]
	s_add_u32 s8, s8, s10
	s_addc_u32 s9, s9, 0
	global_load_dword v29, v1, s[8:9]
	s_add_u32 s8, s8, s10
	s_addc_u32 s9, s9, 0
	global_load_dword v30, v1, s[8:9]
	s_add_u32 s8, s8, s10
	s_addc_u32 s9, s9, 0
	global_load_dword v31, v1, s[8:9]
	s_add_u32 s8, s8, s10
	s_addc_u32 s9, s9, 0
	global_load_dword v32, v1, s[8:9]
	s_add_u32 s8, s8, s10
	s_addc_u32 s9, s9, 0
	global_load_dword v33, v1, s[8:9]
	s_add_u32 s8, s8, s10
	s_addc_u32 s9, s9, 0
	global_load_dword v34, v1, s[8:9]
	s_add_u32 s8, s8, s10
	s_addc_u32 s9, s9, 0
	global_load_dword v35, v1, s[8:9]
	s_add_u32 s8, s8, s10
	s_addc_u32 s9, s9, 0
	s_waitcnt vmcnt(40)
; __device__ __forceinline__ void convert_item(const float* __restrict__ src, int Ksz, int Nsz, u16* __restrict__ dst, int kb, int nb,
;                                              int mode, const int tid) {
;     ...
;     u32x4* d = reinterpret_cast<u32x4*>(dst + (size_t)nd * Ksz + kb * 64);
; #pragma unroll
;     for (int q = 0; q < 8; ++q) {
;       u32x4 o;
;       o.x = pack2(v[q * 8 + 0], v[q * 8 + 1]);
;       o.y = pack2(v[q * 8 + 2], v[q * 8 + 3]);
;       o.z = pack2(v[q * 8 + 4], v[q * 8 + 5]);
;       o.w = pack2(v[q * 8 + 6], v[q * 8 + 7]);
;       d[q] = o;
;     }
	v_cvt_pk_bf16_f32 v100, v36, v37
	v_cvt_pk_bf16_f32 v101, v38, v39
	v_cvt_pk_bf16_f32 v102, v40, v41
	v_cvt_pk_bf16_f32 v103, v42, v43
	v_cvt_pk_bf16_f32 v104, v44, v45
	v_cvt_pk_bf16_f32 v105, v46, v47
	v_cvt_pk_bf16_f32 v106, v48, v49
	v_cvt_pk_bf16_f32 v107, v50, v51
	v_cvt_pk_bf16_f32 v108, v52, v53
	v_cvt_pk_bf16_f32 v109, v54, v55
	v_cvt_pk_bf16_f32 v110, v56, v57
	v_cvt_pk_bf16_f32 v111, v58, v59
	v_cvt_pk_bf16_f32 v112, v60, v61
	v_cvt_pk_bf16_f32 v113, v62, v63
	v_cvt_pk_bf16_f32 v114, v64, v65
	v_cvt_pk_bf16_f32 v115, v66, v67
	ds_write_b128 v2, v[100:103] offset:64
	ds_write_b128 v2, v[104:107] offset:80
	ds_write_b128 v2, v[108:111] offset:96
	ds_write_b128 v2, v[112:115] offset:112
	global_load_dword v36, v1, s[8:9]
	s_add_u32 s8, s8, s10
	s_addc_u32 s9, s9, 0
	global_load_dword v37, v1, s[8:9]
	s_add_u32 s8, s8, s10
	s_addc_u32 s9, s9, 0
	global_load_dword v38, v1, s[8:9]
	s_add_u32 s8, s8, s10
	s_addc_u32 s9, s9, 0
	global_load_dword v39, v1, s[8:9]
	s_add_u32 s8, s8, s10
	s_addc_u32 s9, s9, 0
	global_load_dword v40, v1, s[8:9]
	s_add_u32 s8, s8, s10
	s_addc_u32 s9, s9, 0
	global_load_dword v41, v1, s[8:9]
	s_add_u32 s8, s8, s10
	s_addc_u32 s9, s9, 0
	global_load_dword v42, v1, s[8:9]
	s_add_u32 s8, s8, s10
	s_addc_u32 s9, s9, 0
	global_load_dword v43, v1, s[8:9]
	s_add_u32 s8, s8, s10
	s_addc_u32 s9, s9, 0
	global_load_dword v44, v1, s[8:9]
	s_add_u32 s8, s8, s10
	s_addc_u32 s9, s9, 0
	global_load_dword v45, v1, s[8:9]
	s_add_u32 s8, s8, s10
	s_addc_u32 s9, s9, 0
	global_load_dword v46, v1, s[8:9]
	s_add_u32 s8, s8, s10
	s_addc_u32 s9, s9, 0
	global_load_dword v47, v1, s[8:9]
	s_add_u32 s8, s8, s10
	s_addc_u32 s9, s9, 0
	global_load_dword v48, v1, s[8:9]
	s_add_u32 s8, s8, s10
	s_addc_u32 s9, s9, 0
	global_load_dword v49, v1, s[8:9]
	s_add_u32 s8, s8, s10
	s_addc_u32 s9, s9, 0
	global_load_dword v50, v1, s[8:9]
	s_add_u32 s8, s8, s10
	s_addc_u32 s9, s9, 0
	global_load_dword v51, v1, s[8:9]
	s_add_u32 s8, s8, s10
	s_addc_u32 s9, s9, 0
	global_load_dword v52, v1, s[8:9]
	s_add_u32 s8, s8, s10
	s_addc_u32 s9, s9, 0
	global_load_dword v53, v1, s[8:9]
	s_add_u32 s8, s8, s10
	s_addc_u32 s9, s9, 0
	global_load_dword v54, v1, s[8:9]
	s_add_u32 s8, s8, s10
	s_addc_u32 s9, s9, 0
	global_load_dword v55, v1, s[8:9]
	s_add_u32 s8, s8, s10
	s_addc_u32 s9, s9, 0
	global_load_dword v56, v1, s[8:9]
	s_add_u32 s8, s8, s10
	s_addc_u32 s9, s9, 0
	global_load_dword v57, v1, s[8:9]
	s_add_u32 s8, s8, s10
	s_addc_u32 s9, s9, 0
	global_load_dword v58, v1, s[8:9]
	s_add_u32 s8, s8, s10
	s_addc_u32 s9, s9, 0
	global_load_dword v59, v1, s[8:9]
	s_add_u32 s8, s8, s10
	s_addc_u32 s9, s9, 0
	global_load_dword v60, v1, s[8:9]
	s_add_u32 s8, s8, s10
	s_addc_u32 s9, s9, 0
	global_load_dword v61, v1, s[8:9]
	s_add_u32 s8, s8, s10
	s_addc_u32 s9, s9, 0
	global_load_dword v62, v1, s[8:9]
	s_add_u32 s8, s8, s10
	s_addc_u32 s9, s9, 0
	global_load_dword v63, v1, s[8:9]
	s_add_u32 s8, s8, s10
	s_addc_u32 s9, s9, 0
	global_load_dword v64, v1, s[8:9]
	s_add_u32 s8, s8, s10
	s_addc_u32 s9, s9, 0
	global_load_dword v65, v1, s[8:9]
	s_add_u32 s8, s8, s10
	s_addc_u32 s9, s9, 0
	global_load_dword v66, v1, s[8:9]
	s_add_u32 s8, s8, s10
	s_addc_u32 s9, s9, 0
	global_load_dword v67, v1, s[8:9]
	s_add_u32 s8, s8, s10
	s_addc_u32 s9, s9, 0
	v_mov_b32_e32 v86, v84
	v_mov_b32_e32 v87, v85
	ds_read_b128 v[116:119], v3 offset:0
	ds_read_b128 v[120:123], v3 offset:1152
	ds_read_b128 v[124:127], v3 offset:2304
	ds_read_b128 v[128:131], v3 offset:3456
	s_waitcnt lgkmcnt(0)
	global_store_dwordx4 v[86:87], v[116:119], off offset:128 sc1
	v_lshl_add_u64 v[86:87], v[86:87], 0, s[6:7]
	global_store_dwordx4 v[86:87], v[120:123], off offset:128 sc1
	v_lshl_add_u64 v[86:87], v[86:87], 0, s[6:7]
	global_store_dwordx4 v[86:87], v[124:127], off offset:128 sc1
	v_lshl_add_u64 v[86:87], v[86:87], 0, s[6:7]
	global_store_dwordx4 v[86:87], v[128:131], off offset:128 sc1
	v_lshl_add_u64 v[86:87], v[86:87], 0, s[6:7]
	ds_read_b128 v[116:119], v3 offset:4608
	ds_read_b128 v[120:123], v3 offset:5760
	ds_read_b128 v[124:127], v3 offset:6912
	ds_read_b128 v[128:131], v3 offset:8064
	s_waitcnt lgkmcnt(0)
	global_store_dwordx4 v[86:87], v[116:119], off offset:128 sc1
	v_lshl_add_u64 v[86:87], v[86:87], 0, s[6:7]
	global_store_dwordx4 v[86:87], v[120:123], off offset:128 sc1
	v_lshl_add_u64 v[86:87], v[86:87], 0, s[6:7]
	global_store_dwordx4 v[86:87], v[124:127], off offset:128 sc1
	v_lshl_add_u64 v[86:87], v[86:87], 0, s[6:7]
	global_store_dwordx4 v[86:87], v[128:131], off offset:128 sc1
	v_lshl_add_u64 v[86:87], v[86:87], 0, s[6:7]
	s_waitcnt vmcnt(40)
; __device__ __forceinline__ void convert_item(const float* __restrict__ src, int Ksz, int Nsz, u16* __restrict__ dst, int kb, int nb,
;                                              int mode, const int tid) {
;     ...
;     const float* sp = src + (size_t)(kb * 64) * Nsz + n;
;     float v[64];
; #pragma unroll
;     for (int j = 0; j < 64; ++j) v[j] = sp[(size_t)j * Nsz];
;     int nd = n;
;     if (mode == 1) {
;       int isg = n >= 1024, c = n & 1023;
;       nd = (c >> 7) * 256 + isg * 128 + (c & 127);
;     }
;     u32x4* d = reinterpret_cast<u32x4*>(dst + (size_t)nd * Ksz + kb * 64);
; #pragma unroll
;     for (int q = 0; q < 8; ++q) {
;       u32x4 o;
;       o.x = pack2(v[q * 8 + 0], v[q * 8 + 1]);
;       o.y = pack2(v[q * 8 + 2], v[q * 8 + 3]);
;       o.z = pack2(v[q * 8 + 4], v[q * 8 + 5]);
;       o.w = pack2(v[q * 8 + 6], v[q * 8 + 7]);
;       d[q] = o;
;     }
	v_cvt_pk_bf16_f32 v68, v4, v5
	v_cvt_pk_bf16_f32 v69, v6, v7
	v_cvt_pk_bf16_f32 v70, v8, v9
	v_cvt_pk_bf16_f32 v71, v10, v11
	v_cvt_pk_bf16_f32 v72, v12, v13
	v_cvt_pk_bf16_f32 v73, v14, v15
	v_cvt_pk_bf16_f32 v74, v16, v17
	v_cvt_pk_bf16_f32 v75, v18, v19
	v_cvt_pk_bf16_f32 v76, v20, v21
	v_cvt_pk_bf16_f32 v77, v22, v23
	v_cvt_pk_bf16_f32 v78, v24, v25
	v_cvt_pk_bf16_f32 v79, v26, v27
	v_cvt_pk_bf16_f32 v80, v28, v29
	v_cvt_pk_bf16_f32 v81, v30, v31
	v_cvt_pk_bf16_f32 v82, v32, v33
	v_cvt_pk_bf16_f32 v83, v34, v35
	ds_write_b128 v2, v[68:71] offset:0
	ds_write_b128 v2, v[72:75] offset:16
	ds_write_b128 v2, v[76:79] offset:32
	ds_write_b128 v2, v[80:83] offset:48
	global_load_dword v4, v1, s[8:9]
	s_add_u32 s8, s8, s10
	s_addc_u32 s9, s9, 0
	global_load_dword v5, v1, s[8:9]
	s_add_u32 s8, s8, s10
	s_addc_u32 s9, s9, 0
	global_load_dword v6, v1, s[8:9]
	s_add_u32 s8, s8, s10
	s_addc_u32 s9, s9, 0
	global_load_dword v7, v1, s[8:9]
	s_add_u32 s8, s8, s10
	s_addc_u32 s9, s9, 0
	global_load_dword v8, v1, s[8:9]
	s_add_u32 s8, s8, s10
	s_addc_u32 s9, s9, 0
	global_load_dword v9, v1, s[8:9]
	s_add_u32 s8, s8, s10
	s_addc_u32 s9, s9, 0
	global_load_dword v10, v1, s[8:9]
	s_add_u32 s8, s8, s10
	s_addc_u32 s9, s9, 0
	global_load_dword v11, v1, s[8:9]
	s_add_u32 s8, s8, s10
	s_addc_u32 s9, s9, 0
	global_load_dword v12, v1, s[8:9]
	s_add_u32 s8, s8, s10
	s_addc_u32 s9, s9, 0
	global_load_dword v13, v1, s[8:9]
	s_add_u32 s8, s8, s10
	s_addc_u32 s9, s9, 0
	global_load_dword v14, v1, s[8:9]
	s_add_u32 s8, s8, s10
	s_addc_u32 s9, s9, 0
	global_load_dword v15, v1, s[8:9]
	s_add_u32 s8, s8, s10
	s_addc_u32 s9, s9, 0
	global_load_dword v16, v1, s[8:9]
	s_add_u32 s8, s8, s10
	s_addc_u32 s9, s9, 0
	global_load_dword v17, v1, s[8:9]
	s_add_u32 s8, s8, s10
	s_addc_u32 s9, s9, 0
	global_load_dword v18, v1, s[8:9]
	s_add_u32 s8, s8, s10
	s_addc_u32 s9, s9, 0
	global_load_dword v19, v1, s[8:9]
	s_add_u32 s8, s8, s10
	s_addc_u32 s9, s9, 0
	global_load_dword v20, v1, s[8:9]
	s_add_u32 s8, s8, s10
	s_addc_u32 s9, s9, 0
	global_load_dword v21, v1, s[8:9]
	s_add_u32 s8, s8, s10
	s_addc_u32 s9, s9, 0
	global_load_dword v22, v1, s[8:9]
	s_add_u32 s8, s8, s10
	s_addc_u32 s9, s9, 0
	global_load_dword v23, v1, s[8:9]
	s_add_u32 s8, s8, s10
	s_addc_u32 s9, s9, 0
	global_load_dword v24, v1, s[8:9]
	s_add_u32 s8, s8, s10
	s_addc_u32 s9, s9, 0
	global_load_dword v25, v1, s[8:9]
	s_add_u32 s8, s8, s10
	s_addc_u32 s9, s9, 0
	global_load_dword v26, v1, s[8:9]
	s_add_u32 s8, s8, s10
	s_addc_u32 s9, s9, 0
	global_load_dword v27, v1, s[8:9]
	s_add_u32 s8, s8, s10
	s_addc_u32 s9, s9, 0
	global_load_dword v28, v1, s[8:9]
	s_add_u32 s8, s8, s10
	s_addc_u32 s9, s9, 0
	global_load_dword v29, v1, s[8:9]
	s_add_u32 s8, s8, s10
	s_addc_u32 s9, s9, 0
	global_load_dword v30, v1, s[8:9]
	s_add_u32 s8, s8, s10
	s_addc_u32 s9, s9, 0
	global_load_dword v31, v1, s[8:9]
	s_add_u32 s8, s8, s10
	s_addc_u32 s9, s9, 0
	global_load_dword v32, v1, s[8:9]
	s_add_u32 s8, s8, s10
	s_addc_u32 s9, s9, 0
	global_load_dword v33, v1, s[8:9]
	s_add_u32 s8, s8, s10
	s_addc_u32 s9, s9, 0
	global_load_dword v34, v1, s[8:9]
	s_add_u32 s8, s8, s10
	s_addc_u32 s9, s9, 0
	global_load_dword v35, v1, s[8:9]
	s_add_u32 s8, s8, s10
	s_addc_u32 s9, s9, 0
	s_waitcnt vmcnt(40)
	v_cvt_pk_bf16_f32 v100, v36, v37
	v_cvt_pk_bf16_f32 v101, v38, v39
	v_cvt_pk_bf16_f32 v102, v40, v41
	v_cvt_pk_bf16_f32 v103, v42, v43
	v_cvt_pk_bf16_f32 v104, v44, v45
	v_cvt_pk_bf16_f32 v105, v46, v47
	v_cvt_pk_bf16_f32 v106, v48, v49
	v_cvt_pk_bf16_f32 v107, v50, v51
	v_cvt_pk_bf16_f32 v108, v52, v53
	v_cvt_pk_bf16_f32 v109, v54, v55
	v_cvt_pk_bf16_f32 v110, v56, v57
	v_cvt_pk_bf16_f32 v111, v58, v59
	v_cvt_pk_bf16_f32 v112, v60, v61
	v_cvt_pk_bf16_f32 v113, v62, v63
	v_cvt_pk_bf16_f32 v114, v64, v65
	v_cvt_pk_bf16_f32 v115, v66, v67
	ds_write_b128 v2, v[100:103] offset:64
	ds_write_b128 v2, v[104:107] offset:80
	ds_write_b128 v2, v[108:111] offset:96
	ds_write_b128 v2, v[112:115] offset:112
	global_load_dword v36, v1, s[8:9]
	s_add_u32 s8, s8, s10
	s_addc_u32 s9, s9, 0
	global_load_dword v37, v1, s[8:9]
	s_add_u32 s8, s8, s10
	s_addc_u32 s9, s9, 0
	global_load_dword v38, v1, s[8:9]
	s_add_u32 s8, s8, s10
	s_addc_u32 s9, s9, 0
	global_load_dword v39, v1, s[8:9]
	s_add_u32 s8, s8, s10
	s_addc_u32 s9, s9, 0
	global_load_dword v40, v1, s[8:9]
	s_add_u32 s8, s8, s10
	s_addc_u32 s9, s9, 0
	global_load_dword v41, v1, s[8:9]
	s_add_u32 s8, s8, s10
	s_addc_u32 s9, s9, 0
	global_load_dword v42, v1, s[8:9]
	s_add_u32 s8, s8, s10
	s_addc_u32 s9, s9, 0
	global_load_dword v43, v1, s[8:9]
	s_add_u32 s8, s8, s10
	s_addc_u32 s9, s9, 0
	global_load_dword v44, v1, s[8:9]
	s_add_u32 s8, s8, s10
	s_addc_u32 s9, s9, 0
	global_load_dword v45, v1, s[8:9]
	s_add_u32 s8, s8, s10
	s_addc_u32 s9, s9, 0
	global_load_dword v46, v1, s[8:9]
	s_add_u32 s8, s8, s10
	s_addc_u32 s9, s9, 0
	global_load_dword v47, v1, s[8:9]
	s_add_u32 s8, s8, s10
	s_addc_u32 s9, s9, 0
	global_load_dword v48, v1, s[8:9]
	s_add_u32 s8, s8, s10
	s_addc_u32 s9, s9, 0
	global_load_dword v49, v1, s[8:9]
	s_add_u32 s8, s8, s10
	s_addc_u32 s9, s9, 0
	global_load_dword v50, v1, s[8:9]
	s_add_u32 s8, s8, s10
	s_addc_u32 s9, s9, 0
	global_load_dword v51, v1, s[8:9]
	s_add_u32 s8, s8, s10
	s_addc_u32 s9, s9, 0
	global_load_dword v52, v1, s[8:9]
	s_add_u32 s8, s8, s10
	s_addc_u32 s9, s9, 0
	global_load_dword v53, v1, s[8:9]
	s_add_u32 s8, s8, s10
	s_addc_u32 s9, s9, 0
	global_load_dword v54, v1, s[8:9]
	s_add_u32 s8, s8, s10
	s_addc_u32 s9, s9, 0
	global_load_dword v55, v1, s[8:9]
	s_add_u32 s8, s8, s10
	s_addc_u32 s9, s9, 0
	global_load_dword v56, v1, s[8:9]
	s_add_u32 s8, s8, s10
	s_addc_u32 s9, s9, 0
	global_load_dword v57, v1, s[8:9]
	s_add_u32 s8, s8, s10
	s_addc_u32 s9, s9, 0
	global_load_dword v58, v1, s[8:9]
	s_add_u32 s8, s8, s10
	s_addc_u32 s9, s9, 0
	global_load_dword v59, v1, s[8:9]
	s_add_u32 s8, s8, s10
	s_addc_u32 s9, s9, 0
	global_load_dword v60, v1, s[8:9]
	s_add_u32 s8, s8, s10
	s_addc_u32 s9, s9, 0
	global_load_dword v61, v1, s[8:9]
	s_add_u32 s8, s8, s10
	s_addc_u32 s9, s9, 0
	global_load_dword v62, v1, s[8:9]
	s_add_u32 s8, s8, s10
	s_addc_u32 s9, s9, 0
	global_load_dword v63, v1, s[8:9]
	s_add_u32 s8, s8, s10
	s_addc_u32 s9, s9, 0
	global_load_dword v64, v1, s[8:9]
	s_add_u32 s8, s8, s10
	s_addc_u32 s9, s9, 0
	global_load_dword v65, v1, s[8:9]
	s_add_u32 s8, s8, s10
	s_addc_u32 s9, s9, 0
	global_load_dword v66, v1, s[8:9]
	s_add_u32 s8, s8, s10
	s_addc_u32 s9, s9, 0
	global_load_dword v67, v1, s[8:9]
	s_add_u32 s8, s8, s10
	s_addc_u32 s9, s9, 0
	v_mov_b32_e32 v86, v84
	v_mov_b32_e32 v87, v85
	ds_read_b128 v[116:119], v3 offset:0
	ds_read_b128 v[120:123], v3 offset:1152
	ds_read_b128 v[124:127], v3 offset:2304
	ds_read_b128 v[128:131], v3 offset:3456
	s_waitcnt lgkmcnt(0)
; __device__ __forceinline__ void convert_item(const float* __restrict__ src, int Ksz, int Nsz, u16* __restrict__ dst, int kb, int nb,
;                                              int mode, const int tid) {
;     ...
;     u32x4* d = reinterpret_cast<u32x4*>(dst + (size_t)nd * Ksz + kb * 64);
; #pragma unroll
;     for (int q = 0; q < 8; ++q) {
;       u32x4 o;
;       o.x = pack2(v[q * 8 + 0], v[q * 8 + 1]);
;       o.y = pack2(v[q * 8 + 2], v[q * 8 + 3]);
;       o.z = pack2(v[q * 8 + 4], v[q * 8 + 5]);
;       o.w = pack2(v[q * 8 + 6], v[q * 8 + 7]);
;       d[q] = o;
;     }
	global_store_dwordx4 v[86:87], v[116:119], off offset:256 sc1
	v_lshl_add_u64 v[86:87], v[86:87], 0, s[6:7]
	global_store_dwordx4 v[86:87], v[120:123], off offset:256 sc1
	v_lshl_add_u64 v[86:87], v[86:87], 0, s[6:7]
	global_store_dwordx4 v[86:87], v[124:127], off offset:256 sc1
	v_lshl_add_u64 v[86:87], v[86:87], 0, s[6:7]
	global_store_dwordx4 v[86:87], v[128:131], off offset:256 sc1
	v_lshl_add_u64 v[86:87], v[86:87], 0, s[6:7]
	ds_read_b128 v[116:119], v3 offset:4608
	ds_read_b128 v[120:123], v3 offset:5760
	ds_read_b128 v[124:127], v3 offset:6912
	ds_read_b128 v[128:131], v3 offset:8064
	s_waitcnt lgkmcnt(0)
	global_store_dwordx4 v[86:87], v[116:119], off offset:256 sc1
	v_lshl_add_u64 v[86:87], v[86:87], 0, s[6:7]
	global_store_dwordx4 v[86:87], v[120:123], off offset:256 sc1
	v_lshl_add_u64 v[86:87], v[86:87], 0, s[6:7]
	global_store_dwordx4 v[86:87], v[124:127], off offset:256 sc1
	v_lshl_add_u64 v[86:87], v[86:87], 0, s[6:7]
	global_store_dwordx4 v[86:87], v[128:131], off offset:256 sc1
	v_lshl_add_u64 v[86:87], v[86:87], 0, s[6:7]
	s_waitcnt vmcnt(40)
	v_cvt_pk_bf16_f32 v68, v4, v5
	v_cvt_pk_bf16_f32 v69, v6, v7
	v_cvt_pk_bf16_f32 v70, v8, v9
	v_cvt_pk_bf16_f32 v71, v10, v11
	v_cvt_pk_bf16_f32 v72, v12, v13
	v_cvt_pk_bf16_f32 v73, v14, v15
	v_cvt_pk_bf16_f32 v74, v16, v17
	v_cvt_pk_bf16_f32 v75, v18, v19
	v_cvt_pk_bf16_f32 v76, v20, v21
	v_cvt_pk_bf16_f32 v77, v22, v23
	v_cvt_pk_bf16_f32 v78, v24, v25
	v_cvt_pk_bf16_f32 v79, v26, v27
	v_cvt_pk_bf16_f32 v80, v28, v29
	v_cvt_pk_bf16_f32 v81, v30, v31
	v_cvt_pk_bf16_f32 v82, v32, v33
	v_cvt_pk_bf16_f32 v83, v34, v35
	ds_write_b128 v2, v[68:71] offset:0
	ds_write_b128 v2, v[72:75] offset:16
	ds_write_b128 v2, v[76:79] offset:32
	ds_write_b128 v2, v[80:83] offset:48
	s_waitcnt vmcnt(8)
	v_cvt_pk_bf16_f32 v100, v36, v37
	v_cvt_pk_bf16_f32 v101, v38, v39
	v_cvt_pk_bf16_f32 v102, v40, v41
	v_cvt_pk_bf16_f32 v103, v42, v43
	v_cvt_pk_bf16_f32 v104, v44, v45
	v_cvt_pk_bf16_f32 v105, v46, v47
	v_cvt_pk_bf16_f32 v106, v48, v49
	v_cvt_pk_bf16_f32 v107, v50, v51
	v_cvt_pk_bf16_f32 v108, v52, v53
	v_cvt_pk_bf16_f32 v109, v54, v55
	v_cvt_pk_bf16_f32 v110, v56, v57
	v_cvt_pk_bf16_f32 v111, v58, v59
	v_cvt_pk_bf16_f32 v112, v60, v61
	v_cvt_pk_bf16_f32 v113, v62, v63
	v_cvt_pk_bf16_f32 v114, v64, v65
	v_cvt_pk_bf16_f32 v115, v66, v67
	ds_write_b128 v2, v[100:103] offset:64
	ds_write_b128 v2, v[104:107] offset:80
	ds_write_b128 v2, v[108:111] offset:96
	ds_write_b128 v2, v[112:115] offset:112
	v_mov_b32_e32 v86, v84
	v_mov_b32_e32 v87, v85
	ds_read_b128 v[116:119], v3 offset:0
	ds_read_b128 v[120:123], v3 offset:1152
	ds_read_b128 v[124:127], v3 offset:2304
	ds_read_b128 v[128:131], v3 offset:3456
	s_waitcnt lgkmcnt(0)
	global_store_dwordx4 v[86:87], v[116:119], off offset:384 sc1
	v_lshl_add_u64 v[86:87], v[86:87], 0, s[6:7]
	global_store_dwordx4 v[86:87], v[120:123], off offset:384 sc1
	v_lshl_add_u64 v[86:87], v[86:87], 0, s[6:7]
	global_store_dwordx4 v[86:87], v[124:127], off offset:384 sc1
	v_lshl_add_u64 v[86:87], v[86:87], 0, s[6:7]
	global_store_dwordx4 v[86:87], v[128:131], off offset:384 sc1
	v_lshl_add_u64 v[86:87], v[86:87], 0, s[6:7]
	ds_read_b128 v[116:119], v3 offset:4608
	ds_read_b128 v[120:123], v3 offset:5760
	ds_read_b128 v[124:127], v3 offset:6912
	ds_read_b128 v[128:131], v3 offset:8064
	s_waitcnt lgkmcnt(0)
	global_store_dwordx4 v[86:87], v[116:119], off offset:384 sc1
	v_lshl_add_u64 v[86:87], v[86:87], 0, s[6:7]
	global_store_dwordx4 v[86:87], v[120:123], off offset:384 sc1
	v_lshl_add_u64 v[86:87], v[86:87], 0, s[6:7]
	global_store_dwordx4 v[86:87], v[124:127], off offset:384 sc1
	v_lshl_add_u64 v[86:87], v[86:87], 0, s[6:7]
	global_store_dwordx4 v[86:87], v[128:131], off offset:384 sc1
	v_lshl_add_u64 v[86:87], v[86:87], 0, s[6:7]

; #define SCHED __builtin_amdgcn_sched_barrier(0)
; __device__ __forceinline__ void rmsnorm_rows(const float* __restrict__ xin, const float* __restrict__ g, u16* outb, float* outf,
;                                              int row_begin, int row_end, int row_step, const int tidx) {
;     ...
;   for (int row = row_begin; row < row_end; row += row_step) {
;     const float* xr = xin + (size_t)row * DM;
;     f32x4 v[16];
;     float ss = 0.f;
; #pragma unroll
;     for (int i = 0; i < 16; ++i) {
;       v[i] = *reinterpret_cast<const f32x4*>(xr + i * 256 + lane * 4);
;     }
;     SCHED;
; #pragma unroll
;     for (int i = 0; i < 16; ++i) ss += v[i][0] * v[i][0] + v[i][1] * v[i][1] + v[i][2] * v[i][2] + v[i][3] * v[i][3];
;     ss = wave_sum(ss);
;     float rs = rsqrtf(ss * (1.f / DM) + 1e-6f);
.LBB0_224:
	v_lshl_add_u64 v[64:65], v[132:133], 0, v[162:163]
	v_add_co_u32_e32 v66, vcc, 0x37900000, v64
	s_nop 1
	v_addc_co_u32_e32 v67, vcc, 0, v65, vcc
	global_load_dwordx4 v[126:129], v[66:67], off
	global_load_dwordx4 v[122:125], v[66:67], off offset:1024
	global_load_dwordx4 v[118:121], v[66:67], off offset:2048
	global_load_dwordx4 v[110:113], v[66:67], off offset:3072
	v_add_co_u32_e32 v66, vcc, 0x37901000, v64
	s_nop 1
	v_addc_co_u32_e32 v67, vcc, 0, v65, vcc
	global_load_dwordx4 v[114:117], v[66:67], off
	global_load_dwordx4 v[106:109], v[66:67], off offset:1024
	global_load_dwordx4 v[102:105], v[66:67], off offset:2048
	global_load_dwordx4 v[92:95], v[66:67], off offset:3072
	v_add_co_u32_e32 v66, vcc, 0x37902000, v64
	s_nop 1
	v_addc_co_u32_e32 v67, vcc, 0, v65, vcc
	v_add_co_u32_e32 v64, vcc, 0x37903000, v64
	global_load_dwordx4 v[98:101], v[66:67], off
	global_load_dwordx4 v[88:91], v[66:67], off offset:1024
	global_load_dwordx4 v[84:87], v[66:67], off offset:2048
	global_load_dwordx4 v[76:79], v[66:67], off offset:3072
	v_addc_co_u32_e32 v65, vcc, 0, v65, vcc
	global_load_dwordx4 v[80:83], v[64:65], off
	global_load_dwordx4 v[72:75], v[64:65], off offset:1024
	global_load_dwordx4 v[68:71], v[64:65], off offset:2048
	s_nop 0
	global_load_dwordx4 v[64:67], v[64:65], off offset:3072
	s_waitcnt vmcnt(0)
	v_mul_f32_e32 v131, v127, v127
	s_waitcnt vmcnt(14)
	v_mul_f32_e32 v141, v123, v123
	v_fmac_f32_e32 v131, v126, v126
	v_fmac_f32_e32 v141, v122, v122
	v_fmac_f32_e32 v131, v128, v128
	v_fmac_f32_e32 v141, v124, v124
	v_fmac_f32_e32 v131, v129, v129
	v_fmac_f32_e32 v141, v125, v125
	v_add_f32_e32 v131, v131, v141
	s_waitcnt vmcnt(13)
	v_mul_f32_e32 v141, v119, v119
	v_fmac_f32_e32 v141, v118, v118
	v_fmac_f32_e32 v141, v120, v120
	v_fmac_f32_e32 v141, v121, v121
	v_add_f32_e32 v131, v131, v141
	s_waitcnt vmcnt(12)
	v_mul_f32_e32 v141, v111, v111
	v_fmac_f32_e32 v141, v110, v110
	v_fmac_f32_e32 v141, v112, v112
	v_fmac_f32_e32 v141, v113, v113
	v_add_f32_e32 v131, v131, v141
	s_waitcnt vmcnt(11)
	v_mul_f32_e32 v141, v115, v115
	v_fmac_f32_e32 v141, v114, v114
	v_fmac_f32_e32 v141, v116, v116
	v_fmac_f32_e32 v141, v117, v117
	v_add_f32_e32 v131, v131, v141
	s_waitcnt vmcnt(10)
	v_mul_f32_e32 v141, v107, v107
	v_fmac_f32_e32 v141, v106, v106
	v_fmac_f32_e32 v141, v108, v108
	v_fmac_f32_e32 v141, v109, v109
	v_add_f32_e32 v131, v131, v141
	s_waitcnt vmcnt(9)
	v_mul_f32_e32 v141, v103, v103
	v_fmac_f32_e32 v141, v102, v102
	v_fmac_f32_e32 v141, v104, v104
	v_fmac_f32_e32 v141, v105, v105
	v_add_f32_e32 v131, v131, v141
	s_waitcnt vmcnt(8)
	v_mul_f32_e32 v141, v93, v93
	v_fmac_f32_e32 v141, v92, v92
	v_fmac_f32_e32 v141, v94, v94
	v_fmac_f32_e32 v141, v95, v95
	v_add_f32_e32 v131, v131, v141
	s_waitcnt vmcnt(7)
	v_mul_f32_e32 v141, v99, v99
	v_fmac_f32_e32 v141, v98, v98
	v_fmac_f32_e32 v141, v100, v100
	v_fmac_f32_e32 v141, v101, v101
	v_add_f32_e32 v131, v131, v141
	s_waitcnt vmcnt(6)
	v_mul_f32_e32 v141, v89, v89
	v_fmac_f32_e32 v141, v88, v88
	v_fmac_f32_e32 v141, v90, v90
	v_fmac_f32_e32 v141, v91, v91
	v_add_f32_e32 v131, v131, v141
	s_waitcnt vmcnt(5)
	v_mul_f32_e32 v141, v85, v85
	v_fmac_f32_e32 v141, v84, v84
	v_fmac_f32_e32 v141, v86, v86
	v_fmac_f32_e32 v141, v87, v87
	v_add_f32_e32 v131, v131, v141
	s_waitcnt vmcnt(4)
	v_mul_f32_e32 v141, v77, v77
	s_waitcnt vmcnt(3)
	v_mov_b32_e32 v144, v81
	s_waitcnt vmcnt(2)
	v_mov_b32_e32 v145, v73
	v_fmac_f32_e32 v141, v76, v76
	v_mov_b32_e32 v142, v80
	v_mov_b32_e32 v143, v72
	v_pk_mul_f32 v[144:145], v[144:145], v[144:145]
	v_fmac_f32_e32 v141, v78, v78
	v_pk_fma_f32 v[142:143], v[142:143], v[142:143], v[144:145]
	v_mov_b32_e32 v144, v82
	v_mov_b32_e32 v145, v74
	v_fmac_f32_e32 v141, v79, v79
	v_pk_fma_f32 v[142:143], v[144:145], v[144:145], v[142:143]
	v_mov_b32_e32 v144, v83
	v_mov_b32_e32 v145, v75
	v_add_f32_e32 v131, v131, v141
	v_pk_fma_f32 v[142:143], v[144:145], v[144:145], v[142:143]
	s_waitcnt vmcnt(1)
	v_mov_b32_e32 v144, v69
	v_add_f32_e32 v131, v131, v142
	s_waitcnt vmcnt(0)
	v_mov_b32_e32 v145, v65
	v_add_f32_e32 v131, v131, v143
	v_mov_b32_e32 v142, v68
	v_mov_b32_e32 v143, v64
	v_pk_mul_f32 v[144:145], v[144:145], v[144:145]
	v_add_u32_e32 v130, s8, v130
	v_pk_fma_f32 v[142:143], v[142:143], v[142:143], v[144:145]
	v_mov_b32_e32 v144, v70
	v_mov_b32_e32 v145, v66
	v_pk_fma_f32 v[142:143], v[144:145], v[144:145], v[142:143]
	v_mov_b32_e32 v144, v71
	v_mov_b32_e32 v145, v67
	v_pk_fma_f32 v[142:143], v[144:145], v[144:145], v[142:143]
	v_lshl_add_u64 v[144:145], v[134:135], 0, v[162:163]
	v_add_f32_e32 v131, v131, v142
	v_add_f32_e32 v131, v131, v143
	ds_bpermute_b32 v141, v97, v131
	v_lshl_add_u64 v[132:133], v[132:133], 0, s[10:11]
	v_lshl_add_u64 v[134:135], v[134:135], 0, s[10:11]
	s_waitcnt lgkmcnt(0)
	v_add_f32_e32 v131, v131, v141
	ds_bpermute_b32 v141, v136, v131
	s_waitcnt lgkmcnt(0)
	v_add_f32_e32 v131, v131, v141
	ds_bpermute_b32 v141, v137, v131
	s_waitcnt lgkmcnt(0)
	v_add_f32_e32 v131, v131, v141
	ds_bpermute_b32 v141, v138, v131
	s_waitcnt lgkmcnt(0)
	v_add_f32_e32 v131, v131, v141
	ds_bpermute_b32 v141, v139, v131
	s_waitcnt lgkmcnt(0)
	v_add_f32_e32 v131, v131, v141
	ds_bpermute_b32 v141, v140, v131
	s_waitcnt lgkmcnt(0)
; __device__ __forceinline__ void rmsnorm_rows(const float* __restrict__ xin, const float* __restrict__ g, u16* outb, float* outf,
;                                              int row_begin, int row_end, int row_step, const int tidx) {
;     ...
;     ss = wave_sum(ss);
;     float rs = rsqrtf(ss * (1.f / DM) + 1e-6f);
; #pragma unroll
;     for (int i = 0; i < 16; ++i) {
;       f32x4 o = v[i] * rs * ggv[i];
;       if (outb) {
;         u32x2 pk;
;         pk.x = pack2(o[0], o[1]);
;         pk.y = pack2(o[2], o[3]);
;         *reinterpret_cast<u32x2*>(outb + (size_t)row * DM + i * 256 + lane * 4) = pk;
;       } else {
;         *reinterpret_cast<f32x4*>(outf + (size_t)row * DM + i * 256 + lane * 4) = o;
;       }
;     }
	v_add_f32_e32 v131, v131, v141
	v_fmamk_f32 v131, v131, 0x39800000, v211
	v_cmp_gt_f32_e32 vcc, s1, v131
	v_mul_f32_e32 v141, 0x4b800000, v131
	s_nop 0
	v_cndmask_b32_e32 v131, v131, v141, vcc
	v_rsq_f32_e32 v131, v131
	s_nop 0
	v_mul_f32_e32 v141, 0x45800000, v131
	v_cndmask_b32_e32 v142, v131, v141, vcc
	v_pk_mul_f32 v[110:111], v[110:111], v[142:143] op_sel_hi:[1,0]
	v_pk_mul_f32 v[112:113], v[112:113], v[142:143] op_sel_hi:[1,0]
	v_pk_mul_f32 v[110:111], v[12:13], v[110:111]
	v_pk_mul_f32 v[112:113], v[14:15], v[112:113]
	global_store_dwordx4 v[144:145], v[110:113], off offset:3072 sc1
	v_pk_mul_f32 v[76:77], v[76:77], v[142:143] op_sel_hi:[1,0]
	v_pk_mul_f32 v[78:79], v[78:79], v[142:143] op_sel_hi:[1,0]
	v_pk_mul_f32 v[110:111], v[114:115], v[142:143] op_sel_hi:[1,0]
	v_add_co_u32_e32 v114, vcc, s56, v144
	v_pk_mul_f32 v[112:113], v[116:117], v[142:143] op_sel_hi:[1,0]
	s_nop 0
	v_addc_co_u32_e32 v115, vcc, 0, v145, vcc
	v_add_co_u32_e32 v116, vcc, s51, v144
	v_pk_mul_f32 v[78:79], v[46:47], v[78:79]
	s_nop 0
	v_addc_co_u32_e32 v117, vcc, 0, v145, vcc
	v_pk_mul_f32 v[76:77], v[44:45], v[76:77]
	v_pk_mul_f32 v[92:93], v[92:93], v[142:143] op_sel_hi:[1,0]
	v_pk_mul_f32 v[94:95], v[94:95], v[142:143] op_sel_hi:[1,0]
	global_store_dwordx4 v[116:117], v[76:79], off offset:3072 sc1
	v_pk_mul_f32 v[94:95], v[30:31], v[94:95]
	v_pk_mul_f32 v[92:93], v[28:29], v[92:93]
	v_pk_mul_f32 v[76:77], v[80:81], v[142:143] op_sel_hi:[1,0]
	v_add_co_u32_e32 v80, vcc, s14, v144
	v_pk_mul_f32 v[126:127], v[126:127], v[142:143] op_sel_hi:[1,0]
	s_nop 0
	v_addc_co_u32_e32 v81, vcc, 0, v145, vcc
	v_pk_mul_f32 v[128:129], v[128:129], v[142:143] op_sel_hi:[1,0]
	v_pk_mul_f32 v[122:123], v[122:123], v[142:143] op_sel_hi:[1,0]
	v_pk_mul_f32 v[124:125], v[124:125], v[142:143] op_sel_hi:[1,0]
	v_pk_mul_f32 v[118:119], v[118:119], v[142:143] op_sel_hi:[1,0]
	v_pk_mul_f32 v[120:121], v[120:121], v[142:143] op_sel_hi:[1,0]
	v_pk_mul_f32 v[106:107], v[106:107], v[142:143] op_sel_hi:[1,0]
	v_pk_mul_f32 v[108:109], v[108:109], v[142:143] op_sel_hi:[1,0]
	v_pk_mul_f32 v[102:103], v[102:103], v[142:143] op_sel_hi:[1,0]
	v_pk_mul_f32 v[104:105], v[104:105], v[142:143] op_sel_hi:[1,0]
	global_store_dwordx4 v[114:115], v[92:95], off offset:3072 sc1
	v_pk_mul_f32 v[88:89], v[88:89], v[142:143] op_sel_hi:[1,0]
	v_pk_mul_f32 v[90:91], v[90:91], v[142:143] op_sel_hi:[1,0]
	v_pk_mul_f32 v[92:93], v[98:99], v[142:143] op_sel_hi:[1,0]
	v_pk_mul_f32 v[94:95], v[100:101], v[142:143] op_sel_hi:[1,0]
	v_pk_mul_f32 v[84:85], v[84:85], v[142:143] op_sel_hi:[1,0]
	v_pk_mul_f32 v[86:87], v[86:87], v[142:143] op_sel_hi:[1,0]
	v_pk_mul_f32 v[78:79], v[82:83], v[142:143] op_sel_hi:[1,0]
	v_pk_mul_f32 v[72:73], v[72:73], v[142:143] op_sel_hi:[1,0]
	v_pk_mul_f32 v[74:75], v[74:75], v[142:143] op_sel_hi:[1,0]
	v_pk_mul_f32 v[68:69], v[68:69], v[142:143] op_sel_hi:[1,0]
	v_pk_mul_f32 v[70:71], v[70:71], v[142:143] op_sel_hi:[1,0]
	v_pk_mul_f32 v[64:65], v[64:65], v[142:143] op_sel_hi:[1,0]
	v_pk_mul_f32 v[66:67], v[66:67], v[142:143] op_sel_hi:[1,0]
	v_cmp_lt_i32_e32 vcc, s16, v130
	v_pk_mul_f32 v[128:129], v[2:3], v[128:129]
	v_pk_mul_f32 v[126:127], v[0:1], v[126:127]
	v_pk_mul_f32 v[124:125], v[6:7], v[124:125]
	v_pk_mul_f32 v[122:123], v[4:5], v[122:123]
	v_pk_mul_f32 v[120:121], v[10:11], v[120:121]
	v_pk_mul_f32 v[118:119], v[8:9], v[118:119]
	v_pk_mul_f32 v[112:113], v[18:19], v[112:113]
	v_pk_mul_f32 v[110:111], v[16:17], v[110:111]
	v_pk_mul_f32 v[108:109], v[22:23], v[108:109]
	v_pk_mul_f32 v[106:107], v[20:21], v[106:107]
	v_pk_mul_f32 v[104:105], v[26:27], v[104:105]
	v_pk_mul_f32 v[102:103], v[24:25], v[102:103]
	v_pk_mul_f32 v[94:95], v[34:35], v[94:95]
	v_pk_mul_f32 v[92:93], v[32:33], v[92:93]
	v_pk_mul_f32 v[90:91], v[38:39], v[90:91]
	v_pk_mul_f32 v[88:89], v[36:37], v[88:89]
	v_pk_mul_f32 v[86:87], v[42:43], v[86:87]
	v_pk_mul_f32 v[84:85], v[40:41], v[84:85]
	v_pk_mul_f32 v[78:79], v[50:51], v[78:79]
	v_pk_mul_f32 v[76:77], v[48:49], v[76:77]
	v_pk_mul_f32 v[74:75], v[54:55], v[74:75]
	v_pk_mul_f32 v[72:73], v[52:53], v[72:73]
	v_pk_mul_f32 v[70:71], v[58:59], v[70:71]
	v_pk_mul_f32 v[68:69], v[56:57], v[68:69]
	v_pk_mul_f32 v[66:67], v[62:63], v[66:67]
	v_pk_mul_f32 v[64:65], v[60:61], v[64:65]
	s_or_b64 s[12:13], vcc, s[12:13]
	global_store_dwordx4 v[144:145], v[126:129], off sc1
	global_store_dwordx4 v[144:145], v[122:125], off offset:1024 sc1
	global_store_dwordx4 v[144:145], v[118:121], off offset:2048 sc1
	global_store_dwordx4 v[116:117], v[110:113], off offset:-4096 sc1
	global_store_dwordx4 v[114:115], v[106:109], off offset:1024 sc1
	global_store_dwordx4 v[114:115], v[102:105], off offset:2048 sc1
	global_store_dwordx4 v[116:117], v[92:95], off sc1
	global_store_dwordx4 v[116:117], v[88:91], off offset:1024 sc1
	global_store_dwordx4 v[116:117], v[84:87], off offset:2048 sc1
	global_store_dwordx4 v[80:81], v[76:79], off sc1
	global_store_dwordx4 v[80:81], v[72:75], off offset:1024 sc1
	global_store_dwordx4 v[80:81], v[68:71], off offset:2048 sc1
	global_store_dwordx4 v[80:81], v[64:67], off offset:3072 sc1
	s_andn2_b64 exec, exec, s[12:13]
	s_cbranch_execnz .LBB0_224

; #define SCHED __builtin_amdgcn_sched_barrier(0)
; __device__ __forceinline__ void rmsnorm_rows(const float* __restrict__ xin, const float* __restrict__ g, u16* outb, float* outf,
;                                              int row_begin, int row_end, int row_step, const int tidx) {
;     ...
;   for (int row = row_begin; row < row_end; row += row_step) {
;     const float* xr = xin + (size_t)row * DM;
;     f32x4 v[16];
;     float ss = 0.f;
; #pragma unroll
;     for (int i = 0; i < 16; ++i) {
;       v[i] = *reinterpret_cast<const f32x4*>(xr + i * 256 + lane * 4);
;     }
;     SCHED;
; #pragma unroll
;     for (int i = 0; i < 16; ++i) ss += v[i][0] * v[i][0] + v[i][1] * v[i][1] + v[i][2] * v[i][2] + v[i][3] * v[i][3];
;     ss = wave_sum(ss);
;     float rs = rsqrtf(ss * (1.f / DM) + 1e-6f);
.LBB0_229:
	v_lshl_add_u64 v[64:65], s[86:87], 0, v[132:133]
	v_add_co_u32_e32 v66, vcc, 0x2f900000, v64
	s_nop 1
	v_addc_co_u32_e32 v67, vcc, 0, v65, vcc
	global_load_dwordx4 v[126:129], v[66:67], off
	global_load_dwordx4 v[122:125], v[66:67], off offset:1024
	global_load_dwordx4 v[118:121], v[66:67], off offset:2048
	global_load_dwordx4 v[110:113], v[66:67], off offset:3072
	v_add_co_u32_e32 v66, vcc, 0x2f901000, v64
	s_nop 1
	v_addc_co_u32_e32 v67, vcc, 0, v65, vcc
	global_load_dwordx4 v[114:117], v[66:67], off
	global_load_dwordx4 v[106:109], v[66:67], off offset:1024
	global_load_dwordx4 v[102:105], v[66:67], off offset:2048
	global_load_dwordx4 v[92:95], v[66:67], off offset:3072
	v_add_co_u32_e32 v66, vcc, 0x2f902000, v64
	s_nop 1
	v_addc_co_u32_e32 v67, vcc, 0, v65, vcc
	v_add_co_u32_e32 v64, vcc, 0x2f903000, v64
	global_load_dwordx4 v[98:101], v[66:67], off
	global_load_dwordx4 v[88:91], v[66:67], off offset:1024
	global_load_dwordx4 v[84:87], v[66:67], off offset:2048
	global_load_dwordx4 v[76:79], v[66:67], off offset:3072
	v_addc_co_u32_e32 v65, vcc, 0, v65, vcc
	global_load_dwordx4 v[80:83], v[64:65], off
	global_load_dwordx4 v[72:75], v[64:65], off offset:1024
	global_load_dwordx4 v[68:71], v[64:65], off offset:2048
	s_nop 0
	global_load_dwordx4 v[64:67], v[64:65], off offset:3072
	s_waitcnt vmcnt(0)
	v_mul_f32_e32 v131, v127, v127
	s_waitcnt vmcnt(14)
	v_mul_f32_e32 v141, v123, v123
	v_fmac_f32_e32 v131, v126, v126
	v_fmac_f32_e32 v141, v122, v122
	v_fmac_f32_e32 v131, v128, v128
	v_fmac_f32_e32 v141, v124, v124
	v_fmac_f32_e32 v131, v129, v129
	v_fmac_f32_e32 v141, v125, v125
	v_add_f32_e32 v131, v131, v141
	s_waitcnt vmcnt(13)
	v_mul_f32_e32 v141, v119, v119
	v_fmac_f32_e32 v141, v118, v118
	v_fmac_f32_e32 v141, v120, v120
	v_fmac_f32_e32 v141, v121, v121
	v_add_f32_e32 v131, v131, v141
	s_waitcnt vmcnt(12)
	v_mul_f32_e32 v141, v111, v111
	v_fmac_f32_e32 v141, v110, v110
	v_fmac_f32_e32 v141, v112, v112
	v_fmac_f32_e32 v141, v113, v113
	v_add_f32_e32 v131, v131, v141
	s_waitcnt vmcnt(11)
	v_mul_f32_e32 v141, v115, v115
	v_fmac_f32_e32 v141, v114, v114
	v_fmac_f32_e32 v141, v116, v116
	v_fmac_f32_e32 v141, v117, v117
	v_add_f32_e32 v131, v131, v141
	s_waitcnt vmcnt(10)
	v_mul_f32_e32 v141, v107, v107
	v_fmac_f32_e32 v141, v106, v106
	v_fmac_f32_e32 v141, v108, v108
	v_fmac_f32_e32 v141, v109, v109
	v_add_f32_e32 v131, v131, v141
	s_waitcnt vmcnt(9)
	v_mul_f32_e32 v141, v103, v103
	v_fmac_f32_e32 v141, v102, v102
	v_fmac_f32_e32 v141, v104, v104
	v_fmac_f32_e32 v141, v105, v105
	v_add_f32_e32 v131, v131, v141
	s_waitcnt vmcnt(8)
	v_mul_f32_e32 v141, v93, v93
	v_fmac_f32_e32 v141, v92, v92
	v_fmac_f32_e32 v141, v94, v94
	v_fmac_f32_e32 v141, v95, v95
	v_add_f32_e32 v131, v131, v141
	s_waitcnt vmcnt(7)
	v_mul_f32_e32 v141, v99, v99
	v_fmac_f32_e32 v141, v98, v98
	v_fmac_f32_e32 v141, v100, v100
	v_fmac_f32_e32 v141, v101, v101
	v_add_f32_e32 v131, v131, v141
	s_waitcnt vmcnt(6)
	v_mul_f32_e32 v141, v89, v89
	v_fmac_f32_e32 v141, v88, v88
	v_fmac_f32_e32 v141, v90, v90
	v_fmac_f32_e32 v141, v91, v91
	v_add_f32_e32 v131, v131, v141
	s_waitcnt vmcnt(5)
	v_mul_f32_e32 v141, v85, v85
	v_fmac_f32_e32 v141, v84, v84
	v_fmac_f32_e32 v141, v86, v86
	v_fmac_f32_e32 v141, v87, v87
	v_add_f32_e32 v131, v131, v141
	s_waitcnt vmcnt(4)
	v_mul_f32_e32 v141, v77, v77
	s_waitcnt vmcnt(3)
	v_mov_b32_e32 v144, v81
	s_waitcnt vmcnt(2)
	v_mov_b32_e32 v145, v73
	v_fmac_f32_e32 v141, v76, v76
	v_mov_b32_e32 v142, v80
	v_mov_b32_e32 v143, v72
	v_pk_mul_f32 v[144:145], v[144:145], v[144:145]
	v_fmac_f32_e32 v141, v78, v78
	v_pk_fma_f32 v[142:143], v[142:143], v[142:143], v[144:145]
	v_mov_b32_e32 v144, v82
	v_mov_b32_e32 v145, v74
	v_fmac_f32_e32 v141, v79, v79
	v_pk_fma_f32 v[142:143], v[144:145], v[144:145], v[142:143]
	v_mov_b32_e32 v144, v83
	v_mov_b32_e32 v145, v75
	v_add_f32_e32 v131, v131, v141
	v_pk_fma_f32 v[142:143], v[144:145], v[144:145], v[142:143]
	s_waitcnt vmcnt(1)
	v_mov_b32_e32 v144, v69
	v_add_f32_e32 v131, v131, v142
	s_waitcnt vmcnt(0)
	v_mov_b32_e32 v145, v65
	v_add_f32_e32 v131, v131, v143
	v_mov_b32_e32 v142, v68
	v_mov_b32_e32 v143, v64
	v_pk_mul_f32 v[144:145], v[144:145], v[144:145]
	s_mov_b32 s9, 0x10900000
	v_pk_fma_f32 v[142:143], v[142:143], v[142:143], v[144:145]
	v_mov_b32_e32 v144, v70
	v_mov_b32_e32 v145, v66
	v_pk_fma_f32 v[142:143], v[144:145], v[144:145], v[142:143]
	v_mov_b32_e32 v144, v71
	v_mov_b32_e32 v145, v67
	v_pk_fma_f32 v[142:143], v[144:145], v[144:145], v[142:143]
	v_lshl_add_u64 v[144:145], s[86:87], 0, v[134:135]
	v_add_f32_e32 v131, v131, v142
	v_add_f32_e32 v131, v131, v143
	ds_bpermute_b32 v141, v97, v131
	v_add_u32_e32 v130, s8, v130
	v_lshl_add_u64 v[132:133], v[132:133], 0, s[10:11]
	v_lshl_add_u64 v[134:135], v[134:135], 0, s[12:13]
	s_waitcnt lgkmcnt(0)
	v_add_f32_e32 v131, v131, v141
	ds_bpermute_b32 v141, v136, v131
	s_waitcnt lgkmcnt(0)
	v_add_f32_e32 v131, v131, v141
	ds_bpermute_b32 v141, v137, v131
	s_waitcnt lgkmcnt(0)
	v_add_f32_e32 v131, v131, v141
	ds_bpermute_b32 v141, v138, v131
	s_waitcnt lgkmcnt(0)
	v_add_f32_e32 v131, v131, v141
	ds_bpermute_b32 v141, v139, v131
	s_waitcnt lgkmcnt(0)
	v_add_f32_e32 v131, v131, v141
	ds_bpermute_b32 v141, v140, v131
	s_waitcnt lgkmcnt(0)
; __device__ __forceinline__ void rmsnorm_rows(const float* __restrict__ xin, const float* __restrict__ g, u16* outb, float* outf,
;                                              int row_begin, int row_end, int row_step, const int tidx) {
;     ...
;     ss = wave_sum(ss);
;     float rs = rsqrtf(ss * (1.f / DM) + 1e-6f);
; #pragma unroll
;     for (int i = 0; i < 16; ++i) {
;       f32x4 o = v[i] * rs * ggv[i];
;       if (outb) {
;         u32x2 pk;
;         pk.x = pack2(o[0], o[1]);
;         pk.y = pack2(o[2], o[3]);
;         *reinterpret_cast<u32x2*>(outb + (size_t)row * DM + i * 256 + lane * 4) = pk;
;       } else {
;         *reinterpret_cast<f32x4*>(outf + (size_t)row * DM + i * 256 + lane * 4) = o;
;       }
;     }
	v_add_f32_e32 v131, v131, v141
	v_fmamk_f32 v131, v131, 0x39800000, v211
	v_cmp_gt_f32_e32 vcc, s1, v131
	v_mul_f32_e32 v141, 0x4b800000, v131
	s_nop 0
	v_cndmask_b32_e32 v131, v131, v141, vcc
	v_rsq_f32_e32 v131, v131
	s_nop 0
	v_mul_f32_e32 v141, 0x45800000, v131
	v_cndmask_b32_e32 v142, v131, v141, vcc
	v_pk_mul_f32 v[126:127], v[126:127], v[142:143] op_sel_hi:[1,0]
	v_pk_mul_f32 v[128:129], v[128:129], v[142:143] op_sel_hi:[1,0]
	v_pk_mul_f32 v[126:127], v[8:9], v[126:127]
	v_pk_mul_f32 v[128:129], v[10:11], v[128:129]
	v_cvt_pk_bf16_f32 v126, v126, v127
	v_pk_mul_f32 v[110:111], v[110:111], v[142:143] op_sel_hi:[1,0]
	v_cvt_pk_bf16_f32 v127, v128, v129
	v_add_co_u32_e32 v128, vcc, s9, v144
	s_mov_b32 s9, 0x10901000
	s_nop 0
	v_addc_co_u32_e32 v129, vcc, 0, v145, vcc
	v_pk_mul_f32 v[92:93], v[92:93], v[142:143] op_sel_hi:[1,0]
	v_pk_mul_f32 v[76:77], v[76:77], v[142:143] op_sel_hi:[1,0]
	v_add_co_u32_e32 v144, vcc, s9, v144
	v_pk_mul_f32 v[112:113], v[112:113], v[142:143] op_sel_hi:[1,0]
	v_pk_mul_f32 v[110:111], v[12:13], v[110:111]
	v_pk_mul_f32 v[94:95], v[94:95], v[142:143] op_sel_hi:[1,0]
	v_pk_mul_f32 v[92:93], v[28:29], v[92:93]
	v_pk_mul_f32 v[78:79], v[78:79], v[142:143] op_sel_hi:[1,0]
	v_pk_mul_f32 v[76:77], v[44:45], v[76:77]
	v_addc_co_u32_e32 v145, vcc, 0, v145, vcc
	v_pk_mul_f32 v[112:113], v[14:15], v[112:113]
	v_cvt_pk_bf16_f32 v110, v110, v111
	v_pk_mul_f32 v[94:95], v[30:31], v[94:95]
	v_cvt_pk_bf16_f32 v111, v112, v113
	v_cvt_pk_bf16_f32 v92, v92, v93
	v_pk_mul_f32 v[78:79], v[46:47], v[78:79]
	v_cvt_pk_bf16_f32 v93, v94, v95
	v_cvt_pk_bf16_f32 v76, v76, v77
	v_pk_mul_f32 v[122:123], v[122:123], v[142:143] op_sel_hi:[1,0]
	v_cvt_pk_bf16_f32 v77, v78, v79
	v_pk_mul_f32 v[118:119], v[118:119], v[142:143] op_sel_hi:[1,0]
	global_store_dwordx2 v[128:129], v[110:111], off offset:1536 sc1
	v_pk_mul_f32 v[110:111], v[114:115], v[142:143] op_sel_hi:[1,0]
	v_pk_mul_f32 v[106:107], v[106:107], v[142:143] op_sel_hi:[1,0]
	v_pk_mul_f32 v[102:103], v[102:103], v[142:143] op_sel_hi:[1,0]
	global_store_dwordx2 v[128:129], v[92:93], off offset:3584 sc1
	v_pk_mul_f32 v[92:93], v[98:99], v[142:143] op_sel_hi:[1,0]
	v_pk_mul_f32 v[88:89], v[88:89], v[142:143] op_sel_hi:[1,0]
	v_pk_mul_f32 v[84:85], v[84:85], v[142:143] op_sel_hi:[1,0]
	global_store_dwordx2 v[144:145], v[76:77], off offset:1536 sc1
	v_pk_mul_f32 v[76:77], v[80:81], v[142:143] op_sel_hi:[1,0]
	v_pk_mul_f32 v[72:73], v[72:73], v[142:143] op_sel_hi:[1,0]
	v_pk_mul_f32 v[68:69], v[68:69], v[142:143] op_sel_hi:[1,0]
	v_pk_mul_f32 v[64:65], v[64:65], v[142:143] op_sel_hi:[1,0]
	v_cmp_lt_i32_e32 vcc, s16, v130
	v_pk_mul_f32 v[124:125], v[124:125], v[142:143] op_sel_hi:[1,0]
	v_pk_mul_f32 v[122:123], v[0:1], v[122:123]
	v_pk_mul_f32 v[120:121], v[120:121], v[142:143] op_sel_hi:[1,0]
	v_pk_mul_f32 v[118:119], v[4:5], v[118:119]
	v_pk_mul_f32 v[112:113], v[116:117], v[142:143] op_sel_hi:[1,0]
	v_pk_mul_f32 v[110:111], v[16:17], v[110:111]
	v_pk_mul_f32 v[108:109], v[108:109], v[142:143] op_sel_hi:[1,0]
	v_pk_mul_f32 v[106:107], v[20:21], v[106:107]
	v_pk_mul_f32 v[104:105], v[104:105], v[142:143] op_sel_hi:[1,0]
	v_pk_mul_f32 v[102:103], v[24:25], v[102:103]
	v_pk_mul_f32 v[94:95], v[100:101], v[142:143] op_sel_hi:[1,0]
	v_pk_mul_f32 v[92:93], v[32:33], v[92:93]
	v_pk_mul_f32 v[90:91], v[90:91], v[142:143] op_sel_hi:[1,0]
	v_pk_mul_f32 v[88:89], v[36:37], v[88:89]
	v_pk_mul_f32 v[86:87], v[86:87], v[142:143] op_sel_hi:[1,0]
	v_pk_mul_f32 v[84:85], v[40:41], v[84:85]
	v_pk_mul_f32 v[78:79], v[82:83], v[142:143] op_sel_hi:[1,0]
	v_pk_mul_f32 v[76:77], v[48:49], v[76:77]
	v_pk_mul_f32 v[74:75], v[74:75], v[142:143] op_sel_hi:[1,0]
	v_pk_mul_f32 v[72:73], v[52:53], v[72:73]
	v_pk_mul_f32 v[70:71], v[70:71], v[142:143] op_sel_hi:[1,0]
	v_pk_mul_f32 v[68:69], v[56:57], v[68:69]
	v_pk_mul_f32 v[66:67], v[66:67], v[142:143] op_sel_hi:[1,0]
	v_pk_mul_f32 v[64:65], v[60:61], v[64:65]
	s_or_b64 s[14:15], vcc, s[14:15]
	global_store_dwordx2 v[144:145], v[126:127], off offset:-4096 sc1
	v_pk_mul_f32 v[124:125], v[2:3], v[124:125]
	v_cvt_pk_bf16_f32 v122, v122, v123
	v_pk_mul_f32 v[120:121], v[6:7], v[120:121]
	v_cvt_pk_bf16_f32 v123, v124, v125
	global_store_dwordx2 v[128:129], v[122:123], off offset:512 sc1
	v_cvt_pk_bf16_f32 v118, v118, v119
	v_cvt_pk_bf16_f32 v119, v120, v121
	global_store_dwordx2 v[128:129], v[118:119], off offset:1024 sc1
	v_pk_mul_f32 v[112:113], v[18:19], v[112:113]
	v_cvt_pk_bf16_f32 v110, v110, v111
	v_pk_mul_f32 v[108:109], v[22:23], v[108:109]
	v_cvt_pk_bf16_f32 v111, v112, v113
	global_store_dwordx2 v[128:129], v[110:111], off offset:2048 sc1
	v_cvt_pk_bf16_f32 v106, v106, v107
	v_cvt_pk_bf16_f32 v107, v108, v109
	global_store_dwordx2 v[128:129], v[106:107], off offset:2560 sc1
	v_pk_mul_f32 v[104:105], v[26:27], v[104:105]
	v_cvt_pk_bf16_f32 v102, v102, v103
	v_pk_mul_f32 v[94:95], v[34:35], v[94:95]
	v_cvt_pk_bf16_f32 v103, v104, v105
	global_store_dwordx2 v[128:129], v[102:103], off offset:3072 sc1
	v_cvt_pk_bf16_f32 v92, v92, v93
	v_cvt_pk_bf16_f32 v93, v94, v95
	global_store_dwordx2 v[144:145], v[92:93], off sc1
	v_pk_mul_f32 v[90:91], v[38:39], v[90:91]
	v_cvt_pk_bf16_f32 v88, v88, v89
	v_pk_mul_f32 v[86:87], v[42:43], v[86:87]
	v_cvt_pk_bf16_f32 v89, v90, v91
	global_store_dwordx2 v[144:145], v[88:89], off offset:512 sc1
	v_cvt_pk_bf16_f32 v84, v84, v85
	v_cvt_pk_bf16_f32 v85, v86, v87
	global_store_dwordx2 v[144:145], v[84:85], off offset:1024 sc1
	v_pk_mul_f32 v[78:79], v[50:51], v[78:79]
	v_cvt_pk_bf16_f32 v76, v76, v77
	v_pk_mul_f32 v[74:75], v[54:55], v[74:75]
	v_cvt_pk_bf16_f32 v77, v78, v79
	global_store_dwordx2 v[144:145], v[76:77], off offset:2048 sc1
	v_cvt_pk_bf16_f32 v72, v72, v73
	v_cvt_pk_bf16_f32 v73, v74, v75
	global_store_dwordx2 v[144:145], v[72:73], off offset:2560 sc1
	v_pk_mul_f32 v[70:71], v[58:59], v[70:71]
	v_cvt_pk_bf16_f32 v68, v68, v69
	v_pk_mul_f32 v[66:67], v[62:63], v[66:67]
	v_cvt_pk_bf16_f32 v69, v70, v71
	global_store_dwordx2 v[144:145], v[68:69], off offset:3072 sc1
	v_cvt_pk_bf16_f32 v64, v64, v65
	v_cvt_pk_bf16_f32 v65, v66, v67
	global_store_dwordx2 v[144:145], v[64:65], off offset:3584 sc1
	s_andn2_b64 exec, exec, s[14:15]
	s_cbranch_execnz .LBB0_229

; __device__ __forceinline__ void phase_gemm1(const Params& p, int layer, int rep) {
;     ...
;       const float sc = (feat0 >= OFF_Q && feat0 < OFF_K) ? QSCALE : 1.f;
;       char* cl = smem;
; #pragma unroll
;       for (int ai = 0; ai < 2; ++ai)
; #pragma unroll
;         for (int bj = 0; bj < 2; ++bj)
; #pragma unroll
;           for (int m = 0; m < 4; ++m)
; #pragma unroll
;             for (int n = 0; n < 2; ++n) {
;               int fl = ai * 128 + wr * 64 + m * 16 + fq * 4;
;               int tl = bj * 128 + wc * 32 + n * 16 + fr;
;               f32x4 v = acc[ai][bj][m][n];
;               u32x2 o;
;               o.x = pack2(v[0] * sc, v[1] * sc);
;               o.y = pack2(v[2] * sc, v[3] * sc);
;               *reinterpret_cast<u32x2*>(cl + tl * 512 + (((fl >> 3) ^ (tl & 31)) << 4) + ((fl >> 2) & 1) * 8) = o;
;             }
.LBB0_242:
	s_or_b64 exec, exec, s[14:15]
	s_and_b32 s16, s37, -16
	v_bfe_u32 v133, v146, 6, 2
	s_mov_b64 s[14:15], -1
	s_cmp_eq_u32 s16, 16
	v_or_b32_e32 v132, 16, v97
	s_cbranch_scc1 .LBB0_244
	s_cmp_eq_u32 s11, 8
	s_cselect_b64 vcc, -1, 0
	v_mov_b32_e32 v130, 0x3e0293ee
	v_cndmask_b32_e32 v134, 1.0, v130, vcc
	v_lshlrev_b32_e32 v130, 2, v147
	v_and_or_b32 v135, v130, 8, v148
	v_lshlrev_b32_e32 v130, 3, v147
	v_and_b32_e32 v136, 8, v130
	v_mul_f32_e32 v130, v134, v126
	v_mul_f32_e32 v131, v134, v127
	v_cvt_pk_bf16_f32 v130, v130, v131
	v_mul_f32_e32 v131, v134, v128
	v_mul_f32_e32 v138, v134, v129
	v_lshrrev_b32_e32 v137, 3, v135
	v_cvt_pk_bf16_f32 v131, v131, v138
	v_lshlrev_b32_e32 v138, 14, v133
	v_lshlrev_b32_e32 v139, 9, v97
	v_add3_u32 v138, 32, v138, v139
	v_xor_b32_e32 v139, v137, v97
	v_lshlrev_b32_e32 v139, 4, v139
	v_add3_u32 v140, v138, v139, v136
	ds_write_b64 v140, v[130:131]
	v_mul_f32_e32 v130, v134, v122
	v_mul_f32_e32 v131, v134, v123
	v_cvt_pk_bf16_f32 v130, v130, v131
	v_mul_f32_e32 v131, v134, v124
	v_mul_f32_e32 v140, v134, v125
	v_cvt_pk_bf16_f32 v131, v131, v140
	v_bitop3_b32 v140, v137, v97, 16 bitop3:0x1e
	v_lshlrev_b32_e32 v140, 4, v140
	v_add3_u32 v141, v138, v140, v136
	ds_write_b64 v141, v[130:131] offset:8192
	v_mul_f32_e32 v130, v134, v118
	v_mul_f32_e32 v131, v134, v119
	v_cvt_pk_bf16_f32 v130, v130, v131
	v_mul_f32_e32 v131, v134, v120
	v_mul_f32_e32 v141, v134, v121
	v_cvt_pk_bf16_f32 v131, v131, v141
	v_bitop3_b32 v141, v137, v97, 2 bitop3:0x36
	v_lshlrev_b32_e32 v141, 4, v141
	v_add3_u32 v142, v138, v141, v136
	ds_write_b64 v142, v[130:131]
	v_mul_f32_e32 v130, v134, v114
	v_mul_f32_e32 v131, v134, v115
	v_cvt_pk_bf16_f32 v130, v130, v131
	v_mul_f32_e32 v131, v134, v116
	v_mul_f32_e32 v142, v134, v117
	v_cvt_pk_bf16_f32 v131, v131, v142
	v_bitop3_b32 v142, v137, v132, 2 bitop3:0x36
	v_lshlrev_b32_e32 v142, 4, v142
	v_add3_u32 v143, v138, v142, v136
	ds_write_b64 v143, v[130:131] offset:8192
	v_mul_f32_e32 v130, v134, v110
	v_mul_f32_e32 v131, v134, v111
	v_cvt_pk_bf16_f32 v130, v130, v131
	v_mul_f32_e32 v131, v134, v112
	v_mul_f32_e32 v143, v134, v113
	v_cvt_pk_bf16_f32 v131, v131, v143
	v_bitop3_b32 v143, v137, v97, 4 bitop3:0x36
	v_lshlrev_b32_e32 v143, 4, v143
	v_add3_u32 v144, v138, v143, v136
	ds_write_b64 v144, v[130:131]
	v_mul_f32_e32 v130, v134, v106
	v_mul_f32_e32 v131, v134, v107
	v_cvt_pk_bf16_f32 v130, v130, v131
	v_mul_f32_e32 v131, v134, v108
	v_mul_f32_e32 v144, v134, v109
	v_cvt_pk_bf16_f32 v131, v131, v144
	v_bitop3_b32 v144, v137, v132, 4 bitop3:0x36
	v_lshlrev_b32_e32 v144, 4, v144
	v_add3_u32 v145, v138, v144, v136
	ds_write_b64 v145, v[130:131] offset:8192
	v_mul_f32_e32 v130, v134, v102
	v_mul_f32_e32 v131, v134, v103
	v_cvt_pk_bf16_f32 v130, v130, v131
	v_mul_f32_e32 v131, v134, v104
	v_mul_f32_e32 v145, v134, v105
	v_cvt_pk_bf16_f32 v131, v131, v145
	v_bitop3_b32 v145, v137, v97, 6 bitop3:0x36
	v_lshlrev_b32_e32 v145, 4, v145
	v_add3_u32 v150, v138, v145, v136
	ds_write_b64 v150, v[130:131]
	v_mul_f32_e32 v130, v134, v98
	v_mul_f32_e32 v131, v134, v99
	v_bitop3_b32 v137, v137, v132, 6 bitop3:0x36
	v_cvt_pk_bf16_f32 v130, v130, v131
	v_mul_f32_e32 v131, v134, v100
	v_mul_f32_e32 v150, v134, v101
	v_lshlrev_b32_e32 v137, 4, v137
	v_cvt_pk_bf16_f32 v131, v131, v150
	v_add3_u32 v150, v138, v137, v136
	ds_write_b64 v150, v[130:131] offset:8192
	v_mul_f32_e32 v130, v134, v92
	v_mul_f32_e32 v131, v134, v93
	v_cvt_pk_bf16_f32 v130, v130, v131
	v_mul_f32_e32 v131, v134, v94
	v_mul_f32_e32 v150, v134, v95
	v_cvt_pk_bf16_f32 v131, v131, v150
	v_add_u32_e32 v150, 0x10000, v138
	v_add3_u32 v139, v150, v139, v136
	ds_write_b64 v139, v[130:131]
	v_mul_f32_e32 v130, v134, v88
	v_mul_f32_e32 v131, v134, v89
	v_cvt_pk_bf16_f32 v130, v130, v131
	v_mul_f32_e32 v131, v134, v90
	v_mul_f32_e32 v139, v134, v91
	v_cvt_pk_bf16_f32 v131, v131, v139
	v_add_u32_e32 v139, 0x12000, v138
	v_add3_u32 v140, v139, v140, v136
	ds_write_b64 v140, v[130:131]
	v_mul_f32_e32 v130, v134, v84
	v_mul_f32_e32 v131, v134, v85
	v_cvt_pk_bf16_f32 v130, v130, v131
	v_mul_f32_e32 v131, v134, v86
	v_mul_f32_e32 v140, v134, v87
	v_cvt_pk_bf16_f32 v131, v131, v140
	v_add3_u32 v140, v150, v141, v136
	ds_write_b64 v140, v[130:131]
	v_mul_f32_e32 v130, v134, v80
	v_mul_f32_e32 v131, v134, v81
	v_cvt_pk_bf16_f32 v130, v130, v131
	v_mul_f32_e32 v131, v134, v82
	v_mul_f32_e32 v140, v134, v83
	v_cvt_pk_bf16_f32 v131, v131, v140
	v_add3_u32 v140, v139, v142, v136
	ds_write_b64 v140, v[130:131]
	v_mul_f32_e32 v130, v134, v76
	v_mul_f32_e32 v131, v134, v77
	v_cvt_pk_bf16_f32 v130, v130, v131
	v_mul_f32_e32 v131, v134, v78
	v_mul_f32_e32 v140, v134, v79
	v_cvt_pk_bf16_f32 v131, v131, v140
	v_add3_u32 v140, v150, v143, v136
	ds_write_b64 v140, v[130:131]
	v_mul_f32_e32 v130, v134, v72
	v_mul_f32_e32 v131, v134, v73
	v_cvt_pk_bf16_f32 v130, v130, v131
	v_mul_f32_e32 v131, v134, v74
	v_mul_f32_e32 v140, v134, v75
	v_cvt_pk_bf16_f32 v131, v131, v140
	v_add3_u32 v140, v139, v144, v136
	ds_write_b64 v140, v[130:131]
	v_mul_f32_e32 v130, v134, v68
	v_mul_f32_e32 v131, v134, v69
	v_cvt_pk_bf16_f32 v130, v130, v131
	v_mul_f32_e32 v131, v134, v70
	v_mul_f32_e32 v140, v134, v71
	v_cvt_pk_bf16_f32 v131, v131, v140
	v_add3_u32 v140, v150, v145, v136
	ds_write_b64 v140, v[130:131]
	v_mul_f32_e32 v130, v134, v64
	v_mul_f32_e32 v131, v134, v65
	v_cvt_pk_bf16_f32 v130, v130, v131
	v_mul_f32_e32 v131, v134, v66
	v_add3_u32 v137, v139, v137, v136
	v_mul_f32_e32 v140, v134, v67
	v_cvt_pk_bf16_f32 v131, v131, v140
	ds_write_b64 v137, v[130:131]
	v_add_u32_e32 v130, 0x80, v135
	v_lshrrev_b32_e32 v137, 3, v130
	v_mul_f32_e32 v130, v134, v60
; __device__ __forceinline__ void phase_gemm1(const Params& p, int layer, int rep) {
;     ...
;             for (int n = 0; n < 2; ++n) {
;               int fl = ai * 128 + wr * 64 + m * 16 + fq * 4;
;               int tl = bj * 128 + wc * 32 + n * 16 + fr;
;               f32x4 v = acc[ai][bj][m][n];
;               u32x2 o;
;               o.x = pack2(v[0] * sc, v[1] * sc);
;               o.y = pack2(v[2] * sc, v[3] * sc);
;               *reinterpret_cast<u32x2*>(cl + tl * 512 + (((fl >> 3) ^ (tl & 31)) << 4) + ((fl >> 2) & 1) * 8) = o;
;             }
;       __syncthreads();
	v_mul_f32_e32 v131, v134, v61
	v_cvt_pk_bf16_f32 v130, v130, v131
	v_mul_f32_e32 v131, v134, v62
	v_mul_f32_e32 v140, v134, v63
	v_cvt_pk_bf16_f32 v131, v131, v140
	v_xor_b32_e32 v140, v137, v97
	v_lshlrev_b32_e32 v140, 4, v140
	v_add3_u32 v141, v138, v140, v136
	ds_write_b64 v141, v[130:131]
	v_mul_f32_e32 v130, v134, v56
	v_mul_f32_e32 v131, v134, v57
	v_bitop3_b32 v137, v137, v97, 16 bitop3:0x1e
	v_cvt_pk_bf16_f32 v130, v130, v131
	v_mul_f32_e32 v131, v134, v58
	v_mul_f32_e32 v141, v134, v59
	v_lshlrev_b32_e32 v137, 4, v137
	v_cvt_pk_bf16_f32 v131, v131, v141
	v_add3_u32 v141, v138, v137, v136
	ds_write_b64 v141, v[130:131] offset:8192
	v_add_u32_e32 v130, 0x90, v135
	v_lshrrev_b32_e32 v141, 3, v130
	v_mul_f32_e32 v130, v134, v52
	v_mul_f32_e32 v131, v134, v53
	v_cvt_pk_bf16_f32 v130, v130, v131
	v_mul_f32_e32 v131, v134, v54
	v_mul_f32_e32 v142, v134, v55
	v_cvt_pk_bf16_f32 v131, v131, v142
	v_xor_b32_e32 v142, v141, v97
	v_lshlrev_b32_e32 v142, 4, v142
	v_add3_u32 v143, v138, v142, v136
	ds_write_b64 v143, v[130:131]
	v_mul_f32_e32 v130, v134, v48
	v_mul_f32_e32 v131, v134, v49
	v_bitop3_b32 v141, v141, v97, 16 bitop3:0x1e
	v_cvt_pk_bf16_f32 v130, v130, v131
	v_mul_f32_e32 v131, v134, v50
	v_mul_f32_e32 v143, v134, v51
	v_lshlrev_b32_e32 v141, 4, v141
	v_cvt_pk_bf16_f32 v131, v131, v143
	v_add3_u32 v143, v138, v141, v136
	ds_write_b64 v143, v[130:131] offset:8192
	v_add_u32_e32 v130, 0xa0, v135
	v_lshrrev_b32_e32 v143, 3, v130
	v_mul_f32_e32 v130, v134, v44
	v_mul_f32_e32 v131, v134, v45
	v_cvt_pk_bf16_f32 v130, v130, v131
	v_mul_f32_e32 v131, v134, v46
	v_mul_f32_e32 v144, v134, v47
	v_cvt_pk_bf16_f32 v131, v131, v144
	v_xor_b32_e32 v144, v143, v97
	v_lshlrev_b32_e32 v144, 4, v144
	v_add3_u32 v145, v138, v144, v136
	ds_write_b64 v145, v[130:131]
	v_mul_f32_e32 v130, v134, v40
	v_mul_f32_e32 v131, v134, v41
	v_bitop3_b32 v143, v143, v97, 16 bitop3:0x1e
	v_cvt_pk_bf16_f32 v130, v130, v131
	v_mul_f32_e32 v131, v134, v42
	v_mul_f32_e32 v145, v134, v43
	v_lshlrev_b32_e32 v143, 4, v143
	v_cvt_pk_bf16_f32 v131, v131, v145
	v_add3_u32 v145, v138, v143, v136
	ds_write_b64 v145, v[130:131] offset:8192
	v_add_u32_e32 v130, 0xb0, v135
	v_lshrrev_b32_e32 v135, 3, v130
	v_mul_f32_e32 v130, v134, v36
	v_mul_f32_e32 v131, v134, v37
	v_cvt_pk_bf16_f32 v130, v130, v131
	v_mul_f32_e32 v131, v134, v38
	v_mul_f32_e32 v145, v134, v39
	v_cvt_pk_bf16_f32 v131, v131, v145
	v_xor_b32_e32 v145, v135, v97
	v_lshlrev_b32_e32 v145, 4, v145
	v_add3_u32 v151, v138, v145, v136
	ds_write_b64 v151, v[130:131]
	v_mul_f32_e32 v130, v134, v32
	v_mul_f32_e32 v131, v134, v33
	v_bitop3_b32 v135, v135, v97, 16 bitop3:0x1e
	v_cvt_pk_bf16_f32 v130, v130, v131
	v_mul_f32_e32 v131, v134, v34
	v_lshlrev_b32_e32 v135, 4, v135
	v_mul_f32_e32 v151, v134, v35
	v_cvt_pk_bf16_f32 v131, v131, v151
	v_add3_u32 v138, v138, v135, v136
	ds_write_b64 v138, v[130:131] offset:8192
	v_mul_f32_e32 v130, v134, v28
	v_mul_f32_e32 v131, v134, v29
	v_cvt_pk_bf16_f32 v130, v130, v131
	v_mul_f32_e32 v131, v134, v30
	v_mul_f32_e32 v138, v134, v31
	v_cvt_pk_bf16_f32 v131, v131, v138
	v_add3_u32 v138, v150, v140, v136
	ds_write_b64 v138, v[130:131]
	v_mul_f32_e32 v130, v134, v24
	v_mul_f32_e32 v131, v134, v25
	v_cvt_pk_bf16_f32 v130, v130, v131
	v_mul_f32_e32 v131, v134, v26
	v_mul_f32_e32 v138, v134, v27
	v_cvt_pk_bf16_f32 v131, v131, v138
	v_add3_u32 v137, v139, v137, v136
	ds_write_b64 v137, v[130:131]
	v_mul_f32_e32 v130, v134, v20
	v_mul_f32_e32 v131, v134, v21
	v_cvt_pk_bf16_f32 v130, v130, v131
	v_mul_f32_e32 v131, v134, v22
	v_mul_f32_e32 v137, v134, v23
	v_cvt_pk_bf16_f32 v131, v131, v137
	v_add3_u32 v137, v150, v142, v136
	ds_write_b64 v137, v[130:131]
	v_mul_f32_e32 v130, v134, v16
	v_mul_f32_e32 v131, v134, v17
	v_cvt_pk_bf16_f32 v130, v130, v131
	v_mul_f32_e32 v131, v134, v18
	v_mul_f32_e32 v137, v134, v19
	v_cvt_pk_bf16_f32 v131, v131, v137
	v_add3_u32 v137, v139, v141, v136
	ds_write_b64 v137, v[130:131]
	v_mul_f32_e32 v130, v134, v12
	v_mul_f32_e32 v131, v134, v13
	v_cvt_pk_bf16_f32 v130, v130, v131
	v_mul_f32_e32 v131, v134, v14
	v_mul_f32_e32 v137, v134, v15
	v_cvt_pk_bf16_f32 v131, v131, v137
	v_add3_u32 v137, v150, v144, v136
	ds_write_b64 v137, v[130:131]
	v_mul_f32_e32 v130, v134, v8
	v_mul_f32_e32 v131, v134, v9
	v_cvt_pk_bf16_f32 v130, v130, v131
	v_mul_f32_e32 v131, v134, v10
	v_mul_f32_e32 v137, v134, v11
	v_cvt_pk_bf16_f32 v131, v131, v137
	v_add3_u32 v137, v139, v143, v136
	ds_write_b64 v137, v[130:131]
	v_mul_f32_e32 v130, v134, v4
	v_mul_f32_e32 v131, v134, v5
	v_cvt_pk_bf16_f32 v130, v130, v131
	v_mul_f32_e32 v131, v134, v6
	v_mul_f32_e32 v137, v134, v7
	v_cvt_pk_bf16_f32 v131, v131, v137
	v_add3_u32 v137, v150, v145, v136
	ds_write_b64 v137, v[130:131]
	v_mul_f32_e32 v130, v134, v0
	v_mul_f32_e32 v131, v134, v1
	v_cvt_pk_bf16_f32 v130, v130, v131
	v_mul_f32_e32 v131, v134, v2
	v_mul_f32_e32 v134, v134, v3
	v_cvt_pk_bf16_f32 v131, v131, v134
	v_add3_u32 v134, v139, v135, v136
	v_ashrrev_i32_e32 v204, 5, v146
	ds_write_b64 v134, v[130:131]
	v_xor_b32_e32 v131, v204, v146
	v_lshlrev_b32_e32 v131, 4, v131
	v_lshlrev_b32_e32 v130, 9, v204
	v_and_b32_e32 v131, 0x1f0, v131
	v_add3_u32 v130, 32, v130, v131
	v_add_u32_e32 v131, 0x200, v146
	v_ashrrev_i32_e32 v206, 5, v131
	v_xor_b32_e32 v134, v206, v146
	v_lshlrev_b32_e32 v134, 4, v134
	v_lshlrev_b32_e32 v131, 9, v206
	v_and_b32_e32 v134, 0x1f0, v134
	s_waitcnt vmcnt(0) lgkmcnt(0)
	s_barrier
; __device__ __forceinline__ void phase_gemm1(const Params& p, int layer, int rep) {
;     ...
;       u32x4 cv[16];
; #pragma unroll
;       for (int i = 0; i < 16; ++i) {
;         int id = i * NTHR + tidx, tl = id >> 5, ch = id & 31;
;         cv[i] = *reinterpret_cast<const u32x4*>(cl + tl * 512 + ((ch ^ (tl & 31)) << 4));
;       }
; #pragma unroll
;       for (int i = 0; i < 16; ++i) {
;         int id = i * NTHR + tidx, tl = id >> 5, ch = id & 31;
;         *reinterpret_cast<u32x4*>(proj + (size_t)(tok0 + tl) * DIN + feat0 + ch * 8) = cv[i];
;       }
	v_add3_u32 v131, 32, v131, v134
	ds_read_b128 v[134:137], v130
	ds_read_b128 v[138:141], v131
	v_add_u32_e32 v130, 0x400, v146
	v_ashrrev_i32_e32 v207, 5, v130
	v_xor_b32_e32 v131, v207, v146
	v_lshlrev_b32_e32 v131, 4, v131
	v_lshlrev_b32_e32 v130, 9, v207
	v_and_b32_e32 v131, 0x1f0, v131
	v_add3_u32 v130, 32, v130, v131
	v_add_u32_e32 v131, 0x600, v146
	v_ashrrev_i32_e32 v208, 5, v131
	v_xor_b32_e32 v142, v208, v146
	v_lshlrev_b32_e32 v142, 4, v142
	v_lshlrev_b32_e32 v131, 9, v208
	v_and_b32_e32 v142, 0x1f0, v142
	v_add3_u32 v131, 32, v131, v142
	ds_read_b128 v[142:145], v130
	ds_read_b128 v[150:153], v131
	v_add_u32_e32 v130, 0x800, v146
	v_ashrrev_i32_e32 v209, 5, v130
	v_xor_b32_e32 v131, v209, v146
	v_lshlrev_b32_e32 v131, 4, v131
	v_lshlrev_b32_e32 v130, 9, v209
	v_and_b32_e32 v131, 0x1f0, v131
	v_add3_u32 v130, 32, v130, v131
	v_add_u32_e32 v131, 0xa00, v146
	v_ashrrev_i32_e32 v212, 5, v131
	v_xor_b32_e32 v154, v212, v146
	v_lshlrev_b32_e32 v154, 4, v154
	v_lshlrev_b32_e32 v131, 9, v212
	v_and_b32_e32 v154, 0x1f0, v154
	v_add3_u32 v131, 32, v131, v154
	ds_read_b128 v[154:157], v130
	ds_read_b128 v[158:161], v131
	v_add_u32_e32 v130, 0xc00, v146
	v_ashrrev_i32_e32 v213, 5, v130
	v_xor_b32_e32 v131, v213, v146
	v_lshlrev_b32_e32 v131, 4, v131
	v_lshlrev_b32_e32 v130, 9, v213
	v_and_b32_e32 v131, 0x1f0, v131
	v_add3_u32 v130, 32, v130, v131
	v_add_u32_e32 v131, 0xe00, v146
	v_ashrrev_i32_e32 v216, 5, v131
	v_xor_b32_e32 v162, v216, v146
	v_lshlrev_b32_e32 v162, 4, v162
	v_lshlrev_b32_e32 v131, 9, v216
	v_and_b32_e32 v162, 0x1f0, v162
	v_add3_u32 v131, 32, v131, v162
	ds_read_b128 v[164:167], v130
	ds_read_b128 v[168:171], v131
	v_add_u32_e32 v130, 0x1000, v146
	v_ashrrev_i32_e32 v217, 5, v130
	v_xor_b32_e32 v131, v217, v146
	v_lshlrev_b32_e32 v131, 4, v131
	v_lshlrev_b32_e32 v130, 9, v217
	v_and_b32_e32 v131, 0x1f0, v131
	v_add3_u32 v130, 32, v130, v131
	v_add_u32_e32 v131, 0x1200, v146
	v_ashrrev_i32_e32 v218, 5, v131
	v_xor_b32_e32 v162, v218, v146
	v_lshlrev_b32_e32 v162, 4, v162
	v_lshlrev_b32_e32 v131, 9, v218
	v_and_b32_e32 v162, 0x1f0, v162
	v_add3_u32 v131, 32, v131, v162
	ds_read_b128 v[172:175], v130
	ds_read_b128 v[176:179], v131
	v_add_u32_e32 v130, 0x1400, v146
	v_ashrrev_i32_e32 v219, 5, v130
	v_xor_b32_e32 v131, v219, v146
	v_lshlrev_b32_e32 v131, 4, v131
	v_lshlrev_b32_e32 v130, 9, v219
	v_and_b32_e32 v131, 0x1f0, v131
	v_add3_u32 v130, 32, v130, v131
	v_add_u32_e32 v131, 0x1600, v146
	v_ashrrev_i32_e32 v222, 5, v131
	v_xor_b32_e32 v162, v222, v146
	v_lshlrev_b32_e32 v162, 4, v162
	v_lshlrev_b32_e32 v131, 9, v222
	v_and_b32_e32 v162, 0x1f0, v162
	v_add3_u32 v131, 32, v131, v162
	ds_read_b128 v[180:183], v130
	ds_read_b128 v[184:187], v131
	v_add_u32_e32 v130, 0x1800, v146
	v_ashrrev_i32_e32 v223, 5, v130
	v_xor_b32_e32 v131, v223, v146
	v_lshlrev_b32_e32 v131, 4, v131
	v_lshlrev_b32_e32 v130, 9, v223
	v_and_b32_e32 v131, 0x1f0, v131
	v_add3_u32 v130, 32, v130, v131
	v_add_u32_e32 v131, 0x1a00, v146
	v_ashrrev_i32_e32 v224, 5, v131
	v_xor_b32_e32 v162, v224, v146
	v_lshlrev_b32_e32 v162, 4, v162
	v_lshlrev_b32_e32 v131, 9, v224
	v_and_b32_e32 v162, 0x1f0, v162
	v_add3_u32 v131, 32, v131, v162
	ds_read_b128 v[188:191], v130
	ds_read_b128 v[192:195], v131
	v_add_u32_e32 v130, 0x1c00, v146
	v_ashrrev_i32_e32 v225, 5, v130
	v_xor_b32_e32 v131, v225, v146
	v_lshlrev_b32_e32 v131, 4, v131
	v_lshlrev_b32_e32 v130, 9, v225
	v_and_b32_e32 v131, 0x1f0, v131
	v_add3_u32 v130, 32, v130, v131
	v_add_u32_e32 v131, 0x1e00, v146
	v_ashrrev_i32_e32 v226, 5, v131
	v_xor_b32_e32 v162, v226, v146
	s_ashr_i32 s11, s10, 31
	v_lshlrev_b32_e32 v162, 4, v162
	s_lshl_b64 s[14:15], s[10:11], 1
	v_lshlrev_b32_e32 v131, 9, v226
	v_and_b32_e32 v162, 0x1f0, v162
	s_add_u32 s14, s30, s14
	v_add3_u32 v131, 32, v131, v162
	s_addc_u32 s15, s31, s15
	v_and_b32_e32 v162, 0x1f0, v149
	ds_read_b128 v[196:199], v130
	ds_read_b128 v[200:203], v131
	v_lshl_add_u64 v[130:131], s[14:15], 0, v[162:163]
	v_add_u32_e32 v149, s35, v204
	v_mad_i64_i32 v[204:205], s[14:15], v149, s63, v[130:131]
	s_waitcnt lgkmcnt(14)
	global_store_dwordx4 v[204:205], v[134:137], off sc1
	s_nop 1
	v_add_u32_e32 v134, s35, v206
	v_mad_i64_i32 v[134:135], s[14:15], v134, s63, v[130:131]
	global_store_dwordx4 v[134:135], v[138:141], off sc1
	v_add_u32_e32 v134, s35, v207
	v_mad_i64_i32 v[134:135], s[14:15], v134, s63, v[130:131]
	s_waitcnt lgkmcnt(13)
	global_store_dwordx4 v[134:135], v[142:145], off sc1
	v_add_u32_e32 v134, s35, v208
	v_mad_i64_i32 v[134:135], s[14:15], v134, s63, v[130:131]
	s_waitcnt lgkmcnt(12)
	global_store_dwordx4 v[134:135], v[150:153], off sc1
	v_add_u32_e32 v134, s35, v209
	v_mad_i64_i32 v[134:135], s[14:15], v134, s63, v[130:131]
	s_waitcnt lgkmcnt(11)
	global_store_dwordx4 v[134:135], v[154:157], off sc1
	v_add_u32_e32 v134, s35, v212
	v_mad_i64_i32 v[134:135], s[14:15], v134, s63, v[130:131]
	s_waitcnt lgkmcnt(10)
	global_store_dwordx4 v[134:135], v[158:161], off sc1
	v_add_u32_e32 v134, s35, v213
	v_mad_i64_i32 v[134:135], s[14:15], v134, s63, v[130:131]
	s_waitcnt lgkmcnt(9)
	global_store_dwordx4 v[134:135], v[164:167], off sc1
	v_add_u32_e32 v134, s35, v216
	v_mad_i64_i32 v[134:135], s[14:15], v134, s63, v[130:131]
	s_waitcnt lgkmcnt(8)
	global_store_dwordx4 v[134:135], v[168:171], off sc1
	v_add_u32_e32 v134, s35, v217
	v_mad_i64_i32 v[134:135], s[14:15], v134, s63, v[130:131]
	s_waitcnt lgkmcnt(7)
	global_store_dwordx4 v[134:135], v[172:175], off sc1
	v_add_u32_e32 v134, s35, v218
	v_mad_i64_i32 v[134:135], s[14:15], v134, s63, v[130:131]
	s_waitcnt lgkmcnt(6)
	global_store_dwordx4 v[134:135], v[176:179], off sc1
	v_add_u32_e32 v134, s35, v219
	v_mad_i64_i32 v[134:135], s[14:15], v134, s63, v[130:131]
	s_waitcnt lgkmcnt(5)
	global_store_dwordx4 v[134:135], v[180:183], off sc1
	v_add_u32_e32 v134, s35, v222
	v_mad_i64_i32 v[134:135], s[14:15], v134, s63, v[130:131]
	s_waitcnt lgkmcnt(4)
	global_store_dwordx4 v[134:135], v[184:187], off sc1
	v_add_u32_e32 v134, s35, v223
	v_mad_i64_i32 v[134:135], s[14:15], v134, s63, v[130:131]
	s_waitcnt lgkmcnt(3)
	global_store_dwordx4 v[134:135], v[188:191], off sc1
	v_add_u32_e32 v134, s35, v224
	v_mad_i64_i32 v[134:135], s[14:15], v134, s63, v[130:131]
	s_waitcnt lgkmcnt(2)
	global_store_dwordx4 v[134:135], v[192:195], off sc1
	v_add_u32_e32 v134, s35, v225
	v_mad_i64_i32 v[134:135], s[14:15], v134, s63, v[130:131]
	s_waitcnt lgkmcnt(1)
	global_store_dwordx4 v[134:135], v[196:199], off sc1
	v_add_u32_e32 v134, s35, v226
	v_mad_i64_i32 v[130:131], s[14:15], v134, s63, v[130:131]
	s_mov_b64 s[14:15], 0
	s_waitcnt lgkmcnt(0)
	global_store_dwordx4 v[130:131], v[200:203], off sc1

; __device__ __forceinline__ void rmsnorm_rows(const float* __restrict__ xin, const float* __restrict__ g, u16* outb, float* outf,
;                                              int row_begin, int row_end, int row_step, const int tidx) {
;     ...
;   for (int i = 0; i < 16; ++i) ggv[i] = *reinterpret_cast<const f32x4*>(g + i * 256 + lane * 4);
; #pragma unroll 1
;   for (int row = row_begin; row < row_end; row += row_step) {
;     const float* xr = xin + (size_t)row * DM;
;     f32x4 v[16];
;     float ss = 0.f;
; #pragma unroll
;     for (int i = 0; i < 16; ++i) {
;       v[i] = *reinterpret_cast<const f32x4*>(xr + i * 256 + lane * 4);
; __device__ __forceinline__ void phase_prep(const Params& p) {
;     ...
; #pragma unroll 1
;   for (;;) {
;     const int tid = opaque_tid();
;     __syncthreads();
;     if (tid == 0) s_pitem = atomicAdd(ctr, 1);
;     __syncthreads();
;     int it = s_pitem;
;     if (it >= N_SP + N_CV + N_RN) break;
;     if (it < N_SP) {
;       ssm_prep_item(p, it);
;     } else if (it < N_SP + N_CV) {
;       it -= N_SP;
;       if (it < CV_IN) cv_in(p, 0, it, tid);
;       else cv_pool(p, 0, it - CV_IN, tid);
;     } else {
;       int row = (it - N_SP - N_CV) * 8 + (tid >> 6);
;       rmsnorm_rows(p.x, p.ln_g, (u16*)(p.ws + WS_H), nullptr, row, row + 1, 1, tid);
.LBB0_258:
	s_or_b64 exec, exec, s[6:7]
	s_waitcnt lgkmcnt(0)
	s_barrier
	ds_read_b32 v0, v163 offset:16
	s_movk_i32 s6, 0x603
	s_waitcnt lgkmcnt(0)
	v_cmp_lt_i32_e32 vcc, s6, v0
	v_readfirstlane_b32 s16, v0
	s_mov_b64 s[6:7], -1
	s_cbranch_vccnz .LBB0_253
	s_cmpk_gt_i32 s16, 0x7f
	s_cbranch_scc0 .LBB0_272
	s_cmpk_gt_u32 s16, 0x203
	s_cbranch_scc0 .LBB0_262
	v_ashrrev_i32_e32 v0, 6, v130
	v_lshl_add_u32 v0, s16, 3, v0
	v_add_u32_e32 v132, 0xffffefe0, v0
	v_lshlrev_b32_e32 v0, 2, v130
	v_and_b32_e32 v97, 0xfc, v0
	v_readlane_b32 s64, v254, 33
	v_lshlrev_b32_e32 v162, 2, v97
	v_readlane_b32 s66, v254, 35
	v_readlane_b32 s67, v254, 36
	s_nop 4
	global_load_dwordx4 v[102:105], v162, s[66:67]
	global_load_dwordx4 v[98:101], v162, s[66:67] offset:1024
	global_load_dwordx4 v[88:91], v162, s[66:67] offset:2048
	global_load_dwordx4 v[80:83], v162, s[66:67] offset:3072
	v_lshl_add_u64 v[0:1], s[66:67], 0, v[162:163]
	v_add_co_u32_e32 v2, vcc, 0x1000, v0
	v_readlane_b32 s65, v254, 34
	s_nop 0
	v_addc_co_u32_e32 v3, vcc, 0, v1, vcc
	global_load_dwordx4 v[76:79], v[2:3], off
	global_load_dwordx4 v[68:71], v[2:3], off offset:1024
	global_load_dwordx4 v[56:59], v[2:3], off offset:2048
	global_load_dwordx4 v[40:43], v[2:3], off offset:3072
	v_add_co_u32_e32 v2, vcc, s51, v0
	v_ashrrev_i32_e32 v133, 31, v132
	s_nop 0
	v_addc_co_u32_e32 v3, vcc, 0, v1, vcc
	v_add_co_u32_e32 v0, vcc, s38, v0
	v_lshl_add_u64 v[24:25], s[64:65], 0, v[162:163]
	v_lshlrev_b64 v[26:27], 14, v[132:133]
	v_addc_co_u32_e32 v1, vcc, 0, v1, vcc
	v_lshl_add_u64 v[24:25], v[24:25], 0, v[26:27]
	v_add_co_u32_e32 v26, vcc, s56, v24
	global_load_dwordx4 v[32:35], v[2:3], off offset:1024
	global_load_dwordx4 v[20:23], v[2:3], off offset:2048
	global_load_dwordx4 v[16:19], v[2:3], off offset:3072
	global_load_dwordx4 v[44:47], v[0:1], off offset:-4096
	global_load_dwordx4 v[12:15], v[0:1], off
	global_load_dwordx4 v[8:11], v[0:1], off offset:1024
	global_load_dwordx4 v[4:7], v[0:1], off offset:2048
	s_nop 0
	global_load_dwordx4 v[0:3], v[0:1], off offset:3072
	v_addc_co_u32_e32 v27, vcc, 0, v25, vcc
	v_add_co_u32_e32 v28, vcc, s51, v24
	global_load_dwordx4 v[126:129], v[24:25], off
	global_load_dwordx4 v[122:125], v[24:25], off offset:1024
	global_load_dwordx4 v[118:121], v[24:25], off offset:2048
	global_load_dwordx4 v[114:117], v[24:25], off offset:3072
	v_addc_co_u32_e32 v29, vcc, 0, v25, vcc
	global_load_dwordx4 v[106:109], v[26:27], off offset:1024
	global_load_dwordx4 v[92:95], v[26:27], off offset:2048
	global_load_dwordx4 v[110:113], v[28:29], off offset:-4096
	global_load_dwordx4 v[72:75], v[28:29], off
	global_load_dwordx4 v[64:67], v[28:29], off offset:1024
	global_load_dwordx4 v[60:63], v[28:29], off offset:2048
	global_load_dwordx4 v[52:55], v[28:29], off offset:3072
	v_add_co_u32_e32 v24, vcc, s38, v24
	v_and_b32_e32 v131, 64, v215
	s_nop 0
	v_addc_co_u32_e32 v25, vcc, 0, v25, vcc
	global_load_dwordx4 v[84:87], v[26:27], off offset:3072
	global_load_dwordx4 v[48:51], v[24:25], off
	global_load_dwordx4 v[36:39], v[24:25], off offset:1024
	global_load_dwordx4 v[28:31], v[24:25], off offset:2048
	s_nop 0
	global_load_dwordx4 v[24:27], v[24:25], off offset:3072
	v_add_u32_e32 v131, 64, v131
	v_xor_b32_e32 v134, 32, v215
	v_cmp_lt_i32_e32 vcc, v134, v131
	s_mov_b64 s[54:55], 0x10040100
	s_mov_b64 s[60:61], 0x2e940180
	v_cndmask_b32_e32 v134, v215, v134, vcc
	v_lshlrev_b32_e32 v140, 2, v134
	v_xor_b32_e32 v134, 16, v215
	v_cmp_lt_i32_e32 vcc, v134, v131
	s_mov_b64 s[52:53], 0x10000180
	s_mov_b64 s[46:47], 0x2e900180
	v_cndmask_b32_e32 v134, v215, v134, vcc
	v_lshlrev_b32_e32 v141, 2, v134
	v_xor_b32_e32 v134, 8, v215
	v_cmp_lt_i32_e32 vcc, v134, v131
	s_mov_b64 s[96:97], 0x2e940100
	s_movk_i32 s33, 0x44
	v_cndmask_b32_e32 v134, v215, v134, vcc
	v_lshlrev_b32_e32 v142, 2, v134
	v_xor_b32_e32 v134, 4, v215
	v_cmp_lt_i32_e32 vcc, v134, v131
	s_movk_i32 s0, 0x3c0
	v_lshlrev_b32_e32 v162, 1, v97
	v_cndmask_b32_e32 v134, v215, v134, vcc
	v_lshlrev_b32_e32 v143, 2, v134
	v_xor_b32_e32 v134, 2, v215
	v_cmp_lt_i32_e32 vcc, v134, v131
	v_readlane_b32 s68, v254, 37
	v_readlane_b32 s69, v254, 38
	v_cndmask_b32_e32 v134, v215, v134, vcc
	v_lshlrev_b32_e32 v144, 2, v134
	v_xor_b32_e32 v134, 1, v215
	v_cmp_lt_i32_e32 vcc, v134, v131
	v_readlane_b32 s70, v254, 39
	v_readlane_b32 s71, v254, 40
	v_cndmask_b32_e32 v131, v215, v134, vcc
	v_readlane_b32 s72, v254, 41
	v_readlane_b32 s73, v254, 42
	v_readlane_b32 s74, v254, 43
	v_readlane_b32 s75, v254, 44
	v_readlane_b32 s76, v254, 45
	v_readlane_b32 s77, v254, 46
	v_readlane_b32 s78, v254, 47
	v_readlane_b32 s79, v254, 48
	v_lshlrev_b32_e32 v131, 2, v131
	v_lshl_add_u64 v[134:135], s[14:15], 0, v[162:163]
	s_waitcnt vmcnt(3)
	v_mov_b32_e32 v138, v49
	s_waitcnt vmcnt(2)
; __device__ __forceinline__ void rmsnorm_rows(const float* __restrict__ xin, const float* __restrict__ g, u16* outb, float* outf,
;                                              int row_begin, int row_end, int row_step, const int tidx) {
;     ...
; #pragma unroll
;     for (int i = 0; i < 16; ++i) ss += v[i][0] * v[i][0] + v[i][1] * v[i][1] + v[i][2] * v[i][2] + v[i][3] * v[i][3];
;     ss = wave_sum(ss);
;     float rs = rsqrtf(ss * (1.f / DM) + 1e-6f);
	v_mov_b32_e32 v139, v37
	v_mov_b32_e32 v136, v48
	v_mov_b32_e32 v137, v36
	v_pk_mul_f32 v[138:139], v[138:139], v[138:139]
	v_mul_f32_e32 v97, v127, v127
	v_pk_fma_f32 v[136:137], v[136:137], v[136:137], v[138:139]
	v_mov_b32_e32 v138, v50
	v_mov_b32_e32 v139, v38
	v_pk_fma_f32 v[136:137], v[138:139], v[138:139], v[136:137]
	v_mov_b32_e32 v138, v51
	v_mov_b32_e32 v139, v39
	v_pk_fma_f32 v[136:137], v[138:139], v[138:139], v[136:137]
	v_mul_f32_e32 v138, v123, v123
	v_fmac_f32_e32 v97, v126, v126
	v_fmac_f32_e32 v138, v122, v122
	v_fmac_f32_e32 v97, v128, v128
	v_fmac_f32_e32 v138, v124, v124
	v_fmac_f32_e32 v97, v129, v129
	v_fmac_f32_e32 v138, v125, v125
	v_add_f32_e32 v97, v97, v138
	v_mul_f32_e32 v138, v119, v119
	v_fmac_f32_e32 v138, v118, v118
	v_fmac_f32_e32 v138, v120, v120
	v_fmac_f32_e32 v138, v121, v121
	v_add_f32_e32 v97, v97, v138
	v_mul_f32_e32 v138, v115, v115
	v_fmac_f32_e32 v138, v114, v114
	v_fmac_f32_e32 v138, v116, v116
	v_fmac_f32_e32 v138, v117, v117
	v_add_f32_e32 v97, v97, v138
	v_mul_f32_e32 v138, v111, v111
	v_fmac_f32_e32 v138, v110, v110
	v_fmac_f32_e32 v138, v112, v112
	v_fmac_f32_e32 v138, v113, v113
	v_add_f32_e32 v97, v97, v138
	v_mul_f32_e32 v138, v107, v107
	v_fmac_f32_e32 v138, v106, v106
	v_fmac_f32_e32 v138, v108, v108
	v_fmac_f32_e32 v138, v109, v109
	v_add_f32_e32 v97, v97, v138
	v_mul_f32_e32 v138, v93, v93
	v_fmac_f32_e32 v138, v92, v92
	v_fmac_f32_e32 v138, v94, v94
	v_fmac_f32_e32 v138, v95, v95
	v_add_f32_e32 v97, v97, v138
	v_mul_f32_e32 v138, v85, v85
	v_fmac_f32_e32 v138, v84, v84
	v_fmac_f32_e32 v138, v86, v86
	v_fmac_f32_e32 v138, v87, v87
	v_add_f32_e32 v97, v97, v138
	v_mul_f32_e32 v138, v73, v73
	v_fmac_f32_e32 v138, v72, v72
	v_fmac_f32_e32 v138, v74, v74
	v_fmac_f32_e32 v138, v75, v75
	v_add_f32_e32 v97, v97, v138
	v_mul_f32_e32 v138, v65, v65
	v_fmac_f32_e32 v138, v64, v64
	v_fmac_f32_e32 v138, v66, v66
	v_fmac_f32_e32 v138, v67, v67
	v_add_f32_e32 v97, v97, v138
	v_mul_f32_e32 v138, v61, v61
	v_fmac_f32_e32 v138, v60, v60
	v_fmac_f32_e32 v138, v62, v62
	v_fmac_f32_e32 v138, v63, v63
	v_add_f32_e32 v97, v97, v138
	v_mul_f32_e32 v138, v53, v53
	v_fmac_f32_e32 v138, v52, v52
	v_fmac_f32_e32 v138, v54, v54
	v_fmac_f32_e32 v138, v55, v55
	v_add_f32_e32 v97, v97, v138
	v_add_f32_e32 v97, v97, v136
	s_waitcnt vmcnt(1)
	v_mov_b32_e32 v138, v29
	s_waitcnt vmcnt(0)
	v_mov_b32_e32 v139, v25
	v_add_f32_e32 v97, v97, v137
	v_mov_b32_e32 v136, v28
	v_mov_b32_e32 v137, v24
	v_pk_mul_f32 v[138:139], v[138:139], v[138:139]
	s_mov_b64 s[6:7], 0
	v_pk_fma_f32 v[136:137], v[136:137], v[136:137], v[138:139]
	v_mov_b32_e32 v138, v30
	v_mov_b32_e32 v139, v26
	v_pk_fma_f32 v[136:137], v[138:139], v[138:139], v[136:137]
	v_mov_b32_e32 v138, v31
	v_mov_b32_e32 v139, v27
	v_pk_fma_f32 v[136:137], v[138:139], v[138:139], v[136:137]
	s_nop 0
	v_add_f32_e32 v97, v97, v136
	v_add_f32_e32 v97, v97, v137
	ds_bpermute_b32 v136, v140, v97
	s_waitcnt lgkmcnt(0)
	v_add_f32_e32 v97, v97, v136
	ds_bpermute_b32 v136, v141, v97
	s_waitcnt lgkmcnt(0)
	v_add_f32_e32 v97, v97, v136
	ds_bpermute_b32 v136, v142, v97
	s_waitcnt lgkmcnt(0)
	v_add_f32_e32 v97, v97, v136
	ds_bpermute_b32 v136, v143, v97
	s_waitcnt lgkmcnt(0)
	v_add_f32_e32 v97, v97, v136
	ds_bpermute_b32 v136, v144, v97
	s_waitcnt lgkmcnt(0)
	v_add_f32_e32 v97, v97, v136
	ds_bpermute_b32 v131, v131, v97
	s_waitcnt lgkmcnt(0)
; __device__ __forceinline__ void rmsnorm_rows(const float* __restrict__ xin, const float* __restrict__ g, u16* outb, float* outf,
;                                              int row_begin, int row_end, int row_step, const int tidx) {
;     ...
;     float rs = rsqrtf(ss * (1.f / DM) + 1e-6f);
; #pragma unroll
;     for (int i = 0; i < 16; ++i) {
;       f32x4 o = v[i] * rs * ggv[i];
;       if (outb) {
;         u32x2 pk;
;         pk.x = pack2(o[0], o[1]);
;         pk.y = pack2(o[2], o[3]);
;         *reinterpret_cast<u32x2*>(outb + (size_t)row * DM + i * 256 + lane * 4) = pk;
;       } else {
;         *reinterpret_cast<f32x4*>(outf + (size_t)row * DM + i * 256 + lane * 4) = o;
;       }
;     }
	v_add_f32_e32 v97, v97, v131
	v_fmamk_f32 v97, v97, 0x39800000, v211
	v_mul_f32_e32 v131, 0x4b800000, v97
	v_cmp_gt_f32_e32 vcc, s1, v97
	s_nop 1
	v_cndmask_b32_e32 v97, v97, v131, vcc
	v_rsq_f32_e32 v97, v97
	s_nop 0
	v_mul_f32_e32 v131, 0x45800000, v97
	v_cndmask_b32_e32 v136, v97, v131, vcc
	v_pk_mul_f32 v[106:107], v[106:107], v[136:137] op_sel_hi:[1,0]
	v_pk_mul_f32 v[108:109], v[108:109], v[136:137] op_sel_hi:[1,0]
	v_pk_mul_f32 v[68:69], v[68:69], v[106:107]
	v_lshlrev_b64 v[106:107], 13, v[132:133]
	v_pk_mul_f32 v[70:71], v[70:71], v[108:109]
	v_lshl_add_u64 v[106:107], v[134:135], 0, v[106:107]
	v_cvt_pk_bf16_f32 v68, v68, v69
	v_cvt_pk_bf16_f32 v69, v70, v71
	global_store_dwordx2 v[106:107], v[68:69], off offset:2560 sc1
	v_pk_mul_f32 v[68:69], v[92:93], v[136:137] op_sel_hi:[1,0]
	v_pk_mul_f32 v[70:71], v[94:95], v[136:137] op_sel_hi:[1,0]
	v_pk_mul_f32 v[56:57], v[56:57], v[68:69]
	v_pk_mul_f32 v[58:59], v[58:59], v[70:71]
	v_cvt_pk_bf16_f32 v56, v56, v57
	v_pk_mul_f32 v[126:127], v[126:127], v[136:137] op_sel_hi:[1,0]
	v_cvt_pk_bf16_f32 v57, v58, v59
	global_store_dwordx2 v[106:107], v[56:57], off offset:3072 sc1
	v_pk_mul_f32 v[56:57], v[84:85], v[136:137] op_sel_hi:[1,0]
	v_pk_mul_f32 v[58:59], v[86:87], v[136:137] op_sel_hi:[1,0]
	v_pk_mul_f32 v[40:41], v[40:41], v[56:57]
	v_pk_mul_f32 v[42:43], v[42:43], v[58:59]
	v_cvt_pk_bf16_f32 v40, v40, v41
	v_pk_mul_f32 v[122:123], v[122:123], v[136:137] op_sel_hi:[1,0]
	v_cvt_pk_bf16_f32 v41, v42, v43
	global_store_dwordx2 v[106:107], v[40:41], off offset:3584 sc1
	v_pk_mul_f32 v[40:41], v[72:73], v[136:137] op_sel_hi:[1,0]
	v_pk_mul_f32 v[42:43], v[74:75], v[136:137] op_sel_hi:[1,0]
	v_pk_mul_f32 v[40:41], v[44:45], v[40:41]
	v_pk_mul_f32 v[42:43], v[46:47], v[42:43]
	v_cvt_pk_bf16_f32 v40, v40, v41
	v_pk_mul_f32 v[44:45], v[66:67], v[136:137] op_sel_hi:[1,0]
	v_cvt_pk_bf16_f32 v41, v42, v43
	v_add_co_u32_e32 v42, vcc, s56, v106
	v_pk_mul_f32 v[34:35], v[34:35], v[44:45]
	s_nop 0
	v_addc_co_u32_e32 v43, vcc, 0, v107, vcc
	global_store_dwordx2 v[42:43], v[40:41], off sc1
	v_pk_mul_f32 v[40:41], v[64:65], v[136:137] op_sel_hi:[1,0]
	v_pk_mul_f32 v[118:119], v[118:119], v[136:137] op_sel_hi:[1,0]
	v_pk_mul_f32 v[32:33], v[32:33], v[40:41]
	v_pk_mul_f32 v[114:115], v[114:115], v[136:137] op_sel_hi:[1,0]
	v_cvt_pk_bf16_f32 v32, v32, v33
	v_cvt_pk_bf16_f32 v33, v34, v35
	global_store_dwordx2 v[42:43], v[32:33], off offset:512 sc1
	v_pk_mul_f32 v[32:33], v[60:61], v[136:137] op_sel_hi:[1,0]
	v_pk_mul_f32 v[34:35], v[62:63], v[136:137] op_sel_hi:[1,0]
	v_pk_mul_f32 v[20:21], v[20:21], v[32:33]
	v_pk_mul_f32 v[22:23], v[22:23], v[34:35]
	v_cvt_pk_bf16_f32 v20, v20, v21
	v_pk_mul_f32 v[110:111], v[110:111], v[136:137] op_sel_hi:[1,0]
	v_cvt_pk_bf16_f32 v21, v22, v23
	global_store_dwordx2 v[42:43], v[20:21], off offset:1024 sc1
	v_pk_mul_f32 v[20:21], v[52:53], v[136:137] op_sel_hi:[1,0]
	v_pk_mul_f32 v[22:23], v[54:55], v[136:137] op_sel_hi:[1,0]
	v_pk_mul_f32 v[16:17], v[16:17], v[20:21]
	v_pk_mul_f32 v[18:19], v[18:19], v[22:23]
	v_cvt_pk_bf16_f32 v16, v16, v17
	v_pk_mul_f32 v[128:129], v[128:129], v[136:137] op_sel_hi:[1,0]
	v_cvt_pk_bf16_f32 v17, v18, v19
	global_store_dwordx2 v[42:43], v[16:17], off offset:1536 sc1
	v_pk_mul_f32 v[16:17], v[48:49], v[136:137] op_sel_hi:[1,0]
	v_pk_mul_f32 v[18:19], v[50:51], v[136:137] op_sel_hi:[1,0]
	v_pk_mul_f32 v[12:13], v[12:13], v[16:17]
	v_pk_mul_f32 v[14:15], v[14:15], v[18:19]
	v_cvt_pk_bf16_f32 v12, v12, v13
	v_pk_mul_f32 v[102:103], v[102:103], v[126:127]
	v_cvt_pk_bf16_f32 v13, v14, v15
	global_store_dwordx2 v[42:43], v[12:13], off offset:2048 sc1
	v_pk_mul_f32 v[12:13], v[36:37], v[136:137] op_sel_hi:[1,0]
	v_pk_mul_f32 v[14:15], v[38:39], v[136:137] op_sel_hi:[1,0]
	v_pk_mul_f32 v[8:9], v[8:9], v[12:13]
	v_pk_mul_f32 v[10:11], v[10:11], v[14:15]
	v_cvt_pk_bf16_f32 v8, v8, v9
	v_pk_mul_f32 v[124:125], v[124:125], v[136:137] op_sel_hi:[1,0]
	v_cvt_pk_bf16_f32 v9, v10, v11
	global_store_dwordx2 v[42:43], v[8:9], off offset:2560 sc1
	v_pk_mul_f32 v[8:9], v[28:29], v[136:137] op_sel_hi:[1,0]
	v_pk_mul_f32 v[10:11], v[30:31], v[136:137] op_sel_hi:[1,0]
	v_pk_mul_f32 v[4:5], v[4:5], v[8:9]
	v_pk_mul_f32 v[6:7], v[6:7], v[10:11]
	v_cvt_pk_bf16_f32 v4, v4, v5
	v_pk_mul_f32 v[98:99], v[98:99], v[122:123]
	v_cvt_pk_bf16_f32 v5, v6, v7
	global_store_dwordx2 v[42:43], v[4:5], off offset:3072 sc1
	v_pk_mul_f32 v[4:5], v[24:25], v[136:137] op_sel_hi:[1,0]
	v_pk_mul_f32 v[120:121], v[120:121], v[136:137] op_sel_hi:[1,0]
	v_pk_mul_f32 v[88:89], v[88:89], v[118:119]
	v_pk_mul_f32 v[116:117], v[116:117], v[136:137] op_sel_hi:[1,0]
	v_pk_mul_f32 v[80:81], v[80:81], v[114:115]
	v_pk_mul_f32 v[112:113], v[112:113], v[136:137] op_sel_hi:[1,0]
	v_pk_mul_f32 v[76:77], v[76:77], v[110:111]
	v_pk_mul_f32 v[6:7], v[26:27], v[136:137] op_sel_hi:[1,0]
	v_pk_mul_f32 v[0:1], v[0:1], v[4:5]
	v_pk_mul_f32 v[104:105], v[104:105], v[128:129]
	v_pk_mul_f32 v[100:101], v[100:101], v[124:125]
	v_pk_mul_f32 v[90:91], v[90:91], v[120:121]
	v_pk_mul_f32 v[82:83], v[82:83], v[116:117]
	v_pk_mul_f32 v[78:79], v[78:79], v[112:113]
	v_cvt_pk_bf16_f32 v102, v102, v103
	v_cvt_pk_bf16_f32 v103, v104, v105
	global_store_dwordx2 v[106:107], v[102:103], off sc1
	v_cvt_pk_bf16_f32 v98, v98, v99
	v_cvt_pk_bf16_f32 v99, v100, v101
	global_store_dwordx2 v[106:107], v[98:99], off offset:512 sc1
	v_cvt_pk_bf16_f32 v88, v88, v89
	v_cvt_pk_bf16_f32 v89, v90, v91
	global_store_dwordx2 v[106:107], v[88:89], off offset:1024 sc1
	v_cvt_pk_bf16_f32 v80, v80, v81
	v_cvt_pk_bf16_f32 v81, v82, v83
	global_store_dwordx2 v[106:107], v[80:81], off offset:1536 sc1
	v_cvt_pk_bf16_f32 v76, v76, v77
	v_cvt_pk_bf16_f32 v77, v78, v79
	global_store_dwordx2 v[106:107], v[76:77], off offset:2048 sc1
	v_pk_mul_f32 v[2:3], v[2:3], v[6:7]
	v_cvt_pk_bf16_f32 v0, v0, v1
	s_nop 0
	v_cvt_pk_bf16_f32 v1, v2, v3
	global_store_dwordx2 v[42:43], v[0:1], off offset:3584 sc1

; __device__ __forceinline__ void convert_item(const float* __restrict__ src, int Ksz, int Nsz, u16* __restrict__ dst, int kb, int nb,
;                                              int mode, const int tid) {
;   const int n = nb * NTHR + tid;
;   if (n < Nsz) {
;     const float* sp = src + (size_t)(kb * 64) * Nsz + n;
;     float v[64];
; #pragma unroll
;     for (int j = 0; j < 64; ++j) v[j] = sp[(size_t)j * Nsz];
;     int nd = n;
;     if (mode == 1) {
;       int isg = n >= 1024, c = n & 1023;
;       nd = (c >> 7) * 256 + isg * 128 + (c & 127);
;     }
;     u32x4* d = reinterpret_cast<u32x4*>(dst + (size_t)nd * Ksz + kb * 64);
.Lcvp_nd:
	s_lshl_b32 s74, s69, 1
	s_lshl_b32 s75, s73, 1
	s_add_u32 s66, s66, s75
	s_addc_u32 s67, s67, 0
	s_lshl_b32 s6, s74, 3
	s_mov_b32 s7, 0
	v_mov_b32_e32 v86, s66
	v_mov_b32_e32 v87, s67
	v_mov_b32_e32 v88, s74
	v_mad_u64_u32 v[90:91], vcc, v84, v88, v[86:87]
	v_and_b32_e32 v0, 7, v130
	v_lshlrev_b32_e32 v0, 4, v0
	v_add_co_u32_e32 v84, vcc, v90, v0
	s_nop 1
	v_addc_co_u32_e32 v85, vcc, 0, v91, vcc
	v_lshlrev_b32_e32 v1, 2, v130
	v_lshrrev_b32_e32 v2, 6, v130
	v_mul_u32_u24_e32 v2, 0x2400, v2
	v_and_b32_e32 v3, 63, v130
	v_lshrrev_b32_e32 v89, 3, v3
	v_mul_u32_u24_e32 v89, 0x90, v89
	v_add3_u32 v89, v89, v0, v2
	v_mul_u32_u24_e32 v3, 0x90, v3
	v_add3_u32 v2, v2, v3, 32
	v_add_u32_e32 v3, 32, v89
	global_load_dword v4, v1, s[8:9]
	s_add_u32 s8, s8, s10
	s_addc_u32 s9, s9, 0
	global_load_dword v5, v1, s[8:9]
	s_add_u32 s8, s8, s10
	s_addc_u32 s9, s9, 0
	global_load_dword v6, v1, s[8:9]
	s_add_u32 s8, s8, s10
	s_addc_u32 s9, s9, 0
	global_load_dword v7, v1, s[8:9]
	s_add_u32 s8, s8, s10
	s_addc_u32 s9, s9, 0
	global_load_dword v8, v1, s[8:9]
	s_add_u32 s8, s8, s10
	s_addc_u32 s9, s9, 0
	global_load_dword v9, v1, s[8:9]
	s_add_u32 s8, s8, s10
	s_addc_u32 s9, s9, 0
	global_load_dword v10, v1, s[8:9]
	s_add_u32 s8, s8, s10
	s_addc_u32 s9, s9, 0
	global_load_dword v11, v1, s[8:9]
	s_add_u32 s8, s8, s10
	s_addc_u32 s9, s9, 0
	global_load_dword v12, v1, s[8:9]
	s_add_u32 s8, s8, s10
	s_addc_u32 s9, s9, 0
	global_load_dword v13, v1, s[8:9]
	s_add_u32 s8, s8, s10
	s_addc_u32 s9, s9, 0
	global_load_dword v14, v1, s[8:9]
	s_add_u32 s8, s8, s10
	s_addc_u32 s9, s9, 0
	global_load_dword v15, v1, s[8:9]
	s_add_u32 s8, s8, s10
	s_addc_u32 s9, s9, 0
	global_load_dword v16, v1, s[8:9]
	s_add_u32 s8, s8, s10
	s_addc_u32 s9, s9, 0
	global_load_dword v17, v1, s[8:9]
	s_add_u32 s8, s8, s10
	s_addc_u32 s9, s9, 0
	global_load_dword v18, v1, s[8:9]
	s_add_u32 s8, s8, s10
	s_addc_u32 s9, s9, 0
	global_load_dword v19, v1, s[8:9]
	s_add_u32 s8, s8, s10
	s_addc_u32 s9, s9, 0
	global_load_dword v20, v1, s[8:9]
	s_add_u32 s8, s8, s10
	s_addc_u32 s9, s9, 0
	global_load_dword v21, v1, s[8:9]
	s_add_u32 s8, s8, s10
	s_addc_u32 s9, s9, 0
	global_load_dword v22, v1, s[8:9]
	s_add_u32 s8, s8, s10
	s_addc_u32 s9, s9, 0
	global_load_dword v23, v1, s[8:9]
	s_add_u32 s8, s8, s10
	s_addc_u32 s9, s9, 0
	global_load_dword v24, v1, s[8:9]
	s_add_u32 s8, s8, s10
	s_addc_u32 s9, s9, 0
	global_load_dword v25, v1, s[8:9]
	s_add_u32 s8, s8, s10
	s_addc_u32 s9, s9, 0
	global_load_dword v26, v1, s[8:9]
	s_add_u32 s8, s8, s10
	s_addc_u32 s9, s9, 0
	global_load_dword v27, v1, s[8:9]
	s_add_u32 s8, s8, s10
	s_addc_u32 s9, s9, 0
	global_load_dword v28, v1, s[8:9]
	s_add_u32 s8, s8, s10
	s_addc_u32 s9, s9, 0
	global_load_dword v29, v1, s[8:9]
	s_add_u32 s8, s8, s10
	s_addc_u32 s9, s9, 0
	global_load_dword v30, v1, s[8:9]
	s_add_u32 s8, s8, s10
	s_addc_u32 s9, s9, 0
	global_load_dword v31, v1, s[8:9]
	s_add_u32 s8, s8, s10
	s_addc_u32 s9, s9, 0
	global_load_dword v32, v1, s[8:9]
	s_add_u32 s8, s8, s10
	s_addc_u32 s9, s9, 0
	global_load_dword v33, v1, s[8:9]
	s_add_u32 s8, s8, s10
	s_addc_u32 s9, s9, 0
	global_load_dword v34, v1, s[8:9]
	s_add_u32 s8, s8, s10
	s_addc_u32 s9, s9, 0
	global_load_dword v35, v1, s[8:9]
	s_add_u32 s8, s8, s10
	s_addc_u32 s9, s9, 0
	global_load_dword v36, v1, s[8:9]
	s_add_u32 s8, s8, s10
	s_addc_u32 s9, s9, 0
	global_load_dword v37, v1, s[8:9]
	s_add_u32 s8, s8, s10
	s_addc_u32 s9, s9, 0
	global_load_dword v38, v1, s[8:9]
	s_add_u32 s8, s8, s10
	s_addc_u32 s9, s9, 0
	global_load_dword v39, v1, s[8:9]
	s_add_u32 s8, s8, s10
	s_addc_u32 s9, s9, 0
	global_load_dword v40, v1, s[8:9]
	s_add_u32 s8, s8, s10
	s_addc_u32 s9, s9, 0
	global_load_dword v41, v1, s[8:9]
	s_add_u32 s8, s8, s10
	s_addc_u32 s9, s9, 0
	global_load_dword v42, v1, s[8:9]
	s_add_u32 s8, s8, s10
	s_addc_u32 s9, s9, 0
	global_load_dword v43, v1, s[8:9]
	s_add_u32 s8, s8, s10
	s_addc_u32 s9, s9, 0
	global_load_dword v44, v1, s[8:9]
	s_add_u32 s8, s8, s10
	s_addc_u32 s9, s9, 0
	global_load_dword v45, v1, s[8:9]
	s_add_u32 s8, s8, s10
	s_addc_u32 s9, s9, 0
	global_load_dword v46, v1, s[8:9]
	s_add_u32 s8, s8, s10
	s_addc_u32 s9, s9, 0
	global_load_dword v47, v1, s[8:9]
	s_add_u32 s8, s8, s10
	s_addc_u32 s9, s9, 0
	global_load_dword v48, v1, s[8:9]
	s_add_u32 s8, s8, s10
	s_addc_u32 s9, s9, 0
	global_load_dword v49, v1, s[8:9]
	s_add_u32 s8, s8, s10
	s_addc_u32 s9, s9, 0
	global_load_dword v50, v1, s[8:9]
	s_add_u32 s8, s8, s10
	s_addc_u32 s9, s9, 0
	global_load_dword v51, v1, s[8:9]
	s_add_u32 s8, s8, s10
	s_addc_u32 s9, s9, 0
	global_load_dword v52, v1, s[8:9]
	s_add_u32 s8, s8, s10
	s_addc_u32 s9, s9, 0
	global_load_dword v53, v1, s[8:9]
	s_add_u32 s8, s8, s10
	s_addc_u32 s9, s9, 0
	global_load_dword v54, v1, s[8:9]
	s_add_u32 s8, s8, s10
	s_addc_u32 s9, s9, 0
	global_load_dword v55, v1, s[8:9]
	s_add_u32 s8, s8, s10
	s_addc_u32 s9, s9, 0
	global_load_dword v56, v1, s[8:9]
	s_add_u32 s8, s8, s10
	s_addc_u32 s9, s9, 0
	global_load_dword v57, v1, s[8:9]
	s_add_u32 s8, s8, s10
	s_addc_u32 s9, s9, 0
	global_load_dword v58, v1, s[8:9]
	s_add_u32 s8, s8, s10
	s_addc_u32 s9, s9, 0
	global_load_dword v59, v1, s[8:9]
	s_add_u32 s8, s8, s10
	s_addc_u32 s9, s9, 0
	global_load_dword v60, v1, s[8:9]
	s_add_u32 s8, s8, s10
	s_addc_u32 s9, s9, 0
	global_load_dword v61, v1, s[8:9]
	s_add_u32 s8, s8, s10
	s_addc_u32 s9, s9, 0
	global_load_dword v62, v1, s[8:9]
	s_add_u32 s8, s8, s10
	s_addc_u32 s9, s9, 0
	global_load_dword v63, v1, s[8:9]
	s_add_u32 s8, s8, s10
	s_addc_u32 s9, s9, 0
	global_load_dword v64, v1, s[8:9]
	s_add_u32 s8, s8, s10
	s_addc_u32 s9, s9, 0
	global_load_dword v65, v1, s[8:9]
	s_add_u32 s8, s8, s10
	s_addc_u32 s9, s9, 0
	global_load_dword v66, v1, s[8:9]
	s_add_u32 s8, s8, s10
	s_addc_u32 s9, s9, 0
	global_load_dword v67, v1, s[8:9]
	s_add_u32 s8, s8, s10
	s_addc_u32 s9, s9, 0
	s_waitcnt vmcnt(32)
; __device__ __forceinline__ void convert_item(const float* __restrict__ src, int Ksz, int Nsz, u16* __restrict__ dst, int kb, int nb,
;                                              int mode, const int tid) {
;   const int n = nb * NTHR + tid;
;   if (n < Nsz) {
;     const float* sp = src + (size_t)(kb * 64) * Nsz + n;
;     float v[64];
; #pragma unroll
;     for (int j = 0; j < 64; ++j) v[j] = sp[(size_t)j * Nsz];
;     int nd = n;
;     if (mode == 1) {
;       int isg = n >= 1024, c = n & 1023;
;       nd = (c >> 7) * 256 + isg * 128 + (c & 127);
;     }
;     u32x4* d = reinterpret_cast<u32x4*>(dst + (size_t)nd * Ksz + kb * 64);
; #pragma unroll
;     for (int q = 0; q < 8; ++q) {
;       u32x4 o;
;       o.x = pack2(v[q * 8 + 0], v[q * 8 + 1]);
;       o.y = pack2(v[q * 8 + 2], v[q * 8 + 3]);
;       o.z = pack2(v[q * 8 + 4], v[q * 8 + 5]);
;       o.w = pack2(v[q * 8 + 6], v[q * 8 + 7]);
;       d[q] = o;
;     }
	v_cvt_pk_bf16_f32 v68, v4, v5
	v_cvt_pk_bf16_f32 v69, v6, v7
	v_cvt_pk_bf16_f32 v70, v8, v9
	v_cvt_pk_bf16_f32 v71, v10, v11
	v_cvt_pk_bf16_f32 v72, v12, v13
	v_cvt_pk_bf16_f32 v73, v14, v15
	v_cvt_pk_bf16_f32 v74, v16, v17
	v_cvt_pk_bf16_f32 v75, v18, v19
	v_cvt_pk_bf16_f32 v76, v20, v21
	v_cvt_pk_bf16_f32 v77, v22, v23
	v_cvt_pk_bf16_f32 v78, v24, v25
	v_cvt_pk_bf16_f32 v79, v26, v27
	v_cvt_pk_bf16_f32 v80, v28, v29
	v_cvt_pk_bf16_f32 v81, v30, v31
	v_cvt_pk_bf16_f32 v82, v32, v33
	v_cvt_pk_bf16_f32 v83, v34, v35
	ds_write_b128 v2, v[68:71] offset:0
	ds_write_b128 v2, v[72:75] offset:16
	ds_write_b128 v2, v[76:79] offset:32
	ds_write_b128 v2, v[80:83] offset:48
	global_load_dword v4, v1, s[8:9]
	s_add_u32 s8, s8, s10
	s_addc_u32 s9, s9, 0
	global_load_dword v5, v1, s[8:9]
	s_add_u32 s8, s8, s10
	s_addc_u32 s9, s9, 0
	global_load_dword v6, v1, s[8:9]
	s_add_u32 s8, s8, s10
	s_addc_u32 s9, s9, 0
	global_load_dword v7, v1, s[8:9]
	s_add_u32 s8, s8, s10
	s_addc_u32 s9, s9, 0
	global_load_dword v8, v1, s[8:9]
	s_add_u32 s8, s8, s10
	s_addc_u32 s9, s9, 0
	global_load_dword v9, v1, s[8:9]
	s_add_u32 s8, s8, s10
	s_addc_u32 s9, s9, 0
	global_load_dword v10, v1, s[8:9]
	s_add_u32 s8, s8, s10
	s_addc_u32 s9, s9, 0
	global_load_dword v11, v1, s[8:9]
	s_add_u32 s8, s8, s10
	s_addc_u32 s9, s9, 0
	global_load_dword v12, v1, s[8:9]
	s_add_u32 s8, s8, s10
	s_addc_u32 s9, s9, 0
	global_load_dword v13, v1, s[8:9]
	s_add_u32 s8, s8, s10
	s_addc_u32 s9, s9, 0
	global_load_dword v14, v1, s[8:9]
	s_add_u32 s8, s8, s10
	s_addc_u32 s9, s9, 0
	global_load_dword v15, v1, s[8:9]
	s_add_u32 s8, s8, s10
	s_addc_u32 s9, s9, 0
	global_load_dword v16, v1, s[8:9]
	s_add_u32 s8, s8, s10
	s_addc_u32 s9, s9, 0
	global_load_dword v17, v1, s[8:9]
	s_add_u32 s8, s8, s10
	s_addc_u32 s9, s9, 0
	global_load_dword v18, v1, s[8:9]
	s_add_u32 s8, s8, s10
	s_addc_u32 s9, s9, 0
	global_load_dword v19, v1, s[8:9]
	s_add_u32 s8, s8, s10
	s_addc_u32 s9, s9, 0
	global_load_dword v20, v1, s[8:9]
	s_add_u32 s8, s8, s10
	s_addc_u32 s9, s9, 0
	global_load_dword v21, v1, s[8:9]
	s_add_u32 s8, s8, s10
	s_addc_u32 s9, s9, 0
	global_load_dword v22, v1, s[8:9]
	s_add_u32 s8, s8, s10
	s_addc_u32 s9, s9, 0
	global_load_dword v23, v1, s[8:9]
	s_add_u32 s8, s8, s10
	s_addc_u32 s9, s9, 0
	global_load_dword v24, v1, s[8:9]
	s_add_u32 s8, s8, s10
	s_addc_u32 s9, s9, 0
	global_load_dword v25, v1, s[8:9]
	s_add_u32 s8, s8, s10
	s_addc_u32 s9, s9, 0
	global_load_dword v26, v1, s[8:9]
	s_add_u32 s8, s8, s10
	s_addc_u32 s9, s9, 0
	global_load_dword v27, v1, s[8:9]
	s_add_u32 s8, s8, s10
	s_addc_u32 s9, s9, 0
	global_load_dword v28, v1, s[8:9]
	s_add_u32 s8, s8, s10
	s_addc_u32 s9, s9, 0
	global_load_dword v29, v1, s[8:9]
	s_add_u32 s8, s8, s10
	s_addc_u32 s9, s9, 0
	global_load_dword v30, v1, s[8:9]
	s_add_u32 s8, s8, s10
	s_addc_u32 s9, s9, 0
	global_load_dword v31, v1, s[8:9]
	s_add_u32 s8, s8, s10
	s_addc_u32 s9, s9, 0
	global_load_dword v32, v1, s[8:9]
	s_add_u32 s8, s8, s10
	s_addc_u32 s9, s9, 0
	global_load_dword v33, v1, s[8:9]
	s_add_u32 s8, s8, s10
	s_addc_u32 s9, s9, 0
	global_load_dword v34, v1, s[8:9]
	s_add_u32 s8, s8, s10
	s_addc_u32 s9, s9, 0
	global_load_dword v35, v1, s[8:9]
	s_add_u32 s8, s8, s10
	s_addc_u32 s9, s9, 0
	s_waitcnt vmcnt(32)
	v_cvt_pk_bf16_f32 v100, v36, v37
	v_cvt_pk_bf16_f32 v101, v38, v39
	v_cvt_pk_bf16_f32 v102, v40, v41
	v_cvt_pk_bf16_f32 v103, v42, v43
	v_cvt_pk_bf16_f32 v104, v44, v45
	v_cvt_pk_bf16_f32 v105, v46, v47
	v_cvt_pk_bf16_f32 v106, v48, v49
	v_cvt_pk_bf16_f32 v107, v50, v51
	v_cvt_pk_bf16_f32 v108, v52, v53
	v_cvt_pk_bf16_f32 v109, v54, v55
	v_cvt_pk_bf16_f32 v110, v56, v57
	v_cvt_pk_bf16_f32 v111, v58, v59
	v_cvt_pk_bf16_f32 v112, v60, v61
	v_cvt_pk_bf16_f32 v113, v62, v63
	v_cvt_pk_bf16_f32 v114, v64, v65
	v_cvt_pk_bf16_f32 v115, v66, v67
	ds_write_b128 v2, v[100:103] offset:64
	ds_write_b128 v2, v[104:107] offset:80
	ds_write_b128 v2, v[108:111] offset:96
	ds_write_b128 v2, v[112:115] offset:112
	global_load_dword v36, v1, s[8:9]
	s_add_u32 s8, s8, s10
	s_addc_u32 s9, s9, 0
	global_load_dword v37, v1, s[8:9]
	s_add_u32 s8, s8, s10
	s_addc_u32 s9, s9, 0
	global_load_dword v38, v1, s[8:9]
	s_add_u32 s8, s8, s10
	s_addc_u32 s9, s9, 0
	global_load_dword v39, v1, s[8:9]
	s_add_u32 s8, s8, s10
	s_addc_u32 s9, s9, 0
	global_load_dword v40, v1, s[8:9]
	s_add_u32 s8, s8, s10
	s_addc_u32 s9, s9, 0
	global_load_dword v41, v1, s[8:9]
	s_add_u32 s8, s8, s10
	s_addc_u32 s9, s9, 0
	global_load_dword v42, v1, s[8:9]
	s_add_u32 s8, s8, s10
	s_addc_u32 s9, s9, 0
	global_load_dword v43, v1, s[8:9]
	s_add_u32 s8, s8, s10
	s_addc_u32 s9, s9, 0
	global_load_dword v44, v1, s[8:9]
	s_add_u32 s8, s8, s10
	s_addc_u32 s9, s9, 0
	global_load_dword v45, v1, s[8:9]
	s_add_u32 s8, s8, s10
	s_addc_u32 s9, s9, 0
	global_load_dword v46, v1, s[8:9]
	s_add_u32 s8, s8, s10
	s_addc_u32 s9, s9, 0
	global_load_dword v47, v1, s[8:9]
	s_add_u32 s8, s8, s10
	s_addc_u32 s9, s9, 0
	global_load_dword v48, v1, s[8:9]
	s_add_u32 s8, s8, s10
	s_addc_u32 s9, s9, 0
	global_load_dword v49, v1, s[8:9]
	s_add_u32 s8, s8, s10
	s_addc_u32 s9, s9, 0
	global_load_dword v50, v1, s[8:9]
	s_add_u32 s8, s8, s10
	s_addc_u32 s9, s9, 0
	global_load_dword v51, v1, s[8:9]
	s_add_u32 s8, s8, s10
	s_addc_u32 s9, s9, 0
	global_load_dword v52, v1, s[8:9]
	s_add_u32 s8, s8, s10
	s_addc_u32 s9, s9, 0
	global_load_dword v53, v1, s[8:9]
	s_add_u32 s8, s8, s10
	s_addc_u32 s9, s9, 0
	global_load_dword v54, v1, s[8:9]
	s_add_u32 s8, s8, s10
	s_addc_u32 s9, s9, 0
	global_load_dword v55, v1, s[8:9]
	s_add_u32 s8, s8, s10
	s_addc_u32 s9, s9, 0
	global_load_dword v56, v1, s[8:9]
	s_add_u32 s8, s8, s10
	s_addc_u32 s9, s9, 0
	global_load_dword v57, v1, s[8:9]
	s_add_u32 s8, s8, s10
	s_addc_u32 s9, s9, 0
	global_load_dword v58, v1, s[8:9]
	s_add_u32 s8, s8, s10
	s_addc_u32 s9, s9, 0
	global_load_dword v59, v1, s[8:9]
	s_add_u32 s8, s8, s10
	s_addc_u32 s9, s9, 0
	global_load_dword v60, v1, s[8:9]
	s_add_u32 s8, s8, s10
	s_addc_u32 s9, s9, 0
	global_load_dword v61, v1, s[8:9]
	s_add_u32 s8, s8, s10
	s_addc_u32 s9, s9, 0
	global_load_dword v62, v1, s[8:9]
	s_add_u32 s8, s8, s10
	s_addc_u32 s9, s9, 0
	global_load_dword v63, v1, s[8:9]
	s_add_u32 s8, s8, s10
	s_addc_u32 s9, s9, 0
	global_load_dword v64, v1, s[8:9]
	s_add_u32 s8, s8, s10
	s_addc_u32 s9, s9, 0
	global_load_dword v65, v1, s[8:9]
	s_add_u32 s8, s8, s10
	s_addc_u32 s9, s9, 0
	global_load_dword v66, v1, s[8:9]
	s_add_u32 s8, s8, s10
	s_addc_u32 s9, s9, 0
	global_load_dword v67, v1, s[8:9]
	s_add_u32 s8, s8, s10
	s_addc_u32 s9, s9, 0
	v_mov_b32_e32 v86, v84
	v_mov_b32_e32 v87, v85
	ds_read_b128 v[116:119], v3 offset:0
	ds_read_b128 v[120:123], v3 offset:1152
	ds_read_b128 v[124:127], v3 offset:2304
	ds_read_b128 v[128:131], v3 offset:3456
	s_waitcnt lgkmcnt(0)
; __device__ __forceinline__ void convert_item(const float* __restrict__ src, int Ksz, int Nsz, u16* __restrict__ dst, int kb, int nb,
;                                              int mode, const int tid) {
;   const int n = nb * NTHR + tid;
;   if (n < Nsz) {
;     const float* sp = src + (size_t)(kb * 64) * Nsz + n;
;     float v[64];
; #pragma unroll
;     for (int j = 0; j < 64; ++j) v[j] = sp[(size_t)j * Nsz];
;     int nd = n;
;     if (mode == 1) {
;       int isg = n >= 1024, c = n & 1023;
;       nd = (c >> 7) * 256 + isg * 128 + (c & 127);
;     }
;     u32x4* d = reinterpret_cast<u32x4*>(dst + (size_t)nd * Ksz + kb * 64);
; #pragma unroll
;     for (int q = 0; q < 8; ++q) {
;       u32x4 o;
;       o.x = pack2(v[q * 8 + 0], v[q * 8 + 1]);
;       o.y = pack2(v[q * 8 + 2], v[q * 8 + 3]);
;       o.z = pack2(v[q * 8 + 4], v[q * 8 + 5]);
;       o.w = pack2(v[q * 8 + 6], v[q * 8 + 7]);
;       d[q] = o;
;     }
	global_store_dwordx4 v[86:87], v[116:119], off offset:0 sc1
	v_lshl_add_u64 v[86:87], v[86:87], 0, s[6:7]
	global_store_dwordx4 v[86:87], v[120:123], off offset:0 sc1
	v_lshl_add_u64 v[86:87], v[86:87], 0, s[6:7]
	global_store_dwordx4 v[86:87], v[124:127], off offset:0 sc1
	v_lshl_add_u64 v[86:87], v[86:87], 0, s[6:7]
	global_store_dwordx4 v[86:87], v[128:131], off offset:0 sc1
	v_lshl_add_u64 v[86:87], v[86:87], 0, s[6:7]
	ds_read_b128 v[116:119], v3 offset:4608
	ds_read_b128 v[120:123], v3 offset:5760
	ds_read_b128 v[124:127], v3 offset:6912
	ds_read_b128 v[128:131], v3 offset:8064
	s_waitcnt lgkmcnt(0)
	global_store_dwordx4 v[86:87], v[116:119], off offset:0 sc1
	v_lshl_add_u64 v[86:87], v[86:87], 0, s[6:7]
	global_store_dwordx4 v[86:87], v[120:123], off offset:0 sc1
	v_lshl_add_u64 v[86:87], v[86:87], 0, s[6:7]
	global_store_dwordx4 v[86:87], v[124:127], off offset:0 sc1
	v_lshl_add_u64 v[86:87], v[86:87], 0, s[6:7]
	global_store_dwordx4 v[86:87], v[128:131], off offset:0 sc1
	v_lshl_add_u64 v[86:87], v[86:87], 0, s[6:7]
	s_waitcnt vmcnt(40)
	v_cvt_pk_bf16_f32 v68, v4, v5
	v_cvt_pk_bf16_f32 v69, v6, v7
	v_cvt_pk_bf16_f32 v70, v8, v9
	v_cvt_pk_bf16_f32 v71, v10, v11
	v_cvt_pk_bf16_f32 v72, v12, v13
	v_cvt_pk_bf16_f32 v73, v14, v15
	v_cvt_pk_bf16_f32 v74, v16, v17
	v_cvt_pk_bf16_f32 v75, v18, v19
	v_cvt_pk_bf16_f32 v76, v20, v21
	v_cvt_pk_bf16_f32 v77, v22, v23
	v_cvt_pk_bf16_f32 v78, v24, v25
	v_cvt_pk_bf16_f32 v79, v26, v27
	v_cvt_pk_bf16_f32 v80, v28, v29
	v_cvt_pk_bf16_f32 v81, v30, v31
	v_cvt_pk_bf16_f32 v82, v32, v33
	v_cvt_pk_bf16_f32 v83, v34, v35
	ds_write_b128 v2, v[68:71] offset:0
	ds_write_b128 v2, v[72:75] offset:16
	ds_write_b128 v2, v[76:79] offset:32
	ds_write_b128 v2, v[80:83] offset:48
	global_load_dword v4, v1, s[8:9]
	s_add_u32 s8, s8, s10
	s_addc_u32 s9, s9, 0
	global_load_dword v5, v1, s[8:9]
	s_add_u32 s8, s8, s10
	s_addc_u32 s9, s9, 0
	global_load_dword v6, v1, s[8:9]
	s_add_u32 s8, s8, s10
	s_addc_u32 s9, s9, 0
	global_load_dword v7, v1, s[8:9]
	s_add_u32 s8, s8, s10
	s_addc_u32 s9, s9, 0
	global_load_dword v8, v1, s[8:9]
	s_add_u32 s8, s8, s10
	s_addc_u32 s9, s9, 0
	global_load_dword v9, v1, s[8:9]
	s_add_u32 s8, s8, s10
	s_addc_u32 s9, s9, 0
	global_load_dword v10, v1, s[8:9]
	s_add_u32 s8, s8, s10
	s_addc_u32 s9, s9, 0
	global_load_dword v11, v1, s[8:9]
	s_add_u32 s8, s8, s10
	s_addc_u32 s9, s9, 0
	global_load_dword v12, v1, s[8:9]
	s_add_u32 s8, s8, s10
	s_addc_u32 s9, s9, 0
	global_load_dword v13, v1, s[8:9]
	s_add_u32 s8, s8, s10
	s_addc_u32 s9, s9, 0
	global_load_dword v14, v1, s[8:9]
	s_add_u32 s8, s8, s10
	s_addc_u32 s9, s9, 0
	global_load_dword v15, v1, s[8:9]
	s_add_u32 s8, s8, s10
	s_addc_u32 s9, s9, 0
	global_load_dword v16, v1, s[8:9]
	s_add_u32 s8, s8, s10
	s_addc_u32 s9, s9, 0
	global_load_dword v17, v1, s[8:9]
	s_add_u32 s8, s8, s10
	s_addc_u32 s9, s9, 0
	global_load_dword v18, v1, s[8:9]
	s_add_u32 s8, s8, s10
	s_addc_u32 s9, s9, 0
	global_load_dword v19, v1, s[8:9]
	s_add_u32 s8, s8, s10
	s_addc_u32 s9, s9, 0
	global_load_dword v20, v1, s[8:9]
	s_add_u32 s8, s8, s10
	s_addc_u32 s9, s9, 0
	global_load_dword v21, v1, s[8:9]
	s_add_u32 s8, s8, s10
	s_addc_u32 s9, s9, 0
	global_load_dword v22, v1, s[8:9]
	s_add_u32 s8, s8, s10
	s_addc_u32 s9, s9, 0
	global_load_dword v23, v1, s[8:9]
	s_add_u32 s8, s8, s10
	s_addc_u32 s9, s9, 0
	global_load_dword v24, v1, s[8:9]
	s_add_u32 s8, s8, s10
	s_addc_u32 s9, s9, 0
	global_load_dword v25, v1, s[8:9]
	s_add_u32 s8, s8, s10
	s_addc_u32 s9, s9, 0
	global_load_dword v26, v1, s[8:9]
	s_add_u32 s8, s8, s10
	s_addc_u32 s9, s9, 0
	global_load_dword v27, v1, s[8:9]
	s_add_u32 s8, s8, s10
	s_addc_u32 s9, s9, 0
	global_load_dword v28, v1, s[8:9]
	s_add_u32 s8, s8, s10
	s_addc_u32 s9, s9, 0
	global_load_dword v29, v1, s[8:9]
	s_add_u32 s8, s8, s10
	s_addc_u32 s9, s9, 0
	global_load_dword v30, v1, s[8:9]
	s_add_u32 s8, s8, s10
	s_addc_u32 s9, s9, 0
	global_load_dword v31, v1, s[8:9]
	s_add_u32 s8, s8, s10
	s_addc_u32 s9, s9, 0
	global_load_dword v32, v1, s[8:9]
	s_add_u32 s8, s8, s10
	s_addc_u32 s9, s9, 0
	global_load_dword v33, v1, s[8:9]
	s_add_u32 s8, s8, s10
	s_addc_u32 s9, s9, 0
	global_load_dword v34, v1, s[8:9]
	s_add_u32 s8, s8, s10
	s_addc_u32 s9, s9, 0
	global_load_dword v35, v1, s[8:9]
	s_add_u32 s8, s8, s10
	s_addc_u32 s9, s9, 0
	s_waitcnt vmcnt(40)
; __device__ __forceinline__ void convert_item(const float* __restrict__ src, int Ksz, int Nsz, u16* __restrict__ dst, int kb, int nb,
;                                              int mode, const int tid) {
;   const int n = nb * NTHR + tid;
;   if (n < Nsz) {
;     const float* sp = src + (size_t)(kb * 64) * Nsz + n;
;     float v[64];
; #pragma unroll
;     for (int j = 0; j < 64; ++j) v[j] = sp[(size_t)j * Nsz];
;     int nd = n;
;     if (mode == 1) {
;       int isg = n >= 1024, c = n & 1023;
;       nd = (c >> 7) * 256 + isg * 128 + (c & 127);
;     }
;     u32x4* d = reinterpret_cast<u32x4*>(dst + (size_t)nd * Ksz + kb * 64);
; #pragma unroll
;     for (int q = 0; q < 8; ++q) {
;       u32x4 o;
;       o.x = pack2(v[q * 8 + 0], v[q * 8 + 1]);
;       o.y = pack2(v[q * 8 + 2], v[q * 8 + 3]);
;       o.z = pack2(v[q * 8 + 4], v[q * 8 + 5]);
;       o.w = pack2(v[q * 8 + 6], v[q * 8 + 7]);
;       d[q] = o;
;     }
	v_cvt_pk_bf16_f32 v100, v36, v37
	v_cvt_pk_bf16_f32 v101, v38, v39
	v_cvt_pk_bf16_f32 v102, v40, v41
	v_cvt_pk_bf16_f32 v103, v42, v43
	v_cvt_pk_bf16_f32 v104, v44, v45
	v_cvt_pk_bf16_f32 v105, v46, v47
	v_cvt_pk_bf16_f32 v106, v48, v49
	v_cvt_pk_bf16_f32 v107, v50, v51
	v_cvt_pk_bf16_f32 v108, v52, v53
	v_cvt_pk_bf16_f32 v109, v54, v55
	v_cvt_pk_bf16_f32 v110, v56, v57
	v_cvt_pk_bf16_f32 v111, v58, v59
	v_cvt_pk_bf16_f32 v112, v60, v61
	v_cvt_pk_bf16_f32 v113, v62, v63
	v_cvt_pk_bf16_f32 v114, v64, v65
	v_cvt_pk_bf16_f32 v115, v66, v67
	ds_write_b128 v2, v[100:103] offset:64
	ds_write_b128 v2, v[104:107] offset:80
	ds_write_b128 v2, v[108:111] offset:96
	ds_write_b128 v2, v[112:115] offset:112
	global_load_dword v36, v1, s[8:9]
	s_add_u32 s8, s8, s10
	s_addc_u32 s9, s9, 0
	global_load_dword v37, v1, s[8:9]
	s_add_u32 s8, s8, s10
	s_addc_u32 s9, s9, 0
	global_load_dword v38, v1, s[8:9]
	s_add_u32 s8, s8, s10
	s_addc_u32 s9, s9, 0
	global_load_dword v39, v1, s[8:9]
	s_add_u32 s8, s8, s10
	s_addc_u32 s9, s9, 0
	global_load_dword v40, v1, s[8:9]
	s_add_u32 s8, s8, s10
	s_addc_u32 s9, s9, 0
	global_load_dword v41, v1, s[8:9]
	s_add_u32 s8, s8, s10
	s_addc_u32 s9, s9, 0
	global_load_dword v42, v1, s[8:9]
	s_add_u32 s8, s8, s10
	s_addc_u32 s9, s9, 0
	global_load_dword v43, v1, s[8:9]
	s_add_u32 s8, s8, s10
	s_addc_u32 s9, s9, 0
	global_load_dword v44, v1, s[8:9]
	s_add_u32 s8, s8, s10
	s_addc_u32 s9, s9, 0
	global_load_dword v45, v1, s[8:9]
	s_add_u32 s8, s8, s10
	s_addc_u32 s9, s9, 0
	global_load_dword v46, v1, s[8:9]
	s_add_u32 s8, s8, s10
	s_addc_u32 s9, s9, 0
	global_load_dword v47, v1, s[8:9]
	s_add_u32 s8, s8, s10
	s_addc_u32 s9, s9, 0
	global_load_dword v48, v1, s[8:9]
	s_add_u32 s8, s8, s10
	s_addc_u32 s9, s9, 0
	global_load_dword v49, v1, s[8:9]
	s_add_u32 s8, s8, s10
	s_addc_u32 s9, s9, 0
	global_load_dword v50, v1, s[8:9]
	s_add_u32 s8, s8, s10
	s_addc_u32 s9, s9, 0
	global_load_dword v51, v1, s[8:9]
	s_add_u32 s8, s8, s10
	s_addc_u32 s9, s9, 0
	global_load_dword v52, v1, s[8:9]
	s_add_u32 s8, s8, s10
	s_addc_u32 s9, s9, 0
	global_load_dword v53, v1, s[8:9]
	s_add_u32 s8, s8, s10
	s_addc_u32 s9, s9, 0
	global_load_dword v54, v1, s[8:9]
	s_add_u32 s8, s8, s10
	s_addc_u32 s9, s9, 0
	global_load_dword v55, v1, s[8:9]
	s_add_u32 s8, s8, s10
	s_addc_u32 s9, s9, 0
	global_load_dword v56, v1, s[8:9]
	s_add_u32 s8, s8, s10
	s_addc_u32 s9, s9, 0
	global_load_dword v57, v1, s[8:9]
	s_add_u32 s8, s8, s10
	s_addc_u32 s9, s9, 0
	global_load_dword v58, v1, s[8:9]
	s_add_u32 s8, s8, s10
	s_addc_u32 s9, s9, 0
	global_load_dword v59, v1, s[8:9]
	s_add_u32 s8, s8, s10
	s_addc_u32 s9, s9, 0
	global_load_dword v60, v1, s[8:9]
	s_add_u32 s8, s8, s10
	s_addc_u32 s9, s9, 0
	global_load_dword v61, v1, s[8:9]
	s_add_u32 s8, s8, s10
	s_addc_u32 s9, s9, 0
	global_load_dword v62, v1, s[8:9]
	s_add_u32 s8, s8, s10
	s_addc_u32 s9, s9, 0
	global_load_dword v63, v1, s[8:9]
	s_add_u32 s8, s8, s10
	s_addc_u32 s9, s9, 0
	global_load_dword v64, v1, s[8:9]
	s_add_u32 s8, s8, s10
	s_addc_u32 s9, s9, 0
	global_load_dword v65, v1, s[8:9]
	s_add_u32 s8, s8, s10
	s_addc_u32 s9, s9, 0
	global_load_dword v66, v1, s[8:9]
	s_add_u32 s8, s8, s10
	s_addc_u32 s9, s9, 0
	global_load_dword v67, v1, s[8:9]
	s_add_u32 s8, s8, s10
	s_addc_u32 s9, s9, 0
	v_mov_b32_e32 v86, v84
	v_mov_b32_e32 v87, v85
	ds_read_b128 v[116:119], v3 offset:0
	ds_read_b128 v[120:123], v3 offset:1152
	ds_read_b128 v[124:127], v3 offset:2304
	ds_read_b128 v[128:131], v3 offset:3456
	s_waitcnt lgkmcnt(0)
	global_store_dwordx4 v[86:87], v[116:119], off offset:128 sc1
	v_lshl_add_u64 v[86:87], v[86:87], 0, s[6:7]
	global_store_dwordx4 v[86:87], v[120:123], off offset:128 sc1
	v_lshl_add_u64 v[86:87], v[86:87], 0, s[6:7]
	global_store_dwordx4 v[86:87], v[124:127], off offset:128 sc1
	v_lshl_add_u64 v[86:87], v[86:87], 0, s[6:7]
	global_store_dwordx4 v[86:87], v[128:131], off offset:128 sc1
	v_lshl_add_u64 v[86:87], v[86:87], 0, s[6:7]
	ds_read_b128 v[116:119], v3 offset:4608
	ds_read_b128 v[120:123], v3 offset:5760
	ds_read_b128 v[124:127], v3 offset:6912
	ds_read_b128 v[128:131], v3 offset:8064
	s_waitcnt lgkmcnt(0)
	global_store_dwordx4 v[86:87], v[116:119], off offset:128 sc1
	v_lshl_add_u64 v[86:87], v[86:87], 0, s[6:7]
	global_store_dwordx4 v[86:87], v[120:123], off offset:128 sc1
	v_lshl_add_u64 v[86:87], v[86:87], 0, s[6:7]
	global_store_dwordx4 v[86:87], v[124:127], off offset:128 sc1
	v_lshl_add_u64 v[86:87], v[86:87], 0, s[6:7]
	global_store_dwordx4 v[86:87], v[128:131], off offset:128 sc1
	v_lshl_add_u64 v[86:87], v[86:87], 0, s[6:7]
	s_waitcnt vmcnt(40)
; __device__ __forceinline__ void convert_item(const float* __restrict__ src, int Ksz, int Nsz, u16* __restrict__ dst, int kb, int nb,
;                                              int mode, const int tid) {
;   const int n = nb * NTHR + tid;
;   if (n < Nsz) {
;     const float* sp = src + (size_t)(kb * 64) * Nsz + n;
;     float v[64];
; #pragma unroll
;     for (int j = 0; j < 64; ++j) v[j] = sp[(size_t)j * Nsz];
;     int nd = n;
;     if (mode == 1) {
;       int isg = n >= 1024, c = n & 1023;
;       nd = (c >> 7) * 256 + isg * 128 + (c & 127);
;     }
;     u32x4* d = reinterpret_cast<u32x4*>(dst + (size_t)nd * Ksz + kb * 64);
; #pragma unroll
;     for (int q = 0; q < 8; ++q) {
;       u32x4 o;
;       o.x = pack2(v[q * 8 + 0], v[q * 8 + 1]);
;       o.y = pack2(v[q * 8 + 2], v[q * 8 + 3]);
;       o.z = pack2(v[q * 8 + 4], v[q * 8 + 5]);
;       o.w = pack2(v[q * 8 + 6], v[q * 8 + 7]);
;       d[q] = o;
;     }
	v_cvt_pk_bf16_f32 v68, v4, v5
	v_cvt_pk_bf16_f32 v69, v6, v7
	v_cvt_pk_bf16_f32 v70, v8, v9
	v_cvt_pk_bf16_f32 v71, v10, v11
	v_cvt_pk_bf16_f32 v72, v12, v13
	v_cvt_pk_bf16_f32 v73, v14, v15
	v_cvt_pk_bf16_f32 v74, v16, v17
	v_cvt_pk_bf16_f32 v75, v18, v19
	v_cvt_pk_bf16_f32 v76, v20, v21
	v_cvt_pk_bf16_f32 v77, v22, v23
	v_cvt_pk_bf16_f32 v78, v24, v25
	v_cvt_pk_bf16_f32 v79, v26, v27
	v_cvt_pk_bf16_f32 v80, v28, v29
	v_cvt_pk_bf16_f32 v81, v30, v31
	v_cvt_pk_bf16_f32 v82, v32, v33
	v_cvt_pk_bf16_f32 v83, v34, v35
	ds_write_b128 v2, v[68:71] offset:0
	ds_write_b128 v2, v[72:75] offset:16
	ds_write_b128 v2, v[76:79] offset:32
	ds_write_b128 v2, v[80:83] offset:48
	global_load_dword v4, v1, s[8:9]
	s_add_u32 s8, s8, s10
	s_addc_u32 s9, s9, 0
	global_load_dword v5, v1, s[8:9]
	s_add_u32 s8, s8, s10
	s_addc_u32 s9, s9, 0
	global_load_dword v6, v1, s[8:9]
	s_add_u32 s8, s8, s10
	s_addc_u32 s9, s9, 0
	global_load_dword v7, v1, s[8:9]
	s_add_u32 s8, s8, s10
	s_addc_u32 s9, s9, 0
	global_load_dword v8, v1, s[8:9]
	s_add_u32 s8, s8, s10
	s_addc_u32 s9, s9, 0
	global_load_dword v9, v1, s[8:9]
	s_add_u32 s8, s8, s10
	s_addc_u32 s9, s9, 0
	global_load_dword v10, v1, s[8:9]
	s_add_u32 s8, s8, s10
	s_addc_u32 s9, s9, 0
	global_load_dword v11, v1, s[8:9]
	s_add_u32 s8, s8, s10
	s_addc_u32 s9, s9, 0
	global_load_dword v12, v1, s[8:9]
	s_add_u32 s8, s8, s10
	s_addc_u32 s9, s9, 0
	global_load_dword v13, v1, s[8:9]
	s_add_u32 s8, s8, s10
	s_addc_u32 s9, s9, 0
	global_load_dword v14, v1, s[8:9]
	s_add_u32 s8, s8, s10
	s_addc_u32 s9, s9, 0
	global_load_dword v15, v1, s[8:9]
	s_add_u32 s8, s8, s10
	s_addc_u32 s9, s9, 0
	global_load_dword v16, v1, s[8:9]
	s_add_u32 s8, s8, s10
	s_addc_u32 s9, s9, 0
	global_load_dword v17, v1, s[8:9]
	s_add_u32 s8, s8, s10
	s_addc_u32 s9, s9, 0
	global_load_dword v18, v1, s[8:9]
	s_add_u32 s8, s8, s10
	s_addc_u32 s9, s9, 0
	global_load_dword v19, v1, s[8:9]
	s_add_u32 s8, s8, s10
	s_addc_u32 s9, s9, 0
	global_load_dword v20, v1, s[8:9]
	s_add_u32 s8, s8, s10
	s_addc_u32 s9, s9, 0
	global_load_dword v21, v1, s[8:9]
	s_add_u32 s8, s8, s10
	s_addc_u32 s9, s9, 0
	global_load_dword v22, v1, s[8:9]
	s_add_u32 s8, s8, s10
	s_addc_u32 s9, s9, 0
	global_load_dword v23, v1, s[8:9]
	s_add_u32 s8, s8, s10
	s_addc_u32 s9, s9, 0
	global_load_dword v24, v1, s[8:9]
	s_add_u32 s8, s8, s10
	s_addc_u32 s9, s9, 0
	global_load_dword v25, v1, s[8:9]
	s_add_u32 s8, s8, s10
	s_addc_u32 s9, s9, 0
	global_load_dword v26, v1, s[8:9]
	s_add_u32 s8, s8, s10
	s_addc_u32 s9, s9, 0
	global_load_dword v27, v1, s[8:9]
	s_add_u32 s8, s8, s10
	s_addc_u32 s9, s9, 0
	global_load_dword v28, v1, s[8:9]
	s_add_u32 s8, s8, s10
	s_addc_u32 s9, s9, 0
	global_load_dword v29, v1, s[8:9]
	s_add_u32 s8, s8, s10
	s_addc_u32 s9, s9, 0
	global_load_dword v30, v1, s[8:9]
	s_add_u32 s8, s8, s10
	s_addc_u32 s9, s9, 0
	global_load_dword v31, v1, s[8:9]
	s_add_u32 s8, s8, s10
	s_addc_u32 s9, s9, 0
	global_load_dword v32, v1, s[8:9]
	s_add_u32 s8, s8, s10
	s_addc_u32 s9, s9, 0
	global_load_dword v33, v1, s[8:9]
	s_add_u32 s8, s8, s10
	s_addc_u32 s9, s9, 0
	global_load_dword v34, v1, s[8:9]
	s_add_u32 s8, s8, s10
	s_addc_u32 s9, s9, 0
	global_load_dword v35, v1, s[8:9]
	s_add_u32 s8, s8, s10
	s_addc_u32 s9, s9, 0
	s_waitcnt vmcnt(40)
	v_cvt_pk_bf16_f32 v100, v36, v37
	v_cvt_pk_bf16_f32 v101, v38, v39
	v_cvt_pk_bf16_f32 v102, v40, v41
	v_cvt_pk_bf16_f32 v103, v42, v43
	v_cvt_pk_bf16_f32 v104, v44, v45
	v_cvt_pk_bf16_f32 v105, v46, v47
	v_cvt_pk_bf16_f32 v106, v48, v49
	v_cvt_pk_bf16_f32 v107, v50, v51
	v_cvt_pk_bf16_f32 v108, v52, v53
	v_cvt_pk_bf16_f32 v109, v54, v55
	v_cvt_pk_bf16_f32 v110, v56, v57
	v_cvt_pk_bf16_f32 v111, v58, v59
	v_cvt_pk_bf16_f32 v112, v60, v61
	v_cvt_pk_bf16_f32 v113, v62, v63
	v_cvt_pk_bf16_f32 v114, v64, v65
	v_cvt_pk_bf16_f32 v115, v66, v67
	ds_write_b128 v2, v[100:103] offset:64
	ds_write_b128 v2, v[104:107] offset:80
	ds_write_b128 v2, v[108:111] offset:96
	ds_write_b128 v2, v[112:115] offset:112
	global_load_dword v36, v1, s[8:9]
	s_add_u32 s8, s8, s10
	s_addc_u32 s9, s9, 0
	global_load_dword v37, v1, s[8:9]
	s_add_u32 s8, s8, s10
	s_addc_u32 s9, s9, 0
	global_load_dword v38, v1, s[8:9]
	s_add_u32 s8, s8, s10
	s_addc_u32 s9, s9, 0
	global_load_dword v39, v1, s[8:9]
	s_add_u32 s8, s8, s10
	s_addc_u32 s9, s9, 0
	global_load_dword v40, v1, s[8:9]
	s_add_u32 s8, s8, s10
	s_addc_u32 s9, s9, 0
	global_load_dword v41, v1, s[8:9]
	s_add_u32 s8, s8, s10
	s_addc_u32 s9, s9, 0
	global_load_dword v42, v1, s[8:9]
	s_add_u32 s8, s8, s10
	s_addc_u32 s9, s9, 0
	global_load_dword v43, v1, s[8:9]
	s_add_u32 s8, s8, s10
	s_addc_u32 s9, s9, 0
	global_load_dword v44, v1, s[8:9]
	s_add_u32 s8, s8, s10
	s_addc_u32 s9, s9, 0
	global_load_dword v45, v1, s[8:9]
	s_add_u32 s8, s8, s10
	s_addc_u32 s9, s9, 0
	global_load_dword v46, v1, s[8:9]
	s_add_u32 s8, s8, s10
	s_addc_u32 s9, s9, 0
	global_load_dword v47, v1, s[8:9]
	s_add_u32 s8, s8, s10
	s_addc_u32 s9, s9, 0
	global_load_dword v48, v1, s[8:9]
	s_add_u32 s8, s8, s10
	s_addc_u32 s9, s9, 0
	global_load_dword v49, v1, s[8:9]
	s_add_u32 s8, s8, s10
	s_addc_u32 s9, s9, 0
	global_load_dword v50, v1, s[8:9]
	s_add_u32 s8, s8, s10
	s_addc_u32 s9, s9, 0
	global_load_dword v51, v1, s[8:9]
	s_add_u32 s8, s8, s10
	s_addc_u32 s9, s9, 0
	global_load_dword v52, v1, s[8:9]
	s_add_u32 s8, s8, s10
	s_addc_u32 s9, s9, 0
	global_load_dword v53, v1, s[8:9]
	s_add_u32 s8, s8, s10
	s_addc_u32 s9, s9, 0
	global_load_dword v54, v1, s[8:9]
	s_add_u32 s8, s8, s10
	s_addc_u32 s9, s9, 0
	global_load_dword v55, v1, s[8:9]
	s_add_u32 s8, s8, s10
	s_addc_u32 s9, s9, 0
	global_load_dword v56, v1, s[8:9]
	s_add_u32 s8, s8, s10
	s_addc_u32 s9, s9, 0
	global_load_dword v57, v1, s[8:9]
	s_add_u32 s8, s8, s10
	s_addc_u32 s9, s9, 0
	global_load_dword v58, v1, s[8:9]
	s_add_u32 s8, s8, s10
	s_addc_u32 s9, s9, 0
	global_load_dword v59, v1, s[8:9]
	s_add_u32 s8, s8, s10
	s_addc_u32 s9, s9, 0
	global_load_dword v60, v1, s[8:9]
	s_add_u32 s8, s8, s10
	s_addc_u32 s9, s9, 0
	global_load_dword v61, v1, s[8:9]
	s_add_u32 s8, s8, s10
	s_addc_u32 s9, s9, 0
	global_load_dword v62, v1, s[8:9]
	s_add_u32 s8, s8, s10
	s_addc_u32 s9, s9, 0
	global_load_dword v63, v1, s[8:9]
	s_add_u32 s8, s8, s10
	s_addc_u32 s9, s9, 0
	global_load_dword v64, v1, s[8:9]
	s_add_u32 s8, s8, s10
	s_addc_u32 s9, s9, 0
	global_load_dword v65, v1, s[8:9]
	s_add_u32 s8, s8, s10
	s_addc_u32 s9, s9, 0
	global_load_dword v66, v1, s[8:9]
	s_add_u32 s8, s8, s10
	s_addc_u32 s9, s9, 0
	global_load_dword v67, v1, s[8:9]
	s_add_u32 s8, s8, s10
	s_addc_u32 s9, s9, 0
	v_mov_b32_e32 v86, v84
	v_mov_b32_e32 v87, v85
	ds_read_b128 v[116:119], v3 offset:0
	ds_read_b128 v[120:123], v3 offset:1152
	ds_read_b128 v[124:127], v3 offset:2304
	ds_read_b128 v[128:131], v3 offset:3456
	s_waitcnt lgkmcnt(0)
; __device__ __forceinline__ void convert_item(const float* __restrict__ src, int Ksz, int Nsz, u16* __restrict__ dst, int kb, int nb,
;                                              int mode, const int tid) {
;   const int n = nb * NTHR + tid;
;   if (n < Nsz) {
;     const float* sp = src + (size_t)(kb * 64) * Nsz + n;
;     float v[64];
; #pragma unroll
;     for (int j = 0; j < 64; ++j) v[j] = sp[(size_t)j * Nsz];
;     int nd = n;
;     if (mode == 1) {
;       int isg = n >= 1024, c = n & 1023;
;       nd = (c >> 7) * 256 + isg * 128 + (c & 127);
;     }
;     u32x4* d = reinterpret_cast<u32x4*>(dst + (size_t)nd * Ksz + kb * 64);
; #pragma unroll
;     for (int q = 0; q < 8; ++q) {
;       u32x4 o;
;       o.x = pack2(v[q * 8 + 0], v[q * 8 + 1]);
;       o.y = pack2(v[q * 8 + 2], v[q * 8 + 3]);
;       o.z = pack2(v[q * 8 + 4], v[q * 8 + 5]);
;       o.w = pack2(v[q * 8 + 6], v[q * 8 + 7]);
;       d[q] = o;
;     }
	global_store_dwordx4 v[86:87], v[116:119], off offset:256 sc1
	v_lshl_add_u64 v[86:87], v[86:87], 0, s[6:7]
	global_store_dwordx4 v[86:87], v[120:123], off offset:256 sc1
	v_lshl_add_u64 v[86:87], v[86:87], 0, s[6:7]
	global_store_dwordx4 v[86:87], v[124:127], off offset:256 sc1
	v_lshl_add_u64 v[86:87], v[86:87], 0, s[6:7]
	global_store_dwordx4 v[86:87], v[128:131], off offset:256 sc1
	v_lshl_add_u64 v[86:87], v[86:87], 0, s[6:7]
	ds_read_b128 v[116:119], v3 offset:4608
	ds_read_b128 v[120:123], v3 offset:5760
	ds_read_b128 v[124:127], v3 offset:6912
	ds_read_b128 v[128:131], v3 offset:8064
	s_waitcnt lgkmcnt(0)
	global_store_dwordx4 v[86:87], v[116:119], off offset:256 sc1
	v_lshl_add_u64 v[86:87], v[86:87], 0, s[6:7]
	global_store_dwordx4 v[86:87], v[120:123], off offset:256 sc1
	v_lshl_add_u64 v[86:87], v[86:87], 0, s[6:7]
	global_store_dwordx4 v[86:87], v[124:127], off offset:256 sc1
	v_lshl_add_u64 v[86:87], v[86:87], 0, s[6:7]
	global_store_dwordx4 v[86:87], v[128:131], off offset:256 sc1
	v_lshl_add_u64 v[86:87], v[86:87], 0, s[6:7]
	s_waitcnt vmcnt(40)
	v_cvt_pk_bf16_f32 v68, v4, v5
	v_cvt_pk_bf16_f32 v69, v6, v7
	v_cvt_pk_bf16_f32 v70, v8, v9
	v_cvt_pk_bf16_f32 v71, v10, v11
	v_cvt_pk_bf16_f32 v72, v12, v13
	v_cvt_pk_bf16_f32 v73, v14, v15
	v_cvt_pk_bf16_f32 v74, v16, v17
	v_cvt_pk_bf16_f32 v75, v18, v19
	v_cvt_pk_bf16_f32 v76, v20, v21
	v_cvt_pk_bf16_f32 v77, v22, v23
	v_cvt_pk_bf16_f32 v78, v24, v25
	v_cvt_pk_bf16_f32 v79, v26, v27
	v_cvt_pk_bf16_f32 v80, v28, v29
	v_cvt_pk_bf16_f32 v81, v30, v31
	v_cvt_pk_bf16_f32 v82, v32, v33
	v_cvt_pk_bf16_f32 v83, v34, v35
	ds_write_b128 v2, v[68:71] offset:0
	ds_write_b128 v2, v[72:75] offset:16
	ds_write_b128 v2, v[76:79] offset:32
	ds_write_b128 v2, v[80:83] offset:48
	s_waitcnt vmcnt(8)
	v_cvt_pk_bf16_f32 v100, v36, v37
	v_cvt_pk_bf16_f32 v101, v38, v39
	v_cvt_pk_bf16_f32 v102, v40, v41
	v_cvt_pk_bf16_f32 v103, v42, v43
	v_cvt_pk_bf16_f32 v104, v44, v45
	v_cvt_pk_bf16_f32 v105, v46, v47
	v_cvt_pk_bf16_f32 v106, v48, v49
	v_cvt_pk_bf16_f32 v107, v50, v51
	v_cvt_pk_bf16_f32 v108, v52, v53
	v_cvt_pk_bf16_f32 v109, v54, v55
	v_cvt_pk_bf16_f32 v110, v56, v57
	v_cvt_pk_bf16_f32 v111, v58, v59
	v_cvt_pk_bf16_f32 v112, v60, v61
	v_cvt_pk_bf16_f32 v113, v62, v63
	v_cvt_pk_bf16_f32 v114, v64, v65
	v_cvt_pk_bf16_f32 v115, v66, v67
	ds_write_b128 v2, v[100:103] offset:64
	ds_write_b128 v2, v[104:107] offset:80
	ds_write_b128 v2, v[108:111] offset:96
	ds_write_b128 v2, v[112:115] offset:112
	v_mov_b32_e32 v86, v84
	v_mov_b32_e32 v87, v85
	ds_read_b128 v[116:119], v3 offset:0
	ds_read_b128 v[120:123], v3 offset:1152
	ds_read_b128 v[124:127], v3 offset:2304
	ds_read_b128 v[128:131], v3 offset:3456
	s_waitcnt lgkmcnt(0)
	global_store_dwordx4 v[86:87], v[116:119], off offset:384 sc1
	v_lshl_add_u64 v[86:87], v[86:87], 0, s[6:7]
	global_store_dwordx4 v[86:87], v[120:123], off offset:384 sc1
	v_lshl_add_u64 v[86:87], v[86:87], 0, s[6:7]
	global_store_dwordx4 v[86:87], v[124:127], off offset:384 sc1
	v_lshl_add_u64 v[86:87], v[86:87], 0, s[6:7]
	global_store_dwordx4 v[86:87], v[128:131], off offset:384 sc1
	v_lshl_add_u64 v[86:87], v[86:87], 0, s[6:7]
	ds_read_b128 v[116:119], v3 offset:4608
	ds_read_b128 v[120:123], v3 offset:5760
	ds_read_b128 v[124:127], v3 offset:6912
	ds_read_b128 v[128:131], v3 offset:8064
	s_waitcnt lgkmcnt(0)
	global_store_dwordx4 v[86:87], v[116:119], off offset:384 sc1
	v_lshl_add_u64 v[86:87], v[86:87], 0, s[6:7]
	global_store_dwordx4 v[86:87], v[120:123], off offset:384 sc1
	v_lshl_add_u64 v[86:87], v[86:87], 0, s[6:7]
	global_store_dwordx4 v[86:87], v[124:127], off offset:384 sc1
	v_lshl_add_u64 v[86:87], v[86:87], 0, s[6:7]
	global_store_dwordx4 v[86:87], v[128:131], off offset:384 sc1
	v_lshl_add_u64 v[86:87], v[86:87], 0, s[6:7]
